# all three residual epilogues: f32 Y stores write full 32B sectors via permlane16 lane exchange
# speedup vs baseline: 1.0022x; 1.0022x over previous
; __device__ __forceinline__ float xsum16(float v) { const auto r = __builtin_amdgcn_permlane16_swap(__float_as_uint(v), __float_as_uint(v), false, false); return __uint_as_float(r[0]) + __uint_as_float(r[1]); }
; __device__ __forceinline__ float xsum32(float v) { const auto r = __builtin_amdgcn_permlane32_swap(__float_as_uint(v), __float_as_uint(v), false, false); return __uint_as_float(r[0]) + __uint_as_float(r[1]); }
; __device__ __forceinline__ void row_stats4(const float* st, int rowb, int fq, float (&mu)[4], float (&rs)[4]) {
;     ...
;     for (int m = 0; m < 4; ++m) { const f32x4* p = (const f32x4*)(st + (size_t)(rowb + m * 16) * 32 + fq * 8); a[m] = p[0]; b[m] = p[1]; }
; #pragma unroll
;     for (int m = 0; m < 4; ++m) { float s1 = (a[m][0] + a[m][2]) + (b[m][0] + b[m][2]), s2 = (a[m][1] + a[m][3]) + (b[m][1] + b[m][3]);
;         s1 = xsum32(xsum16(s1)); s2 = xsum32(xsum16(s2));
;         const float mm = s1 * (1.0f / 1024.0f); mu[m] = mm; rs[m] = rsqrtf(fmaxf(s2 * (1.0f / 1024.0f) - mm * mm, 0.f) + LN_EPS_); }
;     __device__ __forceinline__ void operator()(const f32x4 (&acc)[2][2][4][2], const pg8::Unit& u, int wr, int wc, int fr, int fq) const {
;     ...
;         for (int ai = 0; ai < 2; ++ai) { float mu4[4], rs4[4]; row_stats4(stp, row0 + ai * 128, fq, mu4, rs4);
; #pragma unroll
;             for (int m = 0; m < 4; ++m) { const int row = row0 + ai * 128 + m * 16; const float mu = mu4[m], rs = rs4[m];
;                 f32x4 yv[2][2], gq[2][2], bq_[2][2];
; #pragma unroll
;                 for (int bj = 0; bj < 2; ++bj)
; #pragma unroll
;                     for (int n = 0; n < 2; ++n) { yv[bj][n] = *(const f32x4*)(Yin + (size_t)row * D_ + col0 + bj * 128 + 4 * n); gq[bj][n] = *(const f32x4*)(g + col0 + bj * 128 + 4 * n); bq_[bj][n] = *(const f32x4*)(b + col0 + bj * 128 + 4 * n); }
;                 asm volatile("" ::: "memory");
;                 float s1 = 0.f, s2 = 0.f;
; #pragma unroll
;                 for (int bj = 0; bj < 2; ++bj) { float* yp = Y + (size_t)row * D_ + col0 + bj * 128; f32x4 v[2];
; #pragma unroll
;                     for (int n = 0; n < 2; ++n) { v[n] = (((yv[bj][n] - mu) * rs) * gq[bj][n] + bq_[bj][n]) * ALPHA_ + acc[ai][bj][m][n] * sc;
;                         *(f32x4*)(yp + 4 * n) = v[n]; s1 += (v[n][0] + v[n][1]) + (v[n][2] + v[n][3]); s2 += (v[n][0] * v[n][0] + v[n][1] * v[n][1]) + (v[n][2] * v[n][2] + v[n][3] * v[n][3]); }
.LBB0_1535:
	s_lshl_b32 s3, s3, 8
	s_add_i32 s3, s3, s0
	v_or_b32_e32 v158, s3, v184
	v_ashrrev_i32_e32 v159, 31, v158
	v_lshlrev_b64 v[130:131], 7, v[158:159]
	v_lshl_add_u64 v[136:137], v[146:147], 0, v[130:131]
	v_or_b32_e32 v180, 16, v158
	global_load_dwordx4 v[132:135], v[136:137], off
	global_load_dwordx4 v[166:169], v[136:137], off offset:16
	v_ashrrev_i32_e32 v181, 31, v180
	v_lshlrev_b64 v[172:173], 7, v[180:181]
	v_lshl_add_u64 v[136:137], v[146:147], 0, v[172:173]
	global_load_dwordx4 v[174:177], v[136:137], off
	global_load_dwordx4 v[186:189], v[136:137], off offset:16
	v_or_b32_e32 v170, 32, v158
	v_ashrrev_i32_e32 v171, 31, v170
	v_lshlrev_b64 v[164:165], 7, v[170:171]
	v_lshl_add_u64 v[136:137], v[146:147], 0, v[164:165]
	global_load_dwordx4 v[190:193], v[136:137], off
	global_load_dwordx4 v[198:201], v[136:137], off offset:16
	v_or_b32_e32 v162, 48, v158
	v_ashrrev_i32_e32 v163, 31, v162
	v_lshlrev_b64 v[160:161], 7, v[162:163]
	v_lshl_add_u64 v[182:183], v[146:147], 0, v[160:161]
	global_load_dwordx4 v[202:205], v[182:183], off
	global_load_dwordx4 v[206:209], v[182:183], off offset:16
	s_load_dwordx16 s[64:79], s[34:35], 0x38
	s_lshl_b32 s1, s2, 8
	s_lshl_b32 s14, s2, 3
	s_or_b32 s2, s1, s57
	v_or_b32_e32 v152, s2, v185
	v_ashrrev_i32_e32 v153, 31, v152
	v_lshlrev_b64 v[136:137], 12, v[158:159]
	v_lshlrev_b64 v[178:179], 2, v[152:153]
	s_waitcnt lgkmcnt(0)
	v_lshl_add_u64 v[136:137], s[78:79], 0, v[136:137]
	v_lshl_add_u64 v[156:157], s[8:9], 0, v[178:179]
	v_lshl_add_u64 v[154:155], s[10:11], 0, v[178:179]
	v_lshl_add_u64 v[136:137], v[136:137], 0, v[178:179]
	s_or_b32 s52, s14, s61
	s_mov_b32 s14, 0x3a800000
	global_load_dwordx4 v[210:213], v[136:137], off offset:16
	global_load_dwordx4 v[214:217], v[136:137], off
	global_load_dwordx4 v[218:221], v[156:157], off offset:16
	global_load_dwordx4 v[222:225], v[156:157], off
	global_load_dwordx4 v[234:237], v[154:155], off offset:16
	global_load_dwordx4 v[238:241], v[154:155], off
	s_mov_b32 s1, 0x800000
	s_mov_b32 s18, 0x3fd744fd
	v_bitop3_b32 v196, s2, 56, v185 bitop3:0xc8
	s_ashr_i32 s2, s2, 6
	s_ashr_i32 s53, s52, 31
	v_readlane_b32 s16, v253, 59
	v_readlane_b32 s17, v253, 60
	s_waitcnt vmcnt(0)
	v_mov_b32_e32 v178, v132
	v_mov_b32_e32 v179, v166
	v_mov_b32_e32 v182, v134
	v_mov_b32_e32 v183, v168
	v_mov_b32_e32 v166, v133
	v_mov_b32_e32 v168, v135
	v_pk_add_f32 v[132:133], v[178:179], v[182:183]
	v_pk_add_f32 v[134:135], v[166:167], v[168:169]
	v_pk_add_f32 v[132:133], v[132:133], v[132:133] op_sel:[0,1] op_sel_hi:[1,0]
	v_pk_add_f32 v[134:135], v[134:135], v[134:135] op_sel:[0,1] op_sel_hi:[1,0]
	v_mov_b32_e32 v166, v174
	v_mov_b32_e32 v167, v186
	v_mov_b32_e32 v168, v176
	v_mov_b32_e32 v169, v188
	v_mov_b32_e32 v0, v132
	v_mov_b32_e32 v133, v134
	v_pk_add_f32 v[166:167], v[166:167], v[168:169]
	v_permlane16_swap_b32_e32 v132, v0
	v_permlane16_swap_b32_e32 v134, v133
	v_mov_b32_e32 v188, v177
	v_pk_add_f32 v[166:167], v[166:167], v[166:167] op_sel:[0,1] op_sel_hi:[1,0]
	v_add_f32_e32 v177, v132, v0
	v_add_f32_e32 v176, v134, v133
	v_mov_b32_e32 v135, v166
	v_mov_b32_e32 v179, v177
	v_mov_b32_e32 v178, v176
	v_permlane16_swap_b32_e32 v166, v135
	v_permlane32_swap_b32_e32 v177, v179
	v_permlane32_swap_b32_e32 v176, v178
	v_mov_b32_e32 v186, v175
	v_add_f32_e32 v133, v166, v135
	v_pk_add_f32 v[166:167], v[176:177], v[178:179]
	v_pk_add_f32 v[168:169], v[186:187], v[188:189]
	v_pk_mul_f32 v[178:179], v[166:167], s[14:15] op_sel_hi:[1,0]
	v_pk_add_f32 v[168:169], v[168:169], v[168:169] op_sel:[0,1] op_sel_hi:[1,0]
	v_fma_f32 v0, -v179, v179, v178
	v_mov_b32_e32 v159, v168
	v_max_f32_e32 v0, 0, v0
	s_nop 0
	v_permlane16_swap_b32_e32 v168, v159
	v_add_f32_e32 v0, 0x3727c5ac, v0
	v_add_f32_e32 v132, v168, v159
	v_mul_f32_e32 v159, 0x4b800000, v0
	v_cmp_gt_f32_e32 vcc, s1, v0
	v_mov_b32_e32 v174, v190
	v_mov_b32_e32 v175, v198
	v_cndmask_b32_e32 v0, v0, v159, vcc
	v_rsq_f32_e32 v0, v0
	v_mov_b32_e32 v166, v192
	v_mov_b32_e32 v167, v200
	v_pk_add_f32 v[166:167], v[174:175], v[166:167]
	v_mul_f32_e32 v159, 0x45800000, v0
	v_pk_add_f32 v[166:167], v[166:167], v[166:167] op_sel:[0,1] op_sel_hi:[1,0]
	v_mov_b32_e32 v198, v191
	v_mov_b32_e32 v200, v193
	v_cndmask_b32_e32 v0, v0, v159, vcc
	v_pk_add_f32 v[168:169], v[198:199], v[200:201]
	v_mov_b32_e32 v159, v166
	v_pk_add_f32 v[168:169], v[168:169], v[168:169] op_sel:[0,1] op_sel_hi:[1,0]
	s_nop 0
	v_permlane16_swap_b32_e32 v166, v159
	v_add_f32_e32 v175, v166, v159
	v_mov_b32_e32 v159, v168
	s_nop 1
	v_permlane16_swap_b32_e32 v168, v159
	global_load_dwordx4 v[186:189], v[136:137], off offset:528
	global_load_dwordx4 v[190:193], v[136:137], off offset:512
	v_add_f32_e32 v174, v168, v159
	v_mov_b32_e32 v166, v202
	v_mov_b32_e32 v167, v206
	v_mov_b32_e32 v168, v204
	v_mov_b32_e32 v169, v208
	v_mov_b32_e32 v206, v203
	v_mov_b32_e32 v208, v205
	v_pk_add_f32 v[166:167], v[166:167], v[168:169]
	v_pk_add_f32 v[168:169], v[206:207], v[208:209]
	global_load_dwordx4 v[198:201], v[156:157], off offset:528
	global_load_dwordx4 v[202:205], v[156:157], off offset:512
	global_load_dwordx4 v[206:209], v[154:155], off offset:528
	global_load_dwordx4 v[242:245], v[154:155], off offset:512
	v_sub_f32_e32 v183, v215, v179
	v_sub_f32_e32 v182, v214, v179
	v_sub_f32_e32 v215, v217, v179
	v_sub_f32_e32 v214, v216, v179
	v_pk_mul_f32 v[214:215], v[0:1], v[214:215] op_sel_hi:[0,1]
	v_pk_mul_f32 v[182:183], v[0:1], v[182:183] op_sel_hi:[0,1]
	v_pk_fma_f32 v[182:183], v[222:223], v[182:183], v[238:239]
	v_pk_fma_f32 v[214:215], v[224:225], v[214:215], v[240:241]
	v_pk_fma_f32 v[126:127], v[182:183], s[18:19], v[126:127] op_sel_hi:[1,0,1]
; __device__ __forceinline__ float xsum16(float v) { const auto r = __builtin_amdgcn_permlane16_swap(__float_as_uint(v), __float_as_uint(v), false, false); return __uint_as_float(r[0]) + __uint_as_float(r[1]); }
; __device__ __forceinline__ float xsum32(float v) { const auto r = __builtin_amdgcn_permlane32_swap(__float_as_uint(v), __float_as_uint(v), false, false); return __uint_as_float(r[0]) + __uint_as_float(r[1]); }
; __device__ __forceinline__ size_t blk_off(int r, int c, int K) { return (size_t)(r >> 8) * 256 * K + (size_t)(c >> 6) * (256 * 64) + (size_t)((r & 255) * 64 + (c & 63)); }
; __device__ __forceinline__ u32x4 pack8(const f32x4 a, const f32x4 b) { u32x4 w; w.x = cvt_pk_bf16(a[0], a[1]); w.y = cvt_pk_bf16(a[2], a[3]); w.z = cvt_pk_bf16(b[0], b[1]); w.w = cvt_pk_bf16(b[2], b[3]); return w; }
;     __device__ __forceinline__ void operator()(const f32x4 (&acc)[2][2][4][2], const pg8::Unit& u, int wr, int wc, int fr, int fq) const {
;     ...
;             for (int m = 0; m < 4; ++m) { const int row = row0 + ai * 128 + m * 16; const float mu = mu4[m], rs = rs4[m];
;                 f32x4 yv[2][2], gq[2][2], bq_[2][2];
; #pragma unroll
;                 for (int bj = 0; bj < 2; ++bj)
; #pragma unroll
;                     for (int n = 0; n < 2; ++n) { yv[bj][n] = *(const f32x4*)(Yin + (size_t)row * D_ + col0 + bj * 128 + 4 * n); gq[bj][n] = *(const f32x4*)(g + col0 + bj * 128 + 4 * n); bq_[bj][n] = *(const f32x4*)(b + col0 + bj * 128 + 4 * n); }
;                 asm volatile("" ::: "memory");
;                 float s1 = 0.f, s2 = 0.f;
; #pragma unroll
;                 for (int bj = 0; bj < 2; ++bj) { float* yp = Y + (size_t)row * D_ + col0 + bj * 128; f32x4 v[2];
; #pragma unroll
;                     for (int n = 0; n < 2; ++n) { v[n] = (((yv[bj][n] - mu) * rs) * gq[bj][n] + bq_[bj][n]) * ALPHA_ + acc[ai][bj][m][n] * sc;
;                         *(f32x4*)(yp + 4 * n) = v[n]; s1 += (v[n][0] + v[n][1]) + (v[n][2] + v[n][3]); s2 += (v[n][0] * v[n][0] + v[n][1] * v[n][1]) + (v[n][2] * v[n][2] + v[n][3] * v[n][3]); }
;                     *(u32x4*)(Yb + blk_off(row, col0 + bj * 128, D_)) = pack8(v[0], v[1]); }
;                 s1 = xsum32(xsum16(s1)); s2 = xsum32(xsum16(s2));
;                 if (fq == 0) *(f32x2*)(stn + (size_t)row * 32 + (u.pn * 4 + wc) * 2) = (f32x2){s1, s2}; asm volatile("" ::: "memory"); } }
	v_pk_fma_f32 v[128:129], v[214:215], s[18:19], v[128:129] op_sel_hi:[1,0,1]
	v_add_f32_e32 v178, v126, v127
	v_add_f32_e32 v182, v128, v129
	v_add_f32_e32 v178, v178, v182
	v_mul_f32_e32 v182, v127, v127
	v_mul_f32_e32 v183, v129, v129
	v_fmac_f32_e32 v182, v126, v126
	v_fmac_f32_e32 v183, v128, v128
	v_add_f32_e32 v197, v182, v183
	v_sub_f32_e32 v183, v211, v179
	v_sub_f32_e32 v182, v210, v179
	v_sub_f32_e32 v211, v213, v179
	v_sub_f32_e32 v210, v212, v179
	v_pk_mul_f32 v[210:211], v[0:1], v[210:211] op_sel_hi:[0,1]
	v_pk_mul_f32 v[182:183], v[0:1], v[182:183] op_sel_hi:[0,1]
	v_pk_fma_f32 v[182:183], v[218:219], v[182:183], v[234:235]
	v_pk_fma_f32 v[210:211], v[220:221], v[210:211], v[236:237]
	v_pk_add_f32 v[166:167], v[166:167], v[166:167] op_sel:[0,1] op_sel_hi:[1,0]
	v_pk_fma_f32 v[124:125], v[210:211], s[18:19], v[124:125] op_sel_hi:[1,0,1]
	v_pk_fma_f32 v[122:123], v[182:183], s[18:19], v[122:123] op_sel_hi:[1,0,1]
	v_mov_b32_e32 v159, v166
	v_add_f32_e32 v182, v122, v123
	v_add_f32_e32 v183, v124, v125
	v_pk_add_f32 v[168:169], v[168:169], v[168:169] op_sel:[0,1] op_sel_hi:[1,0]
	v_permlane16_swap_b32_e32 v166, v159
	v_add_f32_e32 v178, 0, v178
	v_add_f32_e32 v182, v182, v183
	v_add_f32_e32 v167, v166, v159
	v_mov_b32_e32 v159, v168
	s_ashr_i32 s14, s3, 8
	v_add_f32_e32 v178, v178, v182
	v_mul_f32_e32 v182, v123, v123
	v_mul_f32_e32 v183, v125, v125
	v_permlane16_swap_b32_e32 v168, v159
	s_ashr_i32 s15, s14, 31
	s_nop 0
	s_nop 1
	v_bfe_u32 v135, v227, 4, 1
	v_sub_u32_e32 v135, 0, v135
	v_lshlrev_b32_e32 v134, 4, v135
	v_lshl_add_u64 v[134:135], v[136:137], 0, v[134:135]
	v_permlane16_swap_b32_e32 v126, v122
	v_permlane16_swap_b32_e32 v127, v123
	v_permlane16_swap_b32_e32 v128, v124
	v_permlane16_swap_b32_e32 v129, v125
	global_store_dwordx4 v[134:135], v[126:129], off
	global_store_dwordx4 v[134:135], v[122:125], off offset:32
	s_nop 1
	v_permlane16_swap_b32_e32 v126, v122
	v_permlane16_swap_b32_e32 v127, v123
	v_permlane16_swap_b32_e32 v128, v124
	v_permlane16_swap_b32_e32 v129, v125
	v_fmac_f32_e32 v182, v122, v122
	v_fmac_f32_e32 v183, v124, v124
	v_cvt_pk_bf16_f32 v126, v126, v127
	v_cvt_pk_bf16_f32 v127, v128, v129
	v_cvt_pk_bf16_f32 v128, v122, v123
	v_cvt_pk_bf16_f32 v129, v124, v125
	v_add_f32_e32 v166, v168, v159
	s_lshl_b64 s[14:15], s[14:15], 19
	v_lshlrev_b32_e32 v159, 6, v158
	s_movk_i32 s1, 0x33c0
	s_ashr_i32 s3, s2, 31
	v_and_or_b32 v159, v159, s1, v196
	s_add_u32 s1, s16, s14
	s_addc_u32 s14, s17, s15
	s_lshl_b64 s[24:25], s[2:3], 15
	s_add_u32 s42, s1, s24
	s_addc_u32 s43, s14, s25
	v_lshlrev_b32_e32 v159, 1, v159
	global_store_dwordx4 v159, v[126:129], s[42:43]
	v_add_f32_e32 v182, v182, v183
	s_waitcnt vmcnt(7)
	v_sub_f32_e32 v123, v191, v179
	v_sub_f32_e32 v122, v190, v179
	v_sub_f32_e32 v125, v193, v179
	v_sub_f32_e32 v124, v192, v179
	v_pk_mul_f32 v[124:125], v[0:1], v[124:125] op_sel_hi:[0,1]
	v_pk_mul_f32 v[122:123], v[0:1], v[122:123] op_sel_hi:[0,1]
	v_add_f32_e32 v182, v197, v182
	s_or_b32 s2, s2, 2
	s_ashr_i32 s3, s2, 31
	s_lshl_b64 s[28:29], s[2:3], 15
	s_waitcnt vmcnt(3)
	v_pk_fma_f32 v[122:123], v[202:203], v[122:123], v[242:243]
	v_pk_fma_f32 v[124:125], v[204:205], v[124:125], v[244:245]
	v_pk_fma_f32 v[118:119], v[122:123], s[18:19], v[118:119] op_sel_hi:[1,0,1]
	v_pk_fma_f32 v[120:121], v[124:125], s[18:19], v[120:121] op_sel_hi:[1,0,1]
	v_add_f32_e32 v122, v118, v119
	v_add_f32_e32 v123, v120, v121
	v_add_f32_e32 v122, v122, v123
	v_add_f32_e32 v126, v178, v122
	v_mul_f32_e32 v122, v119, v119
	v_mul_f32_e32 v123, v121, v121
	v_fmac_f32_e32 v122, v118, v118
	v_fmac_f32_e32 v123, v120, v120
	v_add_f32_e32 v122, v122, v123
	v_add_f32_e32 v127, v182, v122
	v_sub_f32_e32 v123, v187, v179
	v_sub_f32_e32 v122, v186, v179
	v_sub_f32_e32 v125, v189, v179
	v_sub_f32_e32 v124, v188, v179
	v_pk_mul_f32 v[124:125], v[0:1], v[124:125] op_sel_hi:[0,1]
	v_pk_mul_f32 v[122:123], v[0:1], v[122:123] op_sel_hi:[0,1]
	v_pk_fma_f32 v[122:123], v[198:199], v[122:123], v[206:207]
	v_pk_fma_f32 v[124:125], v[200:201], v[124:125], v[208:209]
	v_pk_fma_f32 v[114:115], v[122:123], s[18:19], v[114:115] op_sel_hi:[1,0,1]
	v_pk_fma_f32 v[116:117], v[124:125], s[18:19], v[116:117] op_sel_hi:[1,0,1]
	v_add_f32_e32 v0, v114, v115
	v_add_f32_e32 v122, v116, v117
	v_add_f32_e32 v0, v0, v122
	v_mul_f32_e32 v122, v115, v115
	v_mul_f32_e32 v123, v117, v117
	v_add_f32_e32 v0, v126, v0
	v_fmac_f32_e32 v122, v114, v114
	v_fmac_f32_e32 v123, v116, v116
	s_nop 0
	s_nop 1
	v_bfe_u32 v125, v227, 4, 1
	v_sub_u32_e32 v125, 0, v125
	v_lshlrev_b32_e32 v124, 4, v125
	v_lshl_add_u64 v[124:125], v[136:137], 0, v[124:125]
	v_permlane16_swap_b32_e32 v118, v114
	v_permlane16_swap_b32_e32 v119, v115
	v_permlane16_swap_b32_e32 v120, v116
	v_permlane16_swap_b32_e32 v121, v117
	global_store_dwordx4 v[124:125], v[118:121], off offset:512
	global_store_dwordx4 v[124:125], v[114:117], off offset:544
	s_nop 1
	v_permlane16_swap_b32_e32 v118, v114
	v_permlane16_swap_b32_e32 v119, v115
	v_permlane16_swap_b32_e32 v120, v116
	v_permlane16_swap_b32_e32 v121, v117
	v_add_f32_e32 v122, v122, v123
	v_cvt_pk_bf16_f32 v118, v118, v119
	v_cvt_pk_bf16_f32 v119, v120, v121
	v_cvt_pk_bf16_f32 v120, v114, v115
	v_mov_b32_e32 v114, v0
	v_add_f32_e32 v122, v127, v122
	s_nop 0
	v_permlane16_swap_b32_e32 v0, v114
	v_add_f32_e32 v114, v0, v114
	v_mov_b32_e32 v0, v122
	s_nop 1
	v_permlane16_swap_b32_e32 v122, v0
	v_add_f32_e32 v115, v122, v0
	v_mov_b32_e32 v135, v133
	v_mov_b32_e32 v134, v132
	v_mov_b32_e32 v177, v175
	v_mov_b32_e32 v176, v174
	v_mov_b32_e32 v169, v167
	v_mov_b32_e32 v168, v166
	v_cvt_pk_bf16_f32 v121, v116, v117
	s_add_u32 s40, s1, s28
	v_mov_b32_e32 v116, v114
	v_mov_b32_e32 v117, v115
	v_permlane32_swap_b32_e32 v133, v135
	v_permlane32_swap_b32_e32 v132, v134
	v_permlane32_swap_b32_e32 v175, v177
	v_permlane32_swap_b32_e32 v174, v176
	v_permlane32_swap_b32_e32 v167, v169
	v_permlane32_swap_b32_e32 v166, v168
	s_addc_u32 s41, s14, s29
	v_permlane32_swap_b32_e32 v114, v116
	v_permlane32_swap_b32_e32 v115, v117
	global_store_dwordx4 v159, v[118:121], s[40:41]
	s_and_saveexec_b64 s[26:27], s[44:45]
	s_cbranch_execz .LBB0_1537
	v_pk_add_f32 v[114:115], v[114:115], v[116:117]
	v_lshl_add_u64 v[116:117], s[6:7], 0, v[130:131]
	v_lshl_add_u64 v[116:117], s[52:53], 2, v[116:117]
	global_store_dwordx2 v[116:117], v[114:115], off
; __device__ __forceinline__ float xsum16(float v) { const auto r = __builtin_amdgcn_permlane16_swap(__float_as_uint(v), __float_as_uint(v), false, false); return __uint_as_float(r[0]) + __uint_as_float(r[1]); }
; __device__ __forceinline__ float xsum32(float v) { const auto r = __builtin_amdgcn_permlane32_swap(__float_as_uint(v), __float_as_uint(v), false, false); return __uint_as_float(r[0]) + __uint_as_float(r[1]); }
; __device__ __forceinline__ size_t blk_off(int r, int c, int K) { return (size_t)(r >> 8) * 256 * K + (size_t)(c >> 6) * (256 * 64) + (size_t)((r & 255) * 64 + (c & 63)); }
; __device__ __forceinline__ u32x4 pack8(const f32x4 a, const f32x4 b) { u32x4 w; w.x = cvt_pk_bf16(a[0], a[1]); w.y = cvt_pk_bf16(a[2], a[3]); w.z = cvt_pk_bf16(b[0], b[1]); w.w = cvt_pk_bf16(b[2], b[3]); return w; }
;     __device__ __forceinline__ void operator()(const f32x4 (&acc)[2][2][4][2], const pg8::Unit& u, int wr, int wc, int fr, int fq) const {
;     ...
;             for (int m = 0; m < 4; ++m) { const int row = row0 + ai * 128 + m * 16; const float mu = mu4[m], rs = rs4[m];
;                 f32x4 yv[2][2], gq[2][2], bq_[2][2];
; #pragma unroll
;                 for (int bj = 0; bj < 2; ++bj)
; #pragma unroll
;                     for (int n = 0; n < 2; ++n) { yv[bj][n] = *(const f32x4*)(Yin + (size_t)row * D_ + col0 + bj * 128 + 4 * n); gq[bj][n] = *(const f32x4*)(g + col0 + bj * 128 + 4 * n); bq_[bj][n] = *(const f32x4*)(b + col0 + bj * 128 + 4 * n); }
;                 asm volatile("" ::: "memory");
;                 float s1 = 0.f, s2 = 0.f;
; #pragma unroll
;                 for (int bj = 0; bj < 2; ++bj) { float* yp = Y + (size_t)row * D_ + col0 + bj * 128; f32x4 v[2];
; #pragma unroll
;                     for (int n = 0; n < 2; ++n) { v[n] = (((yv[bj][n] - mu) * rs) * gq[bj][n] + bq_[bj][n]) * ALPHA_ + acc[ai][bj][m][n] * sc;
;                         *(f32x4*)(yp + 4 * n) = v[n]; s1 += (v[n][0] + v[n][1]) + (v[n][2] + v[n][3]); s2 += (v[n][0] * v[n][0] + v[n][1] * v[n][1]) + (v[n][2] * v[n][2] + v[n][3] * v[n][3]); }
;                     *(u32x4*)(Yb + blk_off(row, col0 + bj * 128, D_)) = pack8(v[0], v[1]); }
;                 s1 = xsum32(xsum16(s1)); s2 = xsum32(xsum16(s2));
;                 if (fq == 0) *(f32x2*)(stn + (size_t)row * 32 + (u.pn * 4 + wc) * 2) = (f32x2){s1, s2}; asm volatile("" ::: "memory"); } }
.LBB0_1537:
	s_or_b64 exec, exec, s[26:27]
	v_pk_add_f32 v[114:115], v[132:133], v[134:135]
	s_mov_b32 s2, 0x3a800000
	v_pk_mul_f32 v[178:179], v[114:115], s[2:3] op_sel_hi:[1,0]
	s_mov_b32 s1, 0x800000
	v_fma_f32 v0, -v179, v179, v178
	v_max_f32_e32 v0, 0, v0
	v_add_f32_e32 v0, 0x3727c5ac, v0
	v_cmp_gt_f32_e32 vcc, s1, v0
	v_mul_f32_e32 v114, 0x4b800000, v0
	s_load_dwordx16 s[64:79], s[34:35], 0x38
	v_cndmask_b32_e32 v0, v0, v114, vcc
	v_rsq_f32_e32 v0, v0
	v_lshlrev_b32_e32 v159, 6, v180
	s_mov_b32 s2, 0x3fd744fd
	v_mul_f32_e32 v114, 0x45800000, v0
	v_cndmask_b32_e32 v0, v0, v114, vcc
	v_lshlrev_b64 v[114:115], 12, v[180:181]
	s_waitcnt lgkmcnt(0)
	v_lshl_add_u64 v[114:115], s[78:79], 0, v[114:115]
	v_lshl_add_u64 v[182:183], v[152:153], 2, v[114:115]
	global_load_dwordx4 v[186:189], v[182:183], off offset:16
	global_load_dwordx4 v[190:193], v[182:183], off
	global_load_dwordx4 v[198:201], v[156:157], off offset:16
	global_load_dwordx4 v[202:205], v[156:157], off
	global_load_dwordx4 v[206:209], v[154:155], off offset:16
	global_load_dwordx4 v[210:213], v[154:155], off
	global_load_dwordx4 v[114:117], v[182:183], off offset:528
	global_load_dwordx4 v[134:137], v[182:183], off offset:512
	global_load_dwordx4 v[118:121], v[156:157], off offset:528
	global_load_dwordx4 v[126:129], v[156:157], off offset:512
	global_load_dwordx4 v[122:125], v[154:155], off offset:528
	global_load_dwordx4 v[130:133], v[154:155], off offset:512
	s_movk_i32 s1, 0x37c0
	v_and_or_b32 v159, v159, s1, v196
	v_lshlrev_b32_e32 v159, 1, v159
	s_waitcnt vmcnt(10)
	v_sub_f32_e32 v181, v191, v179
	v_sub_f32_e32 v180, v190, v179
	v_sub_f32_e32 v191, v193, v179
	v_sub_f32_e32 v190, v192, v179
	v_pk_mul_f32 v[190:191], v[0:1], v[190:191] op_sel_hi:[0,1]
	v_pk_mul_f32 v[180:181], v[0:1], v[180:181] op_sel_hi:[0,1]
	s_waitcnt vmcnt(6)
	v_pk_fma_f32 v[180:181], v[202:203], v[180:181], v[210:211]
	v_pk_fma_f32 v[190:191], v[204:205], v[190:191], v[212:213]
	v_pk_fma_f32 v[110:111], v[180:181], s[2:3], v[110:111] op_sel_hi:[1,0,1]
	v_pk_fma_f32 v[112:113], v[190:191], s[2:3], v[112:113] op_sel_hi:[1,0,1]
	v_add_f32_e32 v178, v110, v111
	v_add_f32_e32 v180, v112, v113
	v_add_f32_e32 v178, v178, v180
	v_mul_f32_e32 v180, v111, v111
	v_mul_f32_e32 v181, v113, v113
	v_fmac_f32_e32 v180, v110, v110
	v_fmac_f32_e32 v181, v112, v112
	v_add_f32_e32 v190, v180, v181
	v_sub_f32_e32 v181, v187, v179
	v_sub_f32_e32 v180, v186, v179
	v_sub_f32_e32 v187, v189, v179
	v_sub_f32_e32 v186, v188, v179
	v_pk_mul_f32 v[186:187], v[0:1], v[186:187] op_sel_hi:[0,1]
	v_pk_mul_f32 v[180:181], v[0:1], v[180:181] op_sel_hi:[0,1]
	v_pk_fma_f32 v[180:181], v[198:199], v[180:181], v[206:207]
	v_pk_fma_f32 v[186:187], v[200:201], v[186:187], v[208:209]
	v_pk_fma_f32 v[106:107], v[180:181], s[2:3], v[106:107] op_sel_hi:[1,0,1]
	v_pk_fma_f32 v[108:109], v[186:187], s[2:3], v[108:109] op_sel_hi:[1,0,1]
	v_add_f32_e32 v180, v106, v107
	v_add_f32_e32 v181, v108, v109
	v_add_f32_e32 v178, 0, v178
	v_add_f32_e32 v180, v180, v181
	v_add_f32_e32 v178, v178, v180
	v_mul_f32_e32 v180, v107, v107
	v_mul_f32_e32 v181, v109, v109
	s_nop 0
	s_nop 1
	v_bfe_u32 v187, v227, 4, 1
	v_sub_u32_e32 v187, 0, v187
	v_lshlrev_b32_e32 v186, 4, v187
	v_lshl_add_u64 v[186:187], v[182:183], 0, v[186:187]
	v_permlane16_swap_b32_e32 v110, v106
	v_permlane16_swap_b32_e32 v111, v107
	v_permlane16_swap_b32_e32 v112, v108
	v_permlane16_swap_b32_e32 v113, v109
	global_store_dwordx4 v[186:187], v[110:113], off
	global_store_dwordx4 v[186:187], v[106:109], off offset:32
	s_nop 1
	v_permlane16_swap_b32_e32 v110, v106
	v_permlane16_swap_b32_e32 v111, v107
	v_permlane16_swap_b32_e32 v112, v108
	v_permlane16_swap_b32_e32 v113, v109
	v_fmac_f32_e32 v180, v106, v106
	v_fmac_f32_e32 v181, v108, v108
	v_cvt_pk_bf16_f32 v110, v110, v111
	v_cvt_pk_bf16_f32 v111, v112, v113
	v_cvt_pk_bf16_f32 v112, v106, v107
	v_cvt_pk_bf16_f32 v113, v108, v109
	s_waitcnt vmcnt(6)
	v_sub_f32_e32 v107, v135, v179
	v_sub_f32_e32 v106, v134, v179
	v_sub_f32_e32 v109, v137, v179
	v_sub_f32_e32 v108, v136, v179
	v_pk_mul_f32 v[108:109], v[0:1], v[108:109] op_sel_hi:[0,1]
	v_pk_mul_f32 v[106:107], v[0:1], v[106:107] op_sel_hi:[0,1]
	s_waitcnt vmcnt(2)
	v_pk_fma_f32 v[106:107], v[126:127], v[106:107], v[130:131]
	v_pk_fma_f32 v[108:109], v[128:129], v[108:109], v[132:133]
	v_pk_fma_f32 v[102:103], v[106:107], s[2:3], v[102:103] op_sel_hi:[1,0,1]
	v_pk_fma_f32 v[104:105], v[108:109], s[2:3], v[104:105] op_sel_hi:[1,0,1]
	v_add_f32_e32 v106, v102, v103
	v_add_f32_e32 v107, v104, v105
	v_add_f32_e32 v106, v106, v107
	global_store_dwordx4 v159, v[110:113], s[42:43]
	v_mul_f32_e32 v107, v105, v105
	v_add_f32_e32 v180, v180, v181
	v_add_f32_e32 v110, v178, v106
	v_mul_f32_e32 v106, v103, v103
	v_fmac_f32_e32 v106, v102, v102
	v_fmac_f32_e32 v107, v104, v104
	v_add_f32_e32 v180, v190, v180
	v_add_f32_e32 v106, v106, v107
	v_add_f32_e32 v111, v180, v106
	v_sub_f32_e32 v107, v115, v179
	v_sub_f32_e32 v106, v114, v179
	v_sub_f32_e32 v109, v117, v179
	v_sub_f32_e32 v108, v116, v179
	v_pk_mul_f32 v[108:109], v[0:1], v[108:109] op_sel_hi:[0,1]
	v_pk_mul_f32 v[106:107], v[0:1], v[106:107] op_sel_hi:[0,1]
	v_pk_fma_f32 v[106:107], v[118:119], v[106:107], v[122:123]
	v_pk_fma_f32 v[108:109], v[120:121], v[108:109], v[124:125]
	v_pk_fma_f32 v[98:99], v[106:107], s[2:3], v[98:99] op_sel_hi:[1,0,1]
	v_pk_fma_f32 v[100:101], v[108:109], s[2:3], v[100:101] op_sel_hi:[1,0,1]
	v_add_f32_e32 v0, v98, v99
	v_add_f32_e32 v106, v100, v101
	v_add_f32_e32 v0, v0, v106
	v_mul_f32_e32 v106, v99, v99
	v_mul_f32_e32 v107, v101, v101
	v_add_f32_e32 v0, v110, v0
	v_fmac_f32_e32 v106, v98, v98
	v_fmac_f32_e32 v107, v100, v100
	s_nop 0
	s_nop 1
	v_bfe_u32 v109, v227, 4, 1
	v_sub_u32_e32 v109, 0, v109
	v_lshlrev_b32_e32 v108, 4, v109
	v_lshl_add_u64 v[108:109], v[182:183], 0, v[108:109]
	v_permlane16_swap_b32_e32 v102, v98
	v_permlane16_swap_b32_e32 v103, v99
	v_permlane16_swap_b32_e32 v104, v100
	v_permlane16_swap_b32_e32 v105, v101
	global_store_dwordx4 v[108:109], v[102:105], off offset:512
	global_store_dwordx4 v[108:109], v[98:101], off offset:544
	s_nop 1
	v_permlane16_swap_b32_e32 v102, v98
	v_permlane16_swap_b32_e32 v103, v99
	v_permlane16_swap_b32_e32 v104, v100
	v_permlane16_swap_b32_e32 v105, v101
	v_add_f32_e32 v106, v106, v107
	v_cvt_pk_bf16_f32 v102, v102, v103
	v_cvt_pk_bf16_f32 v103, v104, v105
	v_cvt_pk_bf16_f32 v104, v98, v99
	v_mov_b32_e32 v98, v0
	v_add_f32_e32 v106, v111, v106
	s_nop 0
	v_permlane16_swap_b32_e32 v0, v98
	v_add_f32_e32 v98, v0, v98
	v_mov_b32_e32 v0, v106
	s_nop 1
	v_permlane16_swap_b32_e32 v106, v0
	v_add_f32_e32 v99, v106, v0
	v_cvt_pk_bf16_f32 v105, v100, v101
	v_mov_b32_e32 v100, v98
	v_mov_b32_e32 v101, v99
	s_nop 0
	v_permlane32_swap_b32_e32 v98, v100
	v_permlane32_swap_b32_e32 v99, v101
	global_store_dwordx4 v159, v[102:105], s[40:41]
	s_and_saveexec_b64 s[26:27], s[44:45]
	s_cbranch_execz .LBB0_1539
; __device__ __forceinline__ float xsum16(float v) { const auto r = __builtin_amdgcn_permlane16_swap(__float_as_uint(v), __float_as_uint(v), false, false); return __uint_as_float(r[0]) + __uint_as_float(r[1]); }
; __device__ __forceinline__ float xsum32(float v) { const auto r = __builtin_amdgcn_permlane32_swap(__float_as_uint(v), __float_as_uint(v), false, false); return __uint_as_float(r[0]) + __uint_as_float(r[1]); }
; __device__ __forceinline__ size_t blk_off(int r, int c, int K) { return (size_t)(r >> 8) * 256 * K + (size_t)(c >> 6) * (256 * 64) + (size_t)((r & 255) * 64 + (c & 63)); }
;     __device__ __forceinline__ void operator()(const f32x4 (&acc)[2][2][4][2], const pg8::Unit& u, int wr, int wc, int fr, int fq) const {
;         const int row0 = u.pm * 256 + wr * 64 + fr, col0 = u.pn * 256 + wc * 32 + fq * 8;
; #pragma unroll
;         for (int ai = 0; ai < 2; ++ai) { float mu4[4], rs4[4]; row_stats4(stp, row0 + ai * 128, fq, mu4, rs4);
; #pragma unroll
;             for (int m = 0; m < 4; ++m) { const int row = row0 + ai * 128 + m * 16; const float mu = mu4[m], rs = rs4[m];
;                 f32x4 yv[2][2], gq[2][2], bq_[2][2];
; #pragma unroll
;                 for (int bj = 0; bj < 2; ++bj)
; #pragma unroll
;                     for (int n = 0; n < 2; ++n) { yv[bj][n] = *(const f32x4*)(Yin + (size_t)row * D_ + col0 + bj * 128 + 4 * n); gq[bj][n] = *(const f32x4*)(g + col0 + bj * 128 + 4 * n); bq_[bj][n] = *(const f32x4*)(b + col0 + bj * 128 + 4 * n); }
;                 asm volatile("" ::: "memory");
;                 float s1 = 0.f, s2 = 0.f;
; #pragma unroll
;                 for (int bj = 0; bj < 2; ++bj) { float* yp = Y + (size_t)row * D_ + col0 + bj * 128; f32x4 v[2];
; #pragma unroll
;                     for (int n = 0; n < 2; ++n) { v[n] = (((yv[bj][n] - mu) * rs) * gq[bj][n] + bq_[bj][n]) * ALPHA_ + acc[ai][bj][m][n] * sc;
;                         *(f32x4*)(yp + 4 * n) = v[n]; s1 += (v[n][0] + v[n][1]) + (v[n][2] + v[n][3]); s2 += (v[n][0] * v[n][0] + v[n][1] * v[n][1]) + (v[n][2] * v[n][2] + v[n][3] * v[n][3]); }
;                     *(u32x4*)(Yb + blk_off(row, col0 + bj * 128, D_)) = pack8(v[0], v[1]); }
;                 s1 = xsum32(xsum16(s1)); s2 = xsum32(xsum16(s2));
;                 if (fq == 0) *(f32x2*)(stn + (size_t)row * 32 + (u.pn * 4 + wc) * 2) = (f32x2){s1, s2}; asm volatile("" ::: "memory"); } }
	v_pk_add_f32 v[98:99], v[98:99], v[100:101]
	v_lshl_add_u64 v[100:101], s[6:7], 0, v[172:173]
	v_lshl_add_u64 v[100:101], s[52:53], 2, v[100:101]
	global_store_dwordx2 v[100:101], v[98:99], off
.LBB0_1539:
	s_or_b64 exec, exec, s[26:27]
	v_pk_add_f32 v[98:99], v[174:175], v[176:177]
	s_mov_b32 s2, 0x3a800000
	v_pk_mul_f32 v[122:123], v[98:99], s[2:3] op_sel_hi:[1,0]
	s_mov_b32 s1, 0x800000
	v_fma_f32 v0, -v123, v123, v122
	v_max_f32_e32 v0, 0, v0
	v_add_f32_e32 v0, 0x3727c5ac, v0
	v_cmp_gt_f32_e32 vcc, s1, v0
	v_mul_f32_e32 v98, 0x4b800000, v0
	s_load_dwordx16 s[64:79], s[34:35], 0x38
	v_cndmask_b32_e32 v0, v0, v98, vcc
	v_rsq_f32_e32 v0, v0
	s_mov_b32 s2, 0x3fd744fd
	v_lshlrev_b32_e32 v122, 6, v170
	v_mul_f32_e32 v98, 0x45800000, v0
	v_cndmask_b32_e32 v0, v0, v98, vcc
	v_lshlrev_b64 v[98:99], 12, v[170:171]
	s_waitcnt lgkmcnt(0)
	v_lshl_add_u64 v[98:99], s[78:79], 0, v[98:99]
	v_lshl_add_u64 v[124:125], v[152:153], 2, v[98:99]
	global_load_dwordx4 v[126:129], v[124:125], off offset:16
	global_load_dwordx4 v[130:133], v[124:125], off
	global_load_dwordx4 v[134:137], v[156:157], off offset:16
	global_load_dwordx4 v[172:175], v[156:157], off
	global_load_dwordx4 v[176:179], v[154:155], off offset:16
	global_load_dwordx4 v[180:183], v[154:155], off
	global_load_dwordx4 v[98:101], v[124:125], off offset:528
	global_load_dwordx4 v[118:121], v[124:125], off offset:512
	global_load_dwordx4 v[102:105], v[156:157], off offset:528
	global_load_dwordx4 v[110:113], v[156:157], off offset:512
	global_load_dwordx4 v[106:109], v[154:155], off offset:528
	global_load_dwordx4 v[114:117], v[154:155], off offset:512
	s_movk_i32 s1, 0x3bc0
	v_and_or_b32 v122, v122, s1, v196
	v_lshlrev_b32_e32 v122, 1, v122
	s_waitcnt vmcnt(11)
	v_sub_f32_e32 v127, v127, v123
	s_waitcnt vmcnt(10)
	v_sub_f32_e32 v131, v131, v123
	v_sub_f32_e32 v130, v130, v123
	v_sub_f32_e32 v133, v133, v123
	v_sub_f32_e32 v132, v132, v123
	v_sub_f32_e32 v126, v126, v123
	v_sub_f32_e32 v129, v129, v123
	v_sub_f32_e32 v128, v128, v123
	v_pk_mul_f32 v[132:133], v[0:1], v[132:133] op_sel_hi:[0,1]
	v_pk_mul_f32 v[130:131], v[0:1], v[130:131] op_sel_hi:[0,1]
	v_pk_mul_f32 v[128:129], v[0:1], v[128:129] op_sel_hi:[0,1]
	v_pk_mul_f32 v[126:127], v[0:1], v[126:127] op_sel_hi:[0,1]
	s_waitcnt vmcnt(6)
	v_pk_fma_f32 v[130:131], v[172:173], v[130:131], v[180:181]
	v_pk_fma_f32 v[132:133], v[174:175], v[132:133], v[182:183]
	v_pk_fma_f32 v[126:127], v[134:135], v[126:127], v[176:177]
	v_pk_fma_f32 v[128:129], v[136:137], v[128:129], v[178:179]
	v_pk_fma_f32 v[96:97], v[132:133], s[2:3], v[96:97] op_sel_hi:[1,0,1]
	v_pk_fma_f32 v[94:95], v[130:131], s[2:3], v[94:95] op_sel_hi:[1,0,1]
	v_pk_fma_f32 v[92:93], v[128:129], s[2:3], v[92:93] op_sel_hi:[1,0,1]
	v_pk_fma_f32 v[90:91], v[126:127], s[2:3], v[90:91] op_sel_hi:[1,0,1]
	v_add_f32_e32 v130, v94, v95
	v_add_f32_e32 v131, v96, v97
	v_add_f32_e32 v126, v90, v91
	v_add_f32_e32 v127, v92, v93
	v_add_f32_e32 v130, v130, v131
	v_mul_f32_e32 v131, v95, v95
	v_mul_f32_e32 v132, v97, v97
	v_add_f32_e32 v126, v126, v127
	v_mul_f32_e32 v127, v91, v91
	v_mul_f32_e32 v128, v93, v93
	s_nop 0
	v_fmac_f32_e32 v131, v94, v94
	v_fmac_f32_e32 v132, v96, v96
	s_nop 1
	v_bfe_u32 v135, v227, 4, 1
	v_sub_u32_e32 v135, 0, v135
	v_lshlrev_b32_e32 v134, 4, v135
	v_lshl_add_u64 v[134:135], v[124:125], 0, v[134:135]
	v_permlane16_swap_b32_e32 v94, v90
	v_permlane16_swap_b32_e32 v95, v91
	v_permlane16_swap_b32_e32 v96, v92
	v_permlane16_swap_b32_e32 v97, v93
	global_store_dwordx4 v[134:135], v[94:97], off
	global_store_dwordx4 v[134:135], v[90:93], off offset:32
	s_nop 1
	v_permlane16_swap_b32_e32 v94, v90
	v_permlane16_swap_b32_e32 v95, v91
	v_permlane16_swap_b32_e32 v96, v92
	v_permlane16_swap_b32_e32 v97, v93
	v_fmac_f32_e32 v127, v90, v90
	v_fmac_f32_e32 v128, v92, v92
	v_cvt_pk_bf16_f32 v94, v94, v95
	v_cvt_pk_bf16_f32 v95, v96, v97
	v_cvt_pk_bf16_f32 v96, v90, v91
	v_cvt_pk_bf16_f32 v97, v92, v93
	s_waitcnt vmcnt(6)
	v_sub_f32_e32 v91, v119, v123
	v_sub_f32_e32 v90, v118, v123
	v_sub_f32_e32 v93, v121, v123
	v_sub_f32_e32 v92, v120, v123
	v_pk_mul_f32 v[92:93], v[0:1], v[92:93] op_sel_hi:[0,1]
	v_pk_mul_f32 v[90:91], v[0:1], v[90:91] op_sel_hi:[0,1]
	s_waitcnt vmcnt(2)
	v_pk_fma_f32 v[90:91], v[110:111], v[90:91], v[114:115]
	v_pk_fma_f32 v[92:93], v[112:113], v[92:93], v[116:117]
	v_pk_fma_f32 v[86:87], v[90:91], s[2:3], v[86:87] op_sel_hi:[1,0,1]
	v_pk_fma_f32 v[88:89], v[92:93], s[2:3], v[88:89] op_sel_hi:[1,0,1]
	v_add_f32_e32 v130, 0, v130
	v_add_f32_e32 v90, v86, v87
	v_add_f32_e32 v91, v88, v89
	v_add_f32_e32 v126, v130, v126
	v_add_f32_e32 v90, v90, v91
	global_store_dwordx4 v122, v[94:97], s[42:43]
	v_mul_f32_e32 v91, v89, v89
	v_add_f32_e32 v131, v131, v132
	v_add_f32_e32 v94, v126, v90
	v_mul_f32_e32 v90, v87, v87
	v_add_f32_e32 v127, v127, v128
	v_fmac_f32_e32 v90, v86, v86
	v_fmac_f32_e32 v91, v88, v88
	v_add_f32_e32 v127, v131, v127
	v_add_f32_e32 v90, v90, v91
	v_add_f32_e32 v95, v127, v90
	v_sub_f32_e32 v91, v99, v123
	v_sub_f32_e32 v90, v98, v123
	v_sub_f32_e32 v93, v101, v123
	v_sub_f32_e32 v92, v100, v123
	v_pk_mul_f32 v[92:93], v[0:1], v[92:93] op_sel_hi:[0,1]
	v_pk_mul_f32 v[90:91], v[0:1], v[90:91] op_sel_hi:[0,1]
	v_pk_fma_f32 v[90:91], v[102:103], v[90:91], v[106:107]
	v_pk_fma_f32 v[92:93], v[104:105], v[92:93], v[108:109]
	v_pk_fma_f32 v[82:83], v[90:91], s[2:3], v[82:83] op_sel_hi:[1,0,1]
	v_pk_fma_f32 v[84:85], v[92:93], s[2:3], v[84:85] op_sel_hi:[1,0,1]
	v_add_f32_e32 v0, v82, v83
	v_add_f32_e32 v90, v84, v85
	v_add_f32_e32 v0, v0, v90
	v_mul_f32_e32 v90, v83, v83
	v_mul_f32_e32 v91, v85, v85
	v_add_f32_e32 v0, v94, v0
	v_fmac_f32_e32 v90, v82, v82
	v_fmac_f32_e32 v91, v84, v84
	s_nop 0
	s_nop 1
	v_bfe_u32 v93, v227, 4, 1
	v_sub_u32_e32 v93, 0, v93
	v_lshlrev_b32_e32 v92, 4, v93
	v_lshl_add_u64 v[92:93], v[124:125], 0, v[92:93]
	v_permlane16_swap_b32_e32 v86, v82
	v_permlane16_swap_b32_e32 v87, v83
	v_permlane16_swap_b32_e32 v88, v84
	v_permlane16_swap_b32_e32 v89, v85
	global_store_dwordx4 v[92:93], v[86:89], off offset:512
	global_store_dwordx4 v[92:93], v[82:85], off offset:544
	s_nop 1
	v_permlane16_swap_b32_e32 v86, v82
	v_permlane16_swap_b32_e32 v87, v83
	v_permlane16_swap_b32_e32 v88, v84
	v_permlane16_swap_b32_e32 v89, v85
	v_add_f32_e32 v90, v90, v91
	v_cvt_pk_bf16_f32 v86, v86, v87
	v_cvt_pk_bf16_f32 v87, v88, v89
	v_cvt_pk_bf16_f32 v88, v82, v83
	v_mov_b32_e32 v82, v0
	v_add_f32_e32 v90, v95, v90
	s_nop 0
	v_permlane16_swap_b32_e32 v0, v82
	v_add_f32_e32 v82, v0, v82
	v_mov_b32_e32 v0, v90
	s_nop 1
	v_permlane16_swap_b32_e32 v90, v0
	v_add_f32_e32 v83, v90, v0
	v_cvt_pk_bf16_f32 v89, v84, v85
	v_mov_b32_e32 v84, v82
	v_mov_b32_e32 v85, v83
	s_nop 0
	v_permlane32_swap_b32_e32 v82, v84
	v_permlane32_swap_b32_e32 v83, v85
	global_store_dwordx4 v122, v[86:89], s[40:41]
	s_and_saveexec_b64 s[26:27], s[44:45]
	s_cbranch_execz .LBB0_1541
	v_pk_add_f32 v[82:83], v[82:83], v[84:85]
	v_lshl_add_u64 v[84:85], s[6:7], 0, v[164:165]
	v_lshl_add_u64 v[84:85], s[52:53], 2, v[84:85]
	global_store_dwordx2 v[84:85], v[82:83], off
; __device__ __forceinline__ float xsum16(float v) { const auto r = __builtin_amdgcn_permlane16_swap(__float_as_uint(v), __float_as_uint(v), false, false); return __uint_as_float(r[0]) + __uint_as_float(r[1]); }
; __device__ __forceinline__ float xsum32(float v) { const auto r = __builtin_amdgcn_permlane32_swap(__float_as_uint(v), __float_as_uint(v), false, false); return __uint_as_float(r[0]) + __uint_as_float(r[1]); }
; __device__ __forceinline__ size_t blk_off(int r, int c, int K) { return (size_t)(r >> 8) * 256 * K + (size_t)(c >> 6) * (256 * 64) + (size_t)((r & 255) * 64 + (c & 63)); }
;     __device__ __forceinline__ void operator()(const f32x4 (&acc)[2][2][4][2], const pg8::Unit& u, int wr, int wc, int fr, int fq) const {
;         const int row0 = u.pm * 256 + wr * 64 + fr, col0 = u.pn * 256 + wc * 32 + fq * 8;
; #pragma unroll
;         for (int ai = 0; ai < 2; ++ai) { float mu4[4], rs4[4]; row_stats4(stp, row0 + ai * 128, fq, mu4, rs4);
; #pragma unroll
;             for (int m = 0; m < 4; ++m) { const int row = row0 + ai * 128 + m * 16; const float mu = mu4[m], rs = rs4[m];
;                 f32x4 yv[2][2], gq[2][2], bq_[2][2];
; #pragma unroll
;                 for (int bj = 0; bj < 2; ++bj)
; #pragma unroll
;                     for (int n = 0; n < 2; ++n) { yv[bj][n] = *(const f32x4*)(Yin + (size_t)row * D_ + col0 + bj * 128 + 4 * n); gq[bj][n] = *(const f32x4*)(g + col0 + bj * 128 + 4 * n); bq_[bj][n] = *(const f32x4*)(b + col0 + bj * 128 + 4 * n); }
;                 asm volatile("" ::: "memory");
;                 float s1 = 0.f, s2 = 0.f;
; #pragma unroll
;                 for (int bj = 0; bj < 2; ++bj) { float* yp = Y + (size_t)row * D_ + col0 + bj * 128; f32x4 v[2];
; #pragma unroll
;                     for (int n = 0; n < 2; ++n) { v[n] = (((yv[bj][n] - mu) * rs) * gq[bj][n] + bq_[bj][n]) * ALPHA_ + acc[ai][bj][m][n] * sc;
;                         *(f32x4*)(yp + 4 * n) = v[n]; s1 += (v[n][0] + v[n][1]) + (v[n][2] + v[n][3]); s2 += (v[n][0] * v[n][0] + v[n][1] * v[n][1]) + (v[n][2] * v[n][2] + v[n][3] * v[n][3]); }
;                     *(u32x4*)(Yb + blk_off(row, col0 + bj * 128, D_)) = pack8(v[0], v[1]); }
;                 s1 = xsum32(xsum16(s1)); s2 = xsum32(xsum16(s2));
;                 if (fq == 0) *(f32x2*)(stn + (size_t)row * 32 + (u.pn * 4 + wc) * 2) = (f32x2){s1, s2}; asm volatile("" ::: "memory"); } }
.LBB0_1541:
	s_or_b64 exec, exec, s[26:27]
	v_pk_add_f32 v[82:83], v[166:167], v[168:169]
	s_mov_b32 s2, 0x3a800000
	v_pk_mul_f32 v[106:107], v[82:83], s[2:3] op_sel_hi:[1,0]
	s_mov_b32 s1, 0x800000
	v_fma_f32 v0, -v107, v107, v106
	v_max_f32_e32 v0, 0, v0
	v_add_f32_e32 v0, 0x3727c5ac, v0
	v_cmp_gt_f32_e32 vcc, s1, v0
	v_mul_f32_e32 v82, 0x4b800000, v0
	s_load_dwordx16 s[64:79], s[34:35], 0x38
	v_cndmask_b32_e32 v0, v0, v82, vcc
	v_rsq_f32_e32 v0, v0
	s_mov_b32 s2, 0x3fd744fd
	v_lshlrev_b32_e32 v106, 6, v162
	v_mul_f32_e32 v82, 0x45800000, v0
	v_cndmask_b32_e32 v0, v0, v82, vcc
	v_lshlrev_b64 v[82:83], 12, v[162:163]
	s_waitcnt lgkmcnt(0)
	v_lshl_add_u64 v[82:83], s[78:79], 0, v[82:83]
	v_lshl_add_u64 v[108:109], v[152:153], 2, v[82:83]
	global_load_dwordx4 v[110:113], v[108:109], off offset:16
	global_load_dwordx4 v[114:117], v[108:109], off
	global_load_dwordx4 v[118:121], v[156:157], off offset:16
	global_load_dwordx4 v[122:125], v[156:157], off
	global_load_dwordx4 v[126:129], v[154:155], off offset:16
	global_load_dwordx4 v[130:133], v[154:155], off
	global_load_dwordx4 v[82:85], v[108:109], off offset:528
	global_load_dwordx4 v[102:105], v[108:109], off offset:512
	global_load_dwordx4 v[86:89], v[156:157], off offset:528
	global_load_dwordx4 v[94:97], v[156:157], off offset:512
	global_load_dwordx4 v[90:93], v[154:155], off offset:528
	global_load_dwordx4 v[98:101], v[154:155], off offset:512
	s_movk_i32 s1, 0x3fc0
	v_and_or_b32 v106, v106, s1, v196
	v_lshlrev_b32_e32 v106, 1, v106
	s_waitcnt vmcnt(11)
	v_sub_f32_e32 v111, v111, v107
	s_waitcnt vmcnt(10)
	v_sub_f32_e32 v115, v115, v107
	v_sub_f32_e32 v114, v114, v107
	v_sub_f32_e32 v117, v117, v107
	v_sub_f32_e32 v116, v116, v107
	v_sub_f32_e32 v110, v110, v107
	v_sub_f32_e32 v113, v113, v107
	v_sub_f32_e32 v112, v112, v107
	v_pk_mul_f32 v[116:117], v[0:1], v[116:117] op_sel_hi:[0,1]
	v_pk_mul_f32 v[114:115], v[0:1], v[114:115] op_sel_hi:[0,1]
	v_pk_mul_f32 v[112:113], v[0:1], v[112:113] op_sel_hi:[0,1]
	v_pk_mul_f32 v[110:111], v[0:1], v[110:111] op_sel_hi:[0,1]
	s_waitcnt vmcnt(6)
	v_pk_fma_f32 v[114:115], v[122:123], v[114:115], v[130:131]
	v_pk_fma_f32 v[116:117], v[124:125], v[116:117], v[132:133]
	v_pk_fma_f32 v[110:111], v[118:119], v[110:111], v[126:127]
	v_pk_fma_f32 v[112:113], v[120:121], v[112:113], v[128:129]
	v_pk_fma_f32 v[80:81], v[116:117], s[2:3], v[80:81] op_sel_hi:[1,0,1]
	v_pk_fma_f32 v[78:79], v[114:115], s[2:3], v[78:79] op_sel_hi:[1,0,1]
	v_pk_fma_f32 v[76:77], v[112:113], s[2:3], v[76:77] op_sel_hi:[1,0,1]
	v_pk_fma_f32 v[74:75], v[110:111], s[2:3], v[74:75] op_sel_hi:[1,0,1]
	v_add_f32_e32 v114, v78, v79
	v_add_f32_e32 v115, v80, v81
	v_add_f32_e32 v110, v74, v75
	v_add_f32_e32 v111, v76, v77
	v_add_f32_e32 v114, v114, v115
	v_mul_f32_e32 v115, v79, v79
	v_mul_f32_e32 v116, v81, v81
	v_add_f32_e32 v110, v110, v111
	v_mul_f32_e32 v111, v75, v75
	v_mul_f32_e32 v112, v77, v77
	s_nop 0
	v_fmac_f32_e32 v115, v78, v78
	v_fmac_f32_e32 v116, v80, v80
	s_nop 1
	v_bfe_u32 v119, v227, 4, 1
	v_sub_u32_e32 v119, 0, v119
	v_lshlrev_b32_e32 v118, 4, v119
	v_lshl_add_u64 v[118:119], v[108:109], 0, v[118:119]
	v_permlane16_swap_b32_e32 v78, v74
	v_permlane16_swap_b32_e32 v79, v75
	v_permlane16_swap_b32_e32 v80, v76
	v_permlane16_swap_b32_e32 v81, v77
	global_store_dwordx4 v[118:119], v[78:81], off
	global_store_dwordx4 v[118:119], v[74:77], off offset:32
	s_nop 1
	v_permlane16_swap_b32_e32 v78, v74
	v_permlane16_swap_b32_e32 v79, v75
	v_permlane16_swap_b32_e32 v80, v76
	v_permlane16_swap_b32_e32 v81, v77
	v_fmac_f32_e32 v111, v74, v74
	v_fmac_f32_e32 v112, v76, v76
	v_cvt_pk_bf16_f32 v78, v78, v79
	v_cvt_pk_bf16_f32 v79, v80, v81
	v_cvt_pk_bf16_f32 v80, v74, v75
	v_cvt_pk_bf16_f32 v81, v76, v77
	s_waitcnt vmcnt(6)
	v_sub_f32_e32 v75, v103, v107
	v_sub_f32_e32 v74, v102, v107
	v_sub_f32_e32 v77, v105, v107
	v_sub_f32_e32 v76, v104, v107
	v_pk_mul_f32 v[76:77], v[0:1], v[76:77] op_sel_hi:[0,1]
	v_pk_mul_f32 v[74:75], v[0:1], v[74:75] op_sel_hi:[0,1]
	s_waitcnt vmcnt(2)
	v_pk_fma_f32 v[74:75], v[94:95], v[74:75], v[98:99]
	v_pk_fma_f32 v[76:77], v[96:97], v[76:77], v[100:101]
	v_pk_fma_f32 v[70:71], v[74:75], s[2:3], v[70:71] op_sel_hi:[1,0,1]
	v_pk_fma_f32 v[72:73], v[76:77], s[2:3], v[72:73] op_sel_hi:[1,0,1]
	v_add_f32_e32 v114, 0, v114
	v_add_f32_e32 v74, v70, v71
	v_add_f32_e32 v75, v72, v73
	v_add_f32_e32 v110, v114, v110
	v_add_f32_e32 v74, v74, v75
	global_store_dwordx4 v106, v[78:81], s[42:43]
	v_mul_f32_e32 v75, v73, v73
	v_add_f32_e32 v115, v115, v116
	v_add_f32_e32 v78, v110, v74
	v_mul_f32_e32 v74, v71, v71
	v_add_f32_e32 v111, v111, v112
	v_fmac_f32_e32 v74, v70, v70
	v_fmac_f32_e32 v75, v72, v72
	v_add_f32_e32 v111, v115, v111
	v_add_f32_e32 v74, v74, v75
	v_add_f32_e32 v79, v111, v74
	v_sub_f32_e32 v75, v83, v107
	v_sub_f32_e32 v74, v82, v107
	v_sub_f32_e32 v77, v85, v107
	v_sub_f32_e32 v76, v84, v107
	v_pk_mul_f32 v[76:77], v[0:1], v[76:77] op_sel_hi:[0,1]
	v_pk_mul_f32 v[74:75], v[0:1], v[74:75] op_sel_hi:[0,1]
	v_pk_fma_f32 v[74:75], v[86:87], v[74:75], v[90:91]
	v_pk_fma_f32 v[76:77], v[88:89], v[76:77], v[92:93]
	v_pk_fma_f32 v[66:67], v[74:75], s[2:3], v[66:67] op_sel_hi:[1,0,1]
	v_pk_fma_f32 v[68:69], v[76:77], s[2:3], v[68:69] op_sel_hi:[1,0,1]
	v_add_f32_e32 v0, v66, v67
	v_add_f32_e32 v74, v68, v69
	v_add_f32_e32 v0, v0, v74
	v_mul_f32_e32 v74, v67, v67
	v_mul_f32_e32 v75, v69, v69
	v_add_f32_e32 v0, v78, v0
	v_fmac_f32_e32 v74, v66, v66
	v_fmac_f32_e32 v75, v68, v68
	s_nop 0
	s_nop 1
	v_bfe_u32 v77, v227, 4, 1
	v_sub_u32_e32 v77, 0, v77
	v_lshlrev_b32_e32 v76, 4, v77
	v_lshl_add_u64 v[76:77], v[108:109], 0, v[76:77]
	v_permlane16_swap_b32_e32 v70, v66
	v_permlane16_swap_b32_e32 v71, v67
	v_permlane16_swap_b32_e32 v72, v68
	v_permlane16_swap_b32_e32 v73, v69
	global_store_dwordx4 v[76:77], v[70:73], off offset:512
	global_store_dwordx4 v[76:77], v[66:69], off offset:544
	s_nop 1
	v_permlane16_swap_b32_e32 v70, v66
	v_permlane16_swap_b32_e32 v71, v67
	v_permlane16_swap_b32_e32 v72, v68
	v_permlane16_swap_b32_e32 v73, v69
	v_add_f32_e32 v74, v74, v75
	v_cvt_pk_bf16_f32 v70, v70, v71
	v_cvt_pk_bf16_f32 v71, v72, v73
	v_cvt_pk_bf16_f32 v72, v66, v67
	v_mov_b32_e32 v66, v0
	v_add_f32_e32 v74, v79, v74
	s_nop 0
	v_permlane16_swap_b32_e32 v0, v66
	v_add_f32_e32 v66, v0, v66
	v_mov_b32_e32 v0, v74
	s_nop 1
	v_permlane16_swap_b32_e32 v74, v0
	v_add_f32_e32 v67, v74, v0
	v_cvt_pk_bf16_f32 v73, v68, v69
	v_mov_b32_e32 v68, v66
	v_mov_b32_e32 v69, v67
	s_nop 0
	v_permlane32_swap_b32_e32 v66, v68
	v_permlane32_swap_b32_e32 v67, v69
	global_store_dwordx4 v106, v[70:73], s[40:41]
	s_and_saveexec_b64 s[26:27], s[44:45]
	s_cbranch_execz .LBB0_1543
	v_pk_add_f32 v[66:67], v[66:67], v[68:69]
	v_lshl_add_u64 v[68:69], s[6:7], 0, v[160:161]
	v_lshl_add_u64 v[68:69], s[52:53], 2, v[68:69]
	global_store_dwordx2 v[68:69], v[66:67], off
; __device__ __forceinline__ float xsum16(float v) { const auto r = __builtin_amdgcn_permlane16_swap(__float_as_uint(v), __float_as_uint(v), false, false); return __uint_as_float(r[0]) + __uint_as_float(r[1]); }
; __device__ __forceinline__ float xsum32(float v) { const auto r = __builtin_amdgcn_permlane32_swap(__float_as_uint(v), __float_as_uint(v), false, false); return __uint_as_float(r[0]) + __uint_as_float(r[1]); }
; __device__ __forceinline__ void row_stats4(const float* st, int rowb, int fq, float (&mu)[4], float (&rs)[4]) {
;     f32x4 a[4], b[4];
; #pragma unroll
;     for (int m = 0; m < 4; ++m) { const f32x4* p = (const f32x4*)(st + (size_t)(rowb + m * 16) * 32 + fq * 8); a[m] = p[0]; b[m] = p[1]; }
; #pragma unroll
;     for (int m = 0; m < 4; ++m) { float s1 = (a[m][0] + a[m][2]) + (b[m][0] + b[m][2]), s2 = (a[m][1] + a[m][3]) + (b[m][1] + b[m][3]);
;         s1 = xsum32(xsum16(s1)); s2 = xsum32(xsum16(s2));
;         const float mm = s1 * (1.0f / 1024.0f); mu[m] = mm; rs[m] = rsqrtf(fmaxf(s2 * (1.0f / 1024.0f) - mm * mm, 0.f) + LN_EPS_); }
;     asm volatile("" ::: "memory");
; }
;     __device__ __forceinline__ void operator()(const f32x4 (&acc)[2][2][4][2], const pg8::Unit& u, int wr, int wc, int fr, int fq) const {
;     ...
;         for (int ai = 0; ai < 2; ++ai) { float mu4[4], rs4[4]; row_stats4(stp, row0 + ai * 128, fq, mu4, rs4);
; #pragma unroll
;             for (int m = 0; m < 4; ++m) { const int row = row0 + ai * 128 + m * 16; const float mu = mu4[m], rs = rs4[m];
;                 f32x4 yv[2][2], gq[2][2], bq_[2][2];
; #pragma unroll
;                 for (int bj = 0; bj < 2; ++bj)
; #pragma unroll
;                     for (int n = 0; n < 2; ++n) { yv[bj][n] = *(const f32x4*)(Yin + (size_t)row * D_ + col0 + bj * 128 + 4 * n); gq[bj][n] = *(const f32x4*)(g + col0 + bj * 128 + 4 * n); bq_[bj][n] = *(const f32x4*)(b + col0 + bj * 128 + 4 * n); }
.LBB0_1543:
	s_or_b64 exec, exec, s[26:27]
	v_add_u32_e32 v118, 0x80, v158
	v_ashrrev_i32_e32 v119, 31, v118
	v_lshlrev_b64 v[110:111], 7, v[118:119]
	v_lshl_add_u64 v[70:71], v[146:147], 0, v[110:111]
	global_load_dwordx4 v[66:69], v[70:71], off
	s_nop 0
	global_load_dwordx4 v[70:73], v[70:71], off offset:16
	v_add_u32_e32 v108, 0x90, v158
	v_ashrrev_i32_e32 v109, 31, v108
	v_lshlrev_b64 v[102:103], 7, v[108:109]
	v_lshl_add_u64 v[78:79], v[146:147], 0, v[102:103]
	global_load_dwordx4 v[74:77], v[78:79], off
	s_nop 0
	global_load_dwordx4 v[78:81], v[78:79], off offset:16
	v_add_u32_e32 v96, 0xa0, v158
	v_ashrrev_i32_e32 v97, 31, v96
	v_lshlrev_b64 v[82:83], 7, v[96:97]
	v_lshl_add_u64 v[86:87], v[146:147], 0, v[82:83]
	global_load_dwordx4 v[82:85], v[86:87], off
	s_nop 0
	global_load_dwordx4 v[86:89], v[86:87], off offset:16
	v_add_u32_e32 v94, 0xb0, v158
	v_ashrrev_i32_e32 v95, 31, v94
	v_lshlrev_b64 v[90:91], 7, v[94:95]
	v_lshl_add_u64 v[98:99], v[146:147], 0, v[90:91]
	global_load_dwordx4 v[90:93], v[98:99], off
	s_nop 0
	global_load_dwordx4 v[98:101], v[98:99], off offset:16
	s_mov_b32 s2, 0x3a800000
	s_mov_b32 s1, 0x800000
	s_load_dwordx16 s[64:79], s[34:35], 0x38
	s_mov_b32 s14, 0x3fd744fd
	s_waitcnt vmcnt(7)
	v_mov_b32_e32 v104, v66
	s_waitcnt vmcnt(6)
	v_mov_b32_e32 v105, v70
	v_mov_b32_e32 v106, v68
	v_mov_b32_e32 v107, v72
	v_pk_add_f32 v[104:105], v[104:105], v[106:107]
	v_mov_b32_e32 v70, v67
	v_pk_add_f32 v[104:105], v[104:105], v[104:105] op_sel:[0,1] op_sel_hi:[1,0]
	v_mov_b32_e32 v72, v69
	v_pk_add_f32 v[66:67], v[70:71], v[72:73]
	v_mov_b32_e32 v0, v104
	v_pk_add_f32 v[66:67], v[66:67], v[66:67] op_sel:[0,1] op_sel_hi:[1,0]
	s_nop 0
	v_permlane16_swap_b32_e32 v104, v0
	v_add_f32_e32 v67, v104, v0
	v_mov_b32_e32 v0, v66
	s_nop 1
	v_permlane16_swap_b32_e32 v66, v0
	v_add_f32_e32 v66, v66, v0
	v_mov_b32_e32 v69, v67
	v_mov_b32_e32 v68, v66
	s_nop 0
	v_permlane32_swap_b32_e32 v67, v69
	v_permlane32_swap_b32_e32 v66, v68
	v_pk_add_f32 v[66:67], v[66:67], v[68:69]
	s_waitcnt vmcnt(5)
	v_mov_b32_e32 v68, v76
	v_pk_mul_f32 v[116:117], v[66:67], s[2:3] op_sel_hi:[1,0]
	s_waitcnt vmcnt(4)
	v_mov_b32_e32 v67, v78
	v_fma_f32 v0, -v117, v117, v116
	v_max_f32_e32 v0, 0, v0
	v_add_f32_e32 v0, 0x3727c5ac, v0
	v_cmp_gt_f32_e32 vcc, s1, v0
	v_mul_f32_e32 v66, 0x4b800000, v0
	v_mov_b32_e32 v69, v80
	v_cndmask_b32_e32 v0, v0, v66, vcc
	v_rsq_f32_e32 v0, v0
	v_mov_b32_e32 v78, v75
	v_mov_b32_e32 v80, v77
	v_readlane_b32 s2, v253, 59
	v_mul_f32_e32 v66, 0x45800000, v0
	v_cndmask_b32_e32 v116, v0, v66, vcc
	v_mov_b32_e32 v66, v74
	v_pk_add_f32 v[66:67], v[66:67], v[68:69]
	v_pk_add_f32 v[68:69], v[78:79], v[80:81]
	v_pk_add_f32 v[66:67], v[66:67], v[66:67] op_sel:[0,1] op_sel_hi:[1,0]
	v_pk_add_f32 v[68:69], v[68:69], v[68:69] op_sel:[0,1] op_sel_hi:[1,0]
	v_mov_b32_e32 v0, v66
	s_nop 1
	v_permlane16_swap_b32_e32 v66, v0
	v_add_f32_e32 v113, v66, v0
	v_mov_b32_e32 v0, v68
	s_nop 1
	v_permlane16_swap_b32_e32 v68, v0
	v_add_f32_e32 v112, v68, v0
	s_waitcnt vmcnt(3)
	v_mov_b32_e32 v66, v82
	s_waitcnt vmcnt(2)
	v_mov_b32_e32 v67, v86
	v_mov_b32_e32 v68, v84
	v_mov_b32_e32 v69, v88
	v_pk_add_f32 v[66:67], v[66:67], v[68:69]
	v_mov_b32_e32 v86, v83
	v_pk_add_f32 v[66:67], v[66:67], v[66:67] op_sel:[0,1] op_sel_hi:[1,0]
	v_mov_b32_e32 v88, v85
	v_pk_add_f32 v[68:69], v[86:87], v[88:89]
	v_mov_b32_e32 v0, v66
	v_pk_add_f32 v[68:69], v[68:69], v[68:69] op_sel:[0,1] op_sel_hi:[1,0]
	s_nop 0
	v_permlane16_swap_b32_e32 v66, v0
	v_add_f32_e32 v105, v66, v0
	v_mov_b32_e32 v0, v68
	s_nop 1
	v_permlane16_swap_b32_e32 v68, v0
	v_add_f32_e32 v104, v68, v0
	s_waitcnt vmcnt(1)
	v_mov_b32_e32 v66, v90
	s_waitcnt vmcnt(0)
	v_mov_b32_e32 v67, v98
	v_mov_b32_e32 v68, v92
	v_mov_b32_e32 v69, v100
	v_pk_add_f32 v[66:67], v[66:67], v[68:69]
	v_mov_b32_e32 v98, v91
	v_pk_add_f32 v[66:67], v[66:67], v[66:67] op_sel:[0,1] op_sel_hi:[1,0]
	v_mov_b32_e32 v100, v93
	v_mov_b32_e32 v0, v66
	s_nop 1
	v_permlane16_swap_b32_e32 v66, v0
	v_pk_add_f32 v[68:69], v[98:99], v[100:101]
	v_add_f32_e32 v99, v66, v0
	v_ashrrev_i32_e32 v66, 8, v118
	v_ashrrev_i32_e32 v67, 31, v66
	v_pk_add_f32 v[68:69], v[68:69], v[68:69] op_sel:[0,1] op_sel_hi:[1,0]
	v_lshlrev_b64 v[120:121], 19, v[66:67]
	v_lshlrev_b64 v[66:67], 12, v[118:119]
	v_mov_b32_e32 v0, v68
	s_waitcnt lgkmcnt(0)
	v_lshl_add_u64 v[66:67], s[78:79], 0, v[66:67]
	v_permlane16_swap_b32_e32 v68, v0
	v_lshl_add_u64 v[122:123], v[152:153], 2, v[66:67]
	v_add_f32_e32 v98, v68, v0
	global_load_dwordx4 v[74:77], v[122:123], off offset:16
	global_load_dwordx4 v[86:89], v[122:123], off
	global_load_dwordx4 v[66:69], v[156:157], off offset:16
	global_load_dwordx4 v[78:81], v[156:157], off
	global_load_dwordx4 v[70:73], v[154:155], off offset:16
	global_load_dwordx4 v[82:85], v[154:155], off
	global_load_dwordx4 v[90:93], v[122:123], off offset:528
	global_load_dwordx4 v[124:127], v[122:123], off offset:512
	global_load_dwordx4 v[128:131], v[156:157], off offset:528
	global_load_dwordx4 v[132:135], v[156:157], off offset:512
	global_load_dwordx4 v[158:161], v[154:155], off offset:528
	global_load_dwordx4 v[162:165], v[154:155], off offset:512
	v_lshlrev_b32_e32 v0, 6, v118
	s_movk_i32 s1, 0x33c0
	v_readlane_b32 s3, v253, 60
	v_and_or_b32 v0, v0, s1, v196
	v_lshlrev_b32_e32 v0, 1, v0
	v_mov_b32_e32 v115, v113
	v_mov_b32_e32 v114, v112
	v_mov_b32_e32 v107, v105
	v_mov_b32_e32 v106, v104
	v_mov_b32_e32 v101, v99
	v_mov_b32_e32 v100, v98
	v_permlane32_swap_b32_e32 v113, v115
	v_permlane32_swap_b32_e32 v112, v114
	v_permlane32_swap_b32_e32 v105, v107
	v_permlane32_swap_b32_e32 v104, v106
	v_permlane32_swap_b32_e32 v99, v101
	v_permlane32_swap_b32_e32 v98, v100
	s_waitcnt vmcnt(11)
; __device__ __forceinline__ float xsum16(float v) { const auto r = __builtin_amdgcn_permlane16_swap(__float_as_uint(v), __float_as_uint(v), false, false); return __uint_as_float(r[0]) + __uint_as_float(r[1]); }
; __device__ __forceinline__ float xsum32(float v) { const auto r = __builtin_amdgcn_permlane32_swap(__float_as_uint(v), __float_as_uint(v), false, false); return __uint_as_float(r[0]) + __uint_as_float(r[1]); }
; __device__ __forceinline__ size_t blk_off(int r, int c, int K) { return (size_t)(r >> 8) * 256 * K + (size_t)(c >> 6) * (256 * 64) + (size_t)((r & 255) * 64 + (c & 63)); }
; __device__ __forceinline__ u32x4 pack8(const f32x4 a, const f32x4 b) { u32x4 w; w.x = cvt_pk_bf16(a[0], a[1]); w.y = cvt_pk_bf16(a[2], a[3]); w.z = cvt_pk_bf16(b[0], b[1]); w.w = cvt_pk_bf16(b[2], b[3]); return w; }
;     __device__ __forceinline__ void operator()(const f32x4 (&acc)[2][2][4][2], const pg8::Unit& u, int wr, int wc, int fr, int fq) const {
;     ...
;             for (int m = 0; m < 4; ++m) { const int row = row0 + ai * 128 + m * 16; const float mu = mu4[m], rs = rs4[m];
;                 f32x4 yv[2][2], gq[2][2], bq_[2][2];
; #pragma unroll
;                 for (int bj = 0; bj < 2; ++bj)
; #pragma unroll
;                     for (int n = 0; n < 2; ++n) { yv[bj][n] = *(const f32x4*)(Yin + (size_t)row * D_ + col0 + bj * 128 + 4 * n); gq[bj][n] = *(const f32x4*)(g + col0 + bj * 128 + 4 * n); bq_[bj][n] = *(const f32x4*)(b + col0 + bj * 128 + 4 * n); }
;                 asm volatile("" ::: "memory");
;                 float s1 = 0.f, s2 = 0.f;
; #pragma unroll
;                 for (int bj = 0; bj < 2; ++bj) { float* yp = Y + (size_t)row * D_ + col0 + bj * 128; f32x4 v[2];
; #pragma unroll
;                     for (int n = 0; n < 2; ++n) { v[n] = (((yv[bj][n] - mu) * rs) * gq[bj][n] + bq_[bj][n]) * ALPHA_ + acc[ai][bj][m][n] * sc;
;                         *(f32x4*)(yp + 4 * n) = v[n]; s1 += (v[n][0] + v[n][1]) + (v[n][2] + v[n][3]); s2 += (v[n][0] * v[n][0] + v[n][1] * v[n][1]) + (v[n][2] * v[n][2] + v[n][3] * v[n][3]); }
;                     *(u32x4*)(Yb + blk_off(row, col0 + bj * 128, D_)) = pack8(v[0], v[1]); }
;                 s1 = xsum32(xsum16(s1)); s2 = xsum32(xsum16(s2));
;                 if (fq == 0) *(f32x2*)(stn + (size_t)row * 32 + (u.pn * 4 + wc) * 2) = (f32x2){s1, s2}; asm volatile("" ::: "memory"); } }
	v_sub_f32_e32 v75, v75, v117
	s_waitcnt vmcnt(10)
	v_sub_f32_e32 v87, v87, v117
	v_sub_f32_e32 v86, v86, v117
	v_sub_f32_e32 v89, v89, v117
	v_sub_f32_e32 v88, v88, v117
	v_sub_f32_e32 v74, v74, v117
	v_sub_f32_e32 v77, v77, v117
	v_sub_f32_e32 v76, v76, v117
	v_pk_mul_f32 v[88:89], v[116:117], v[88:89] op_sel_hi:[0,1]
	v_pk_mul_f32 v[86:87], v[116:117], v[86:87] op_sel_hi:[0,1]
	v_pk_mul_f32 v[76:77], v[116:117], v[76:77] op_sel_hi:[0,1]
	v_pk_mul_f32 v[74:75], v[116:117], v[74:75] op_sel_hi:[0,1]
	s_waitcnt vmcnt(6)
	v_pk_fma_f32 v[78:79], v[78:79], v[86:87], v[82:83]
	v_pk_fma_f32 v[80:81], v[80:81], v[88:89], v[84:85]
	v_pk_fma_f32 v[66:67], v[66:67], v[74:75], v[70:71]
	v_pk_fma_f32 v[68:69], v[68:69], v[76:77], v[72:73]
	v_pk_fma_f32 v[64:65], v[80:81], s[14:15], v[64:65] op_sel_hi:[1,0,1]
	v_pk_fma_f32 v[62:63], v[78:79], s[14:15], v[62:63] op_sel_hi:[1,0,1]
	v_pk_fma_f32 v[60:61], v[68:69], s[14:15], v[60:61] op_sel_hi:[1,0,1]
	v_pk_fma_f32 v[58:59], v[66:67], s[14:15], v[58:59] op_sel_hi:[1,0,1]
	v_add_f32_e32 v78, v62, v63
	v_add_f32_e32 v79, v64, v65
	v_add_f32_e32 v66, v58, v59
	v_add_f32_e32 v67, v60, v61
	v_add_f32_e32 v78, v78, v79
	v_mul_f32_e32 v79, v63, v63
	v_mul_f32_e32 v80, v65, v65
	v_add_f32_e32 v66, v66, v67
	v_mul_f32_e32 v67, v59, v59
	s_nop 0
	v_fmac_f32_e32 v79, v62, v62
	v_fmac_f32_e32 v80, v64, v64
	s_nop 1
	v_bfe_u32 v69, v227, 4, 1
	v_sub_u32_e32 v69, 0, v69
	v_lshlrev_b32_e32 v68, 4, v69
	v_lshl_add_u64 v[68:69], v[122:123], 0, v[68:69]
	v_permlane16_swap_b32_e32 v62, v58
	v_permlane16_swap_b32_e32 v63, v59
	v_permlane16_swap_b32_e32 v64, v60
	v_permlane16_swap_b32_e32 v65, v61
	global_store_dwordx4 v[68:69], v[62:65], off
	global_store_dwordx4 v[68:69], v[58:61], off offset:32
	s_nop 1
	v_permlane16_swap_b32_e32 v62, v58
	v_permlane16_swap_b32_e32 v63, v59
	v_permlane16_swap_b32_e32 v64, v60
	v_permlane16_swap_b32_e32 v65, v61
	v_fmac_f32_e32 v67, v58, v58
	v_cvt_pk_bf16_f32 v62, v62, v63
	v_cvt_pk_bf16_f32 v63, v64, v65
	v_cvt_pk_bf16_f32 v64, v58, v59
	v_lshl_add_u64 v[58:59], s[2:3], 0, v[120:121]
	v_mul_f32_e32 v68, v61, v61
	v_lshl_add_u64 v[76:77], v[58:59], 0, s[24:25]
	v_fmac_f32_e32 v68, v60, v60
	v_cvt_pk_bf16_f32 v65, v60, v61
	v_lshl_add_u64 v[60:61], v[76:77], 0, v[0:1]
	global_store_dwordx4 v[60:61], v[62:65], off
	s_waitcnt vmcnt(7)
	v_sub_f32_e32 v61, v125, v117
	v_sub_f32_e32 v60, v124, v117
	v_sub_f32_e32 v63, v127, v117
	v_sub_f32_e32 v62, v126, v117
	v_pk_mul_f32 v[62:63], v[116:117], v[62:63] op_sel_hi:[0,1]
	v_pk_mul_f32 v[60:61], v[116:117], v[60:61] op_sel_hi:[0,1]
	s_waitcnt vmcnt(3)
	v_pk_fma_f32 v[60:61], v[132:133], v[60:61], v[162:163]
	v_pk_fma_f32 v[62:63], v[134:135], v[62:63], v[164:165]
	v_pk_fma_f32 v[54:55], v[60:61], s[14:15], v[54:55] op_sel_hi:[1,0,1]
	v_pk_fma_f32 v[56:57], v[62:63], s[14:15], v[56:57] op_sel_hi:[1,0,1]
	v_add_f32_e32 v78, 0, v78
	v_add_f32_e32 v60, v54, v55
	v_add_f32_e32 v61, v56, v57
	v_add_f32_e32 v66, v78, v66
	v_add_f32_e32 v60, v60, v61
	v_add_f32_e32 v64, v66, v60
	v_mul_f32_e32 v60, v55, v55
	v_mul_f32_e32 v61, v57, v57
	v_add_f32_e32 v79, v79, v80
	v_add_f32_e32 v67, v67, v68
	v_fmac_f32_e32 v60, v54, v54
	v_fmac_f32_e32 v61, v56, v56
	v_add_f32_e32 v67, v79, v67
	v_add_f32_e32 v60, v60, v61
	v_add_f32_e32 v65, v67, v60
	v_sub_f32_e32 v61, v91, v117
	v_sub_f32_e32 v60, v90, v117
	v_sub_f32_e32 v63, v93, v117
	v_sub_f32_e32 v62, v92, v117
	v_pk_mul_f32 v[62:63], v[116:117], v[62:63] op_sel_hi:[0,1]
	v_pk_mul_f32 v[60:61], v[116:117], v[60:61] op_sel_hi:[0,1]
	v_pk_fma_f32 v[60:61], v[128:129], v[60:61], v[158:159]
	v_pk_fma_f32 v[62:63], v[130:131], v[62:63], v[160:161]
	v_pk_fma_f32 v[50:51], v[60:61], s[14:15], v[50:51] op_sel_hi:[1,0,1]
	v_pk_fma_f32 v[52:53], v[62:63], s[14:15], v[52:53] op_sel_hi:[1,0,1]
	v_add_f32_e32 v60, v50, v51
	v_add_f32_e32 v61, v52, v53
	v_add_f32_e32 v60, v60, v61
	v_mul_f32_e32 v61, v51, v51
	v_mul_f32_e32 v62, v53, v53
	v_add_f32_e32 v60, v64, v60
	v_fmac_f32_e32 v61, v50, v50
	v_fmac_f32_e32 v62, v52, v52
	v_lshl_add_u64 v[74:75], v[58:59], 0, s[28:29]
	s_nop 0
	s_nop 1
	v_bfe_u32 v67, v227, 4, 1
	v_sub_u32_e32 v67, 0, v67
	v_lshlrev_b32_e32 v66, 4, v67
	v_lshl_add_u64 v[66:67], v[122:123], 0, v[66:67]
	v_permlane16_swap_b32_e32 v54, v50
	v_permlane16_swap_b32_e32 v55, v51
	v_permlane16_swap_b32_e32 v56, v52
	v_permlane16_swap_b32_e32 v57, v53
	global_store_dwordx4 v[66:67], v[54:57], off offset:512
	global_store_dwordx4 v[66:67], v[50:53], off offset:544
	s_nop 1
	v_permlane16_swap_b32_e32 v54, v50
	v_permlane16_swap_b32_e32 v55, v51
	v_permlane16_swap_b32_e32 v56, v52
	v_permlane16_swap_b32_e32 v57, v53
	v_add_f32_e32 v61, v61, v62
	v_cvt_pk_bf16_f32 v54, v54, v55
	v_cvt_pk_bf16_f32 v55, v56, v57
	v_cvt_pk_bf16_f32 v56, v50, v51
	v_lshl_add_u64 v[50:51], v[74:75], 0, v[0:1]
	v_mov_b32_e32 v0, v60
	v_add_f32_e32 v61, v65, v61
	v_cvt_pk_bf16_f32 v57, v52, v53
	v_permlane16_swap_b32_e32 v60, v0
	global_store_dwordx4 v[50:51], v[54:57], off
	v_add_f32_e32 v50, v60, v0
	v_mov_b32_e32 v0, v61
	s_nop 1
	v_permlane16_swap_b32_e32 v61, v0
	v_add_f32_e32 v51, v61, v0
	v_mov_b32_e32 v52, v50
	v_mov_b32_e32 v53, v51
	s_nop 0
	v_permlane32_swap_b32_e32 v50, v52
	v_permlane32_swap_b32_e32 v51, v53
	s_and_saveexec_b64 s[24:25], s[44:45]
	s_cbranch_execz .LBB0_1545
	v_pk_add_f32 v[50:51], v[50:51], v[52:53]
	v_lshl_add_u64 v[52:53], s[6:7], 0, v[110:111]
	v_lshl_add_u64 v[52:53], s[52:53], 2, v[52:53]
	global_store_dwordx2 v[52:53], v[50:51], off
; __device__ __forceinline__ float xsum16(float v) { const auto r = __builtin_amdgcn_permlane16_swap(__float_as_uint(v), __float_as_uint(v), false, false); return __uint_as_float(r[0]) + __uint_as_float(r[1]); }
; __device__ __forceinline__ float xsum32(float v) { const auto r = __builtin_amdgcn_permlane32_swap(__float_as_uint(v), __float_as_uint(v), false, false); return __uint_as_float(r[0]) + __uint_as_float(r[1]); }
; __device__ __forceinline__ size_t blk_off(int r, int c, int K) { return (size_t)(r >> 8) * 256 * K + (size_t)(c >> 6) * (256 * 64) + (size_t)((r & 255) * 64 + (c & 63)); }
; __device__ __forceinline__ u32x4 pack8(const f32x4 a, const f32x4 b) { u32x4 w; w.x = cvt_pk_bf16(a[0], a[1]); w.y = cvt_pk_bf16(a[2], a[3]); w.z = cvt_pk_bf16(b[0], b[1]); w.w = cvt_pk_bf16(b[2], b[3]); return w; }
;     __device__ __forceinline__ void operator()(const f32x4 (&acc)[2][2][4][2], const pg8::Unit& u, int wr, int wc, int fr, int fq) const {
;     ...
;             for (int m = 0; m < 4; ++m) { const int row = row0 + ai * 128 + m * 16; const float mu = mu4[m], rs = rs4[m];
;                 f32x4 yv[2][2], gq[2][2], bq_[2][2];
; #pragma unroll
;                 for (int bj = 0; bj < 2; ++bj)
; #pragma unroll
;                     for (int n = 0; n < 2; ++n) { yv[bj][n] = *(const f32x4*)(Yin + (size_t)row * D_ + col0 + bj * 128 + 4 * n); gq[bj][n] = *(const f32x4*)(g + col0 + bj * 128 + 4 * n); bq_[bj][n] = *(const f32x4*)(b + col0 + bj * 128 + 4 * n); }
;                 asm volatile("" ::: "memory");
;                 float s1 = 0.f, s2 = 0.f;
; #pragma unroll
;                 for (int bj = 0; bj < 2; ++bj) { float* yp = Y + (size_t)row * D_ + col0 + bj * 128; f32x4 v[2];
; #pragma unroll
;                     for (int n = 0; n < 2; ++n) { v[n] = (((yv[bj][n] - mu) * rs) * gq[bj][n] + bq_[bj][n]) * ALPHA_ + acc[ai][bj][m][n] * sc;
;                         *(f32x4*)(yp + 4 * n) = v[n]; s1 += (v[n][0] + v[n][1]) + (v[n][2] + v[n][3]); s2 += (v[n][0] * v[n][0] + v[n][1] * v[n][1]) + (v[n][2] * v[n][2] + v[n][3] * v[n][3]); }
;                     *(u32x4*)(Yb + blk_off(row, col0 + bj * 128, D_)) = pack8(v[0], v[1]); }
;                 s1 = xsum32(xsum16(s1)); s2 = xsum32(xsum16(s2));
;                 if (fq == 0) *(f32x2*)(stn + (size_t)row * 32 + (u.pn * 4 + wc) * 2) = (f32x2){s1, s2}; asm volatile("" ::: "memory"); } }
.LBB0_1545:
	s_or_b64 exec, exec, s[24:25]
	v_pk_add_f32 v[50:51], v[112:113], v[114:115]
	s_mov_b32 s2, 0x3a800000
	v_pk_mul_f32 v[78:79], v[50:51], s[2:3] op_sel_hi:[1,0]
	s_mov_b32 s1, 0x800000
	v_fma_f32 v0, -v79, v79, v78
	v_max_f32_e32 v0, 0, v0
	v_add_f32_e32 v0, 0x3727c5ac, v0
	v_cmp_gt_f32_e32 vcc, s1, v0
	v_mul_f32_e32 v50, 0x4b800000, v0
	s_load_dwordx16 s[64:79], s[34:35], 0x38
	v_cndmask_b32_e32 v0, v0, v50, vcc
	v_rsq_f32_e32 v0, v0
	s_mov_b32 s2, 0x3fd744fd
	s_movk_i32 s1, 0x37c0
	v_mul_f32_e32 v50, 0x45800000, v0
	v_cndmask_b32_e32 v78, v0, v50, vcc
	v_lshlrev_b64 v[50:51], 12, v[108:109]
	s_waitcnt lgkmcnt(0)
	v_lshl_add_u64 v[50:51], s[78:79], 0, v[50:51]
	v_lshl_add_u64 v[80:81], v[152:153], 2, v[50:51]
	global_load_dwordx4 v[82:85], v[80:81], off offset:16
	global_load_dwordx4 v[86:89], v[80:81], off
	global_load_dwordx4 v[90:93], v[156:157], off offset:16
	global_load_dwordx4 v[110:113], v[156:157], off
	global_load_dwordx4 v[114:117], v[154:155], off offset:16
	global_load_dwordx4 v[118:121], v[154:155], off
	global_load_dwordx4 v[50:53], v[80:81], off offset:528
	global_load_dwordx4 v[70:73], v[80:81], off offset:512
	global_load_dwordx4 v[54:57], v[156:157], off offset:528
	global_load_dwordx4 v[62:65], v[156:157], off offset:512
	global_load_dwordx4 v[58:61], v[154:155], off offset:528
	global_load_dwordx4 v[66:69], v[154:155], off offset:512
	v_lshlrev_b32_e32 v0, 6, v108
	v_and_or_b32 v0, v0, s1, v196
	v_lshlrev_b32_e32 v0, 1, v0
	s_waitcnt vmcnt(10)
	v_sub_f32_e32 v87, v87, v79
	v_sub_f32_e32 v86, v86, v79
	v_sub_f32_e32 v89, v89, v79
	v_sub_f32_e32 v88, v88, v79
	v_pk_mul_f32 v[88:89], v[78:79], v[88:89] op_sel_hi:[0,1]
	v_pk_mul_f32 v[86:87], v[78:79], v[86:87] op_sel_hi:[0,1]
	s_waitcnt vmcnt(6)
	v_pk_fma_f32 v[86:87], v[110:111], v[86:87], v[118:119]
	v_pk_fma_f32 v[88:89], v[112:113], v[88:89], v[120:121]
	v_pk_fma_f32 v[86:87], v[86:87], s[2:3], v[46:47] op_sel_hi:[1,0,1]
	v_pk_fma_f32 v[88:89], v[88:89], s[2:3], v[48:49] op_sel_hi:[1,0,1]
	v_add_f32_e32 v46, v86, v87
	v_add_f32_e32 v47, v88, v89
	v_add_f32_e32 v46, v46, v47
	v_add_f32_e32 v108, 0, v46
	v_mul_f32_e32 v46, v87, v87
	v_mul_f32_e32 v47, v89, v89
	v_fmac_f32_e32 v46, v86, v86
	v_fmac_f32_e32 v47, v88, v88
	v_add_f32_e32 v109, v46, v47
	v_sub_f32_e32 v47, v83, v79
	v_sub_f32_e32 v46, v82, v79
	v_sub_f32_e32 v49, v85, v79
	v_sub_f32_e32 v48, v84, v79
	v_pk_mul_f32 v[48:49], v[78:79], v[48:49] op_sel_hi:[0,1]
	v_pk_mul_f32 v[46:47], v[78:79], v[46:47] op_sel_hi:[0,1]
	v_pk_fma_f32 v[46:47], v[90:91], v[46:47], v[114:115]
	v_pk_fma_f32 v[48:49], v[92:93], v[48:49], v[116:117]
	v_pk_fma_f32 v[82:83], v[46:47], s[2:3], v[42:43] op_sel_hi:[1,0,1]
	v_pk_fma_f32 v[84:85], v[48:49], s[2:3], v[44:45] op_sel_hi:[1,0,1]
	v_add_f32_e32 v42, v82, v83
	v_add_f32_e32 v43, v84, v85
	v_add_f32_e32 v42, v42, v43
	v_add_f32_e32 v47, v108, v42
	v_mul_f32_e32 v42, v83, v83
	v_mul_f32_e32 v43, v85, v85
	v_fmac_f32_e32 v42, v82, v82
	v_fmac_f32_e32 v43, v84, v84
	v_add_f32_e32 v42, v42, v43
	v_add_f32_e32 v46, v109, v42
	v_cvt_pk_bf16_f32 v42, v86, v87
	v_cvt_pk_bf16_f32 v43, v88, v89
	v_cvt_pk_bf16_f32 v44, v82, v83
	v_cvt_pk_bf16_f32 v45, v84, v85
	v_lshl_add_u64 v[48:49], v[76:77], 0, v[0:1]
	s_nop 0
	s_nop 1
	v_bfe_u32 v91, v227, 4, 1
	v_sub_u32_e32 v91, 0, v91
	v_lshlrev_b32_e32 v90, 4, v91
	v_lshl_add_u64 v[90:91], v[80:81], 0, v[90:91]
	v_permlane16_swap_b32_e32 v86, v82
	v_permlane16_swap_b32_e32 v87, v83
	v_permlane16_swap_b32_e32 v88, v84
	v_permlane16_swap_b32_e32 v89, v85
	global_store_dwordx4 v[90:91], v[86:89], off
	global_store_dwordx4 v[90:91], v[82:85], off offset:32
	s_nop 1
	v_permlane16_swap_b32_e32 v86, v82
	v_permlane16_swap_b32_e32 v87, v83
	v_permlane16_swap_b32_e32 v88, v84
	v_permlane16_swap_b32_e32 v89, v85
	global_store_dwordx4 v[48:49], v[42:45], off
	s_waitcnt vmcnt(7)
	s_nop 0
	v_sub_f32_e32 v43, v71, v79
	v_sub_f32_e32 v42, v70, v79
	v_sub_f32_e32 v45, v73, v79
	v_sub_f32_e32 v44, v72, v79
	v_pk_mul_f32 v[44:45], v[78:79], v[44:45] op_sel_hi:[0,1]
	v_pk_mul_f32 v[42:43], v[78:79], v[42:43] op_sel_hi:[0,1]
	s_waitcnt vmcnt(3)
	v_pk_fma_f32 v[42:43], v[62:63], v[42:43], v[66:67]
	v_pk_fma_f32 v[44:45], v[64:65], v[44:45], v[68:69]
	v_pk_fma_f32 v[38:39], v[42:43], s[2:3], v[38:39] op_sel_hi:[1,0,1]
	v_pk_fma_f32 v[40:41], v[44:45], s[2:3], v[40:41] op_sel_hi:[1,0,1]
	v_add_f32_e32 v42, v38, v39
	v_add_f32_e32 v43, v40, v41
	v_add_f32_e32 v42, v42, v43
	v_add_f32_e32 v47, v47, v42
	v_mul_f32_e32 v42, v39, v39
	v_mul_f32_e32 v43, v41, v41
	v_fmac_f32_e32 v42, v38, v38
	v_fmac_f32_e32 v43, v40, v40
	v_add_f32_e32 v42, v42, v43
	v_add_f32_e32 v46, v46, v42
	v_sub_f32_e32 v43, v51, v79
	v_sub_f32_e32 v42, v50, v79
	v_sub_f32_e32 v45, v53, v79
	v_sub_f32_e32 v44, v52, v79
	v_pk_mul_f32 v[44:45], v[78:79], v[44:45] op_sel_hi:[0,1]
	v_pk_mul_f32 v[42:43], v[78:79], v[42:43] op_sel_hi:[0,1]
	v_pk_fma_f32 v[42:43], v[54:55], v[42:43], v[58:59]
	v_pk_fma_f32 v[44:45], v[56:57], v[44:45], v[60:61]
	v_pk_fma_f32 v[34:35], v[42:43], s[2:3], v[34:35] op_sel_hi:[1,0,1]
	v_pk_fma_f32 v[36:37], v[44:45], s[2:3], v[36:37] op_sel_hi:[1,0,1]
	v_add_f32_e32 v42, v34, v35
	v_add_f32_e32 v43, v36, v37
	v_add_f32_e32 v42, v42, v43
	v_mul_f32_e32 v43, v35, v35
	v_mul_f32_e32 v44, v37, v37
	v_add_f32_e32 v42, v47, v42
	v_fmac_f32_e32 v43, v34, v34
	v_fmac_f32_e32 v44, v36, v36
	s_nop 0
	s_nop 1
	v_bfe_u32 v49, v227, 4, 1
	v_sub_u32_e32 v49, 0, v49
	v_lshlrev_b32_e32 v48, 4, v49
	v_lshl_add_u64 v[48:49], v[80:81], 0, v[48:49]
	v_permlane16_swap_b32_e32 v38, v34
	v_permlane16_swap_b32_e32 v39, v35
	v_permlane16_swap_b32_e32 v40, v36
	v_permlane16_swap_b32_e32 v41, v37
	global_store_dwordx4 v[48:49], v[38:41], off offset:512
	global_store_dwordx4 v[48:49], v[34:37], off offset:544
	s_nop 1
	v_permlane16_swap_b32_e32 v38, v34
	v_permlane16_swap_b32_e32 v39, v35
	v_permlane16_swap_b32_e32 v40, v36
	v_permlane16_swap_b32_e32 v41, v37
	v_add_f32_e32 v43, v43, v44
	v_cvt_pk_bf16_f32 v38, v38, v39
	v_cvt_pk_bf16_f32 v39, v40, v41
	v_cvt_pk_bf16_f32 v40, v34, v35
	v_lshl_add_u64 v[34:35], v[74:75], 0, v[0:1]
	v_mov_b32_e32 v0, v42
	v_add_f32_e32 v43, v46, v43
	v_cvt_pk_bf16_f32 v41, v36, v37
	v_permlane16_swap_b32_e32 v42, v0
	global_store_dwordx4 v[34:35], v[38:41], off
	v_add_f32_e32 v34, v42, v0
	v_mov_b32_e32 v0, v43
	s_nop 1
	v_permlane16_swap_b32_e32 v43, v0
	v_add_f32_e32 v35, v43, v0
	v_mov_b32_e32 v36, v34
	v_mov_b32_e32 v37, v35
	s_nop 0
	v_permlane32_swap_b32_e32 v34, v36
	v_permlane32_swap_b32_e32 v35, v37
	s_and_saveexec_b64 s[24:25], s[44:45]
	s_cbranch_execz .LBB0_1547
	v_pk_add_f32 v[34:35], v[34:35], v[36:37]
	v_lshl_add_u64 v[36:37], s[6:7], 0, v[102:103]
	v_lshl_add_u64 v[36:37], s[52:53], 2, v[36:37]
	global_store_dwordx2 v[36:37], v[34:35], off
; __device__ __forceinline__ float xsum16(float v) { const auto r = __builtin_amdgcn_permlane16_swap(__float_as_uint(v), __float_as_uint(v), false, false); return __uint_as_float(r[0]) + __uint_as_float(r[1]); }
; __device__ __forceinline__ float xsum32(float v) { const auto r = __builtin_amdgcn_permlane32_swap(__float_as_uint(v), __float_as_uint(v), false, false); return __uint_as_float(r[0]) + __uint_as_float(r[1]); }
; __device__ __forceinline__ size_t blk_off(int r, int c, int K) { return (size_t)(r >> 8) * 256 * K + (size_t)(c >> 6) * (256 * 64) + (size_t)((r & 255) * 64 + (c & 63)); }
; __device__ __forceinline__ u32x4 pack8(const f32x4 a, const f32x4 b) { u32x4 w; w.x = cvt_pk_bf16(a[0], a[1]); w.y = cvt_pk_bf16(a[2], a[3]); w.z = cvt_pk_bf16(b[0], b[1]); w.w = cvt_pk_bf16(b[2], b[3]); return w; }
;     __device__ __forceinline__ void operator()(const f32x4 (&acc)[2][2][4][2], const pg8::Unit& u, int wr, int wc, int fr, int fq) const {
;     ...
;             for (int m = 0; m < 4; ++m) { const int row = row0 + ai * 128 + m * 16; const float mu = mu4[m], rs = rs4[m];
;                 f32x4 yv[2][2], gq[2][2], bq_[2][2];
; #pragma unroll
;                 for (int bj = 0; bj < 2; ++bj)
; #pragma unroll
;                     for (int n = 0; n < 2; ++n) { yv[bj][n] = *(const f32x4*)(Yin + (size_t)row * D_ + col0 + bj * 128 + 4 * n); gq[bj][n] = *(const f32x4*)(g + col0 + bj * 128 + 4 * n); bq_[bj][n] = *(const f32x4*)(b + col0 + bj * 128 + 4 * n); }
;                 asm volatile("" ::: "memory");
;                 float s1 = 0.f, s2 = 0.f;
; #pragma unroll
;                 for (int bj = 0; bj < 2; ++bj) { float* yp = Y + (size_t)row * D_ + col0 + bj * 128; f32x4 v[2];
; #pragma unroll
;                     for (int n = 0; n < 2; ++n) { v[n] = (((yv[bj][n] - mu) * rs) * gq[bj][n] + bq_[bj][n]) * ALPHA_ + acc[ai][bj][m][n] * sc;
;                         *(f32x4*)(yp + 4 * n) = v[n]; s1 += (v[n][0] + v[n][1]) + (v[n][2] + v[n][3]); s2 += (v[n][0] * v[n][0] + v[n][1] * v[n][1]) + (v[n][2] * v[n][2] + v[n][3] * v[n][3]); }
;                     *(u32x4*)(Yb + blk_off(row, col0 + bj * 128, D_)) = pack8(v[0], v[1]); }
;                 s1 = xsum32(xsum16(s1)); s2 = xsum32(xsum16(s2));
;                 if (fq == 0) *(f32x2*)(stn + (size_t)row * 32 + (u.pn * 4 + wc) * 2) = (f32x2){s1, s2}; asm volatile("" ::: "memory"); } }
.LBB0_1547:
	s_or_b64 exec, exec, s[24:25]
	v_pk_add_f32 v[34:35], v[104:105], v[106:107]
	s_mov_b32 s2, 0x3a800000
	v_pk_mul_f32 v[58:59], v[34:35], s[2:3] op_sel_hi:[1,0]
	s_mov_b32 s1, 0x800000
	v_fma_f32 v0, -v59, v59, v58
	v_max_f32_e32 v0, 0, v0
	v_add_f32_e32 v0, 0x3727c5ac, v0
	v_cmp_gt_f32_e32 vcc, s1, v0
	v_mul_f32_e32 v34, 0x4b800000, v0
	s_load_dwordx16 s[64:79], s[34:35], 0x38
	v_cndmask_b32_e32 v0, v0, v34, vcc
	v_rsq_f32_e32 v0, v0
	s_mov_b32 s2, 0x3fd744fd
	s_movk_i32 s1, 0x3bc0
	v_mul_f32_e32 v34, 0x45800000, v0
	v_cndmask_b32_e32 v58, v0, v34, vcc
	v_lshlrev_b64 v[34:35], 12, v[96:97]
	s_waitcnt lgkmcnt(0)
	v_lshl_add_u64 v[34:35], s[78:79], 0, v[34:35]
	v_lshl_add_u64 v[60:61], v[152:153], 2, v[34:35]
	global_load_dwordx4 v[62:65], v[60:61], off offset:16
	global_load_dwordx4 v[66:69], v[60:61], off
	global_load_dwordx4 v[70:73], v[156:157], off offset:16
	global_load_dwordx4 v[78:81], v[156:157], off
	global_load_dwordx4 v[82:85], v[154:155], off offset:16
	global_load_dwordx4 v[86:89], v[154:155], off
	global_load_dwordx4 v[34:37], v[60:61], off offset:528
	global_load_dwordx4 v[54:57], v[60:61], off offset:512
	global_load_dwordx4 v[38:41], v[156:157], off offset:528
	global_load_dwordx4 v[46:49], v[156:157], off offset:512
	global_load_dwordx4 v[42:45], v[154:155], off offset:528
	global_load_dwordx4 v[50:53], v[154:155], off offset:512
	v_lshlrev_b32_e32 v0, 6, v96
	v_and_or_b32 v0, v0, s1, v196
	v_lshlrev_b32_e32 v0, 1, v0
	s_waitcnt vmcnt(10)
	v_sub_f32_e32 v67, v67, v59
	v_sub_f32_e32 v66, v66, v59
	v_sub_f32_e32 v69, v69, v59
	v_sub_f32_e32 v68, v68, v59
	v_pk_mul_f32 v[68:69], v[58:59], v[68:69] op_sel_hi:[0,1]
	v_pk_mul_f32 v[66:67], v[58:59], v[66:67] op_sel_hi:[0,1]
	s_waitcnt vmcnt(6)
	v_pk_fma_f32 v[66:67], v[78:79], v[66:67], v[86:87]
	v_pk_fma_f32 v[68:69], v[80:81], v[68:69], v[88:89]
	v_pk_fma_f32 v[66:67], v[66:67], s[2:3], v[30:31] op_sel_hi:[1,0,1]
	v_pk_fma_f32 v[68:69], v[68:69], s[2:3], v[32:33] op_sel_hi:[1,0,1]
	v_add_f32_e32 v30, v66, v67
	v_add_f32_e32 v31, v68, v69
	v_add_f32_e32 v30, v30, v31
	v_add_f32_e32 v78, 0, v30
	v_mul_f32_e32 v30, v67, v67
	v_mul_f32_e32 v31, v69, v69
	v_fmac_f32_e32 v30, v66, v66
	v_fmac_f32_e32 v31, v68, v68
	v_add_f32_e32 v79, v30, v31
	v_sub_f32_e32 v31, v63, v59
	v_sub_f32_e32 v30, v62, v59
	v_sub_f32_e32 v33, v65, v59
	v_sub_f32_e32 v32, v64, v59
	v_pk_mul_f32 v[32:33], v[58:59], v[32:33] op_sel_hi:[0,1]
	v_pk_mul_f32 v[30:31], v[58:59], v[30:31] op_sel_hi:[0,1]
	v_pk_fma_f32 v[30:31], v[70:71], v[30:31], v[82:83]
	v_pk_fma_f32 v[32:33], v[72:73], v[32:33], v[84:85]
	v_pk_fma_f32 v[62:63], v[30:31], s[2:3], v[26:27] op_sel_hi:[1,0,1]
	v_pk_fma_f32 v[64:65], v[32:33], s[2:3], v[28:29] op_sel_hi:[1,0,1]
	v_add_f32_e32 v26, v62, v63
	v_add_f32_e32 v27, v64, v65
	v_add_f32_e32 v26, v26, v27
	v_add_f32_e32 v31, v78, v26
	v_mul_f32_e32 v26, v63, v63
	v_mul_f32_e32 v27, v65, v65
	v_fmac_f32_e32 v26, v62, v62
	v_fmac_f32_e32 v27, v64, v64
	v_add_f32_e32 v26, v26, v27
	v_add_f32_e32 v30, v79, v26
	v_cvt_pk_bf16_f32 v26, v66, v67
	v_cvt_pk_bf16_f32 v27, v68, v69
	v_cvt_pk_bf16_f32 v28, v62, v63
	v_cvt_pk_bf16_f32 v29, v64, v65
	v_lshl_add_u64 v[32:33], v[76:77], 0, v[0:1]
	s_nop 0
	s_nop 1
	v_bfe_u32 v71, v227, 4, 1
	v_sub_u32_e32 v71, 0, v71
	v_lshlrev_b32_e32 v70, 4, v71
	v_lshl_add_u64 v[70:71], v[60:61], 0, v[70:71]
	v_permlane16_swap_b32_e32 v66, v62
	v_permlane16_swap_b32_e32 v67, v63
	v_permlane16_swap_b32_e32 v68, v64
	v_permlane16_swap_b32_e32 v69, v65
	global_store_dwordx4 v[70:71], v[66:69], off
	global_store_dwordx4 v[70:71], v[62:65], off offset:32
	s_nop 1
	v_permlane16_swap_b32_e32 v66, v62
	v_permlane16_swap_b32_e32 v67, v63
	v_permlane16_swap_b32_e32 v68, v64
	v_permlane16_swap_b32_e32 v69, v65
	global_store_dwordx4 v[32:33], v[26:29], off
	s_waitcnt vmcnt(7)
	s_nop 0
	v_sub_f32_e32 v27, v55, v59
	v_sub_f32_e32 v26, v54, v59
	v_sub_f32_e32 v29, v57, v59
	v_sub_f32_e32 v28, v56, v59
	v_pk_mul_f32 v[28:29], v[58:59], v[28:29] op_sel_hi:[0,1]
	v_pk_mul_f32 v[26:27], v[58:59], v[26:27] op_sel_hi:[0,1]
	s_waitcnt vmcnt(3)
	v_pk_fma_f32 v[26:27], v[46:47], v[26:27], v[50:51]
	v_pk_fma_f32 v[28:29], v[48:49], v[28:29], v[52:53]
	v_pk_fma_f32 v[22:23], v[26:27], s[2:3], v[22:23] op_sel_hi:[1,0,1]
	v_pk_fma_f32 v[24:25], v[28:29], s[2:3], v[24:25] op_sel_hi:[1,0,1]
	v_add_f32_e32 v26, v22, v23
	v_add_f32_e32 v27, v24, v25
	v_add_f32_e32 v26, v26, v27
	v_add_f32_e32 v31, v31, v26
	v_mul_f32_e32 v26, v23, v23
	v_mul_f32_e32 v27, v25, v25
	v_fmac_f32_e32 v26, v22, v22
	v_fmac_f32_e32 v27, v24, v24
	v_add_f32_e32 v26, v26, v27
	v_add_f32_e32 v30, v30, v26
	v_sub_f32_e32 v27, v35, v59
	v_sub_f32_e32 v26, v34, v59
	v_sub_f32_e32 v29, v37, v59
	v_sub_f32_e32 v28, v36, v59
	v_pk_mul_f32 v[28:29], v[58:59], v[28:29] op_sel_hi:[0,1]
	v_pk_mul_f32 v[26:27], v[58:59], v[26:27] op_sel_hi:[0,1]
	v_pk_fma_f32 v[26:27], v[38:39], v[26:27], v[42:43]
	v_pk_fma_f32 v[28:29], v[40:41], v[28:29], v[44:45]
	v_pk_fma_f32 v[18:19], v[26:27], s[2:3], v[18:19] op_sel_hi:[1,0,1]
	v_pk_fma_f32 v[20:21], v[28:29], s[2:3], v[20:21] op_sel_hi:[1,0,1]
	v_add_f32_e32 v26, v18, v19
	v_add_f32_e32 v27, v20, v21
	v_add_f32_e32 v26, v26, v27
	v_mul_f32_e32 v27, v19, v19
	v_mul_f32_e32 v28, v21, v21
	v_add_f32_e32 v26, v31, v26
	v_fmac_f32_e32 v27, v18, v18
	v_fmac_f32_e32 v28, v20, v20
	s_nop 0
	s_nop 1
	v_bfe_u32 v33, v227, 4, 1
	v_sub_u32_e32 v33, 0, v33
	v_lshlrev_b32_e32 v32, 4, v33
	v_lshl_add_u64 v[32:33], v[60:61], 0, v[32:33]
	v_permlane16_swap_b32_e32 v22, v18
	v_permlane16_swap_b32_e32 v23, v19
	v_permlane16_swap_b32_e32 v24, v20
	v_permlane16_swap_b32_e32 v25, v21
	global_store_dwordx4 v[32:33], v[22:25], off offset:512
	global_store_dwordx4 v[32:33], v[18:21], off offset:544
	s_nop 1
	v_permlane16_swap_b32_e32 v22, v18
	v_permlane16_swap_b32_e32 v23, v19
	v_permlane16_swap_b32_e32 v24, v20
	v_permlane16_swap_b32_e32 v25, v21
	v_add_f32_e32 v27, v27, v28
	v_cvt_pk_bf16_f32 v22, v22, v23
	v_cvt_pk_bf16_f32 v23, v24, v25
	v_cvt_pk_bf16_f32 v24, v18, v19
	v_lshl_add_u64 v[18:19], v[74:75], 0, v[0:1]
	v_mov_b32_e32 v0, v26
	v_add_f32_e32 v27, v30, v27
	v_cvt_pk_bf16_f32 v25, v20, v21
	v_permlane16_swap_b32_e32 v26, v0
	global_store_dwordx4 v[18:19], v[22:25], off
	v_add_f32_e32 v18, v26, v0
	v_mov_b32_e32 v0, v27
	s_nop 1
	v_permlane16_swap_b32_e32 v27, v0
	v_add_f32_e32 v19, v27, v0
	v_mov_b32_e32 v20, v18
	v_mov_b32_e32 v21, v19
	s_nop 0
	v_permlane32_swap_b32_e32 v18, v20
	v_permlane32_swap_b32_e32 v19, v21
	s_and_saveexec_b64 s[24:25], s[44:45]
	s_cbranch_execz .LBB0_1549
	v_pk_add_f32 v[18:19], v[18:19], v[20:21]
	v_lshlrev_b64 v[20:21], 7, v[96:97]
	v_lshl_add_u64 v[20:21], s[6:7], 0, v[20:21]
	v_lshl_add_u64 v[20:21], s[52:53], 2, v[20:21]
	global_store_dwordx2 v[20:21], v[18:19], off
; __device__ __forceinline__ float xsum16(float v) { const auto r = __builtin_amdgcn_permlane16_swap(__float_as_uint(v), __float_as_uint(v), false, false); return __uint_as_float(r[0]) + __uint_as_float(r[1]); }
; __device__ __forceinline__ float xsum32(float v) { const auto r = __builtin_amdgcn_permlane32_swap(__float_as_uint(v), __float_as_uint(v), false, false); return __uint_as_float(r[0]) + __uint_as_float(r[1]); }
; __device__ __forceinline__ size_t blk_off(int r, int c, int K) { return (size_t)(r >> 8) * 256 * K + (size_t)(c >> 6) * (256 * 64) + (size_t)((r & 255) * 64 + (c & 63)); }
; __device__ __forceinline__ u32x4 pack8(const f32x4 a, const f32x4 b) { u32x4 w; w.x = cvt_pk_bf16(a[0], a[1]); w.y = cvt_pk_bf16(a[2], a[3]); w.z = cvt_pk_bf16(b[0], b[1]); w.w = cvt_pk_bf16(b[2], b[3]); return w; }
;     __device__ __forceinline__ void operator()(const f32x4 (&acc)[2][2][4][2], const pg8::Unit& u, int wr, int wc, int fr, int fq) const {
;     ...
;             for (int m = 0; m < 4; ++m) { const int row = row0 + ai * 128 + m * 16; const float mu = mu4[m], rs = rs4[m];
;                 f32x4 yv[2][2], gq[2][2], bq_[2][2];
; #pragma unroll
;                 for (int bj = 0; bj < 2; ++bj)
; #pragma unroll
;                     for (int n = 0; n < 2; ++n) { yv[bj][n] = *(const f32x4*)(Yin + (size_t)row * D_ + col0 + bj * 128 + 4 * n); gq[bj][n] = *(const f32x4*)(g + col0 + bj * 128 + 4 * n); bq_[bj][n] = *(const f32x4*)(b + col0 + bj * 128 + 4 * n); }
;                 asm volatile("" ::: "memory");
;                 float s1 = 0.f, s2 = 0.f;
; #pragma unroll
;                 for (int bj = 0; bj < 2; ++bj) { float* yp = Y + (size_t)row * D_ + col0 + bj * 128; f32x4 v[2];
; #pragma unroll
;                     for (int n = 0; n < 2; ++n) { v[n] = (((yv[bj][n] - mu) * rs) * gq[bj][n] + bq_[bj][n]) * ALPHA_ + acc[ai][bj][m][n] * sc;
;                         *(f32x4*)(yp + 4 * n) = v[n]; s1 += (v[n][0] + v[n][1]) + (v[n][2] + v[n][3]); s2 += (v[n][0] * v[n][0] + v[n][1] * v[n][1]) + (v[n][2] * v[n][2] + v[n][3] * v[n][3]); }
;                     *(u32x4*)(Yb + blk_off(row, col0 + bj * 128, D_)) = pack8(v[0], v[1]); }
;                 s1 = xsum32(xsum16(s1)); s2 = xsum32(xsum16(s2));
;                 if (fq == 0) *(f32x2*)(stn + (size_t)row * 32 + (u.pn * 4 + wc) * 2) = (f32x2){s1, s2}; asm volatile("" ::: "memory"); } }
.LBB0_1549:
	s_or_b64 exec, exec, s[24:25]
	v_pk_add_f32 v[18:19], v[98:99], v[100:101]
	s_mov_b32 s2, 0x3a800000
	v_pk_mul_f32 v[42:43], v[18:19], s[2:3] op_sel_hi:[1,0]
	s_mov_b32 s1, 0x800000
	v_fma_f32 v0, -v43, v43, v42
	v_max_f32_e32 v0, 0, v0
	v_add_f32_e32 v0, 0x3727c5ac, v0
	v_cmp_gt_f32_e32 vcc, s1, v0
	v_mul_f32_e32 v18, 0x4b800000, v0
	s_load_dwordx16 s[64:79], s[34:35], 0x38
	v_cndmask_b32_e32 v0, v0, v18, vcc
	v_rsq_f32_e32 v0, v0
	s_mov_b32 s2, 0x3fd744fd
	s_movk_i32 s1, 0x3fc0
	v_mul_f32_e32 v18, 0x45800000, v0
	v_cndmask_b32_e32 v42, v0, v18, vcc
	v_lshlrev_b64 v[18:19], 12, v[94:95]
	s_waitcnt lgkmcnt(0)
	v_lshl_add_u64 v[18:19], s[78:79], 0, v[18:19]
	v_lshl_add_u64 v[44:45], v[152:153], 2, v[18:19]
	global_load_dwordx4 v[46:49], v[44:45], off offset:16
	global_load_dwordx4 v[50:53], v[44:45], off
	global_load_dwordx4 v[54:57], v[156:157], off offset:16
	global_load_dwordx4 v[58:61], v[156:157], off
	global_load_dwordx4 v[62:65], v[154:155], off offset:16
	global_load_dwordx4 v[66:69], v[154:155], off
	global_load_dwordx4 v[18:21], v[44:45], off offset:528
	global_load_dwordx4 v[38:41], v[44:45], off offset:512
	global_load_dwordx4 v[22:25], v[156:157], off offset:528
	global_load_dwordx4 v[30:33], v[156:157], off offset:512
	global_load_dwordx4 v[26:29], v[154:155], off offset:528
	global_load_dwordx4 v[34:37], v[154:155], off offset:512
	v_lshlrev_b32_e32 v0, 6, v94
	v_and_or_b32 v0, v0, s1, v196
	v_lshlrev_b32_e32 v0, 1, v0
	s_waitcnt vmcnt(10)
	v_sub_f32_e32 v51, v51, v43
	v_sub_f32_e32 v50, v50, v43
	v_sub_f32_e32 v53, v53, v43
	v_sub_f32_e32 v52, v52, v43
	v_pk_mul_f32 v[52:53], v[42:43], v[52:53] op_sel_hi:[0,1]
	v_pk_mul_f32 v[50:51], v[42:43], v[50:51] op_sel_hi:[0,1]
	s_waitcnt vmcnt(6)
	v_pk_fma_f32 v[50:51], v[58:59], v[50:51], v[66:67]
	v_pk_fma_f32 v[52:53], v[60:61], v[52:53], v[68:69]
	v_pk_fma_f32 v[50:51], v[50:51], s[2:3], v[14:15] op_sel_hi:[1,0,1]
	v_pk_fma_f32 v[52:53], v[52:53], s[2:3], v[16:17] op_sel_hi:[1,0,1]
	v_add_f32_e32 v14, v50, v51
	v_add_f32_e32 v15, v52, v53
	v_add_f32_e32 v14, v14, v15
	v_add_f32_e32 v58, 0, v14
	v_mul_f32_e32 v14, v51, v51
	v_mul_f32_e32 v15, v53, v53
	v_fmac_f32_e32 v14, v50, v50
	v_fmac_f32_e32 v15, v52, v52
	v_add_f32_e32 v59, v14, v15
	v_sub_f32_e32 v15, v47, v43
	v_sub_f32_e32 v14, v46, v43
	v_sub_f32_e32 v17, v49, v43
	v_sub_f32_e32 v16, v48, v43
	v_pk_mul_f32 v[16:17], v[42:43], v[16:17] op_sel_hi:[0,1]
	v_pk_mul_f32 v[14:15], v[42:43], v[14:15] op_sel_hi:[0,1]
	v_pk_fma_f32 v[14:15], v[54:55], v[14:15], v[62:63]
	v_pk_fma_f32 v[16:17], v[56:57], v[16:17], v[64:65]
	v_pk_fma_f32 v[46:47], v[14:15], s[2:3], v[10:11] op_sel_hi:[1,0,1]
	v_pk_fma_f32 v[48:49], v[16:17], s[2:3], v[12:13] op_sel_hi:[1,0,1]
	v_add_f32_e32 v10, v46, v47
	v_add_f32_e32 v11, v48, v49
	v_add_f32_e32 v10, v10, v11
	v_add_f32_e32 v15, v58, v10
	v_mul_f32_e32 v10, v47, v47
	v_mul_f32_e32 v11, v49, v49
	v_fmac_f32_e32 v10, v46, v46
	v_fmac_f32_e32 v11, v48, v48
	v_add_f32_e32 v10, v10, v11
	v_add_f32_e32 v14, v59, v10
	v_cvt_pk_bf16_f32 v10, v50, v51
	v_cvt_pk_bf16_f32 v11, v52, v53
	v_cvt_pk_bf16_f32 v12, v46, v47
	v_cvt_pk_bf16_f32 v13, v48, v49
	v_lshl_add_u64 v[16:17], v[76:77], 0, v[0:1]
	s_nop 0
	s_nop 1
	v_bfe_u32 v55, v227, 4, 1
	v_sub_u32_e32 v55, 0, v55
	v_lshlrev_b32_e32 v54, 4, v55
	v_lshl_add_u64 v[54:55], v[44:45], 0, v[54:55]
	v_permlane16_swap_b32_e32 v50, v46
	v_permlane16_swap_b32_e32 v51, v47
	v_permlane16_swap_b32_e32 v52, v48
	v_permlane16_swap_b32_e32 v53, v49
	global_store_dwordx4 v[54:55], v[50:53], off
	global_store_dwordx4 v[54:55], v[46:49], off offset:32
	s_nop 1
	v_permlane16_swap_b32_e32 v50, v46
	v_permlane16_swap_b32_e32 v51, v47
	v_permlane16_swap_b32_e32 v52, v48
	v_permlane16_swap_b32_e32 v53, v49
	global_store_dwordx4 v[16:17], v[10:13], off
	s_waitcnt vmcnt(7)
	s_nop 0
	v_sub_f32_e32 v11, v39, v43
	v_sub_f32_e32 v10, v38, v43
	v_sub_f32_e32 v13, v41, v43
	v_sub_f32_e32 v12, v40, v43
	v_pk_mul_f32 v[12:13], v[42:43], v[12:13] op_sel_hi:[0,1]
	v_pk_mul_f32 v[10:11], v[42:43], v[10:11] op_sel_hi:[0,1]
	s_waitcnt vmcnt(3)
	v_pk_fma_f32 v[10:11], v[30:31], v[10:11], v[34:35]
	v_pk_fma_f32 v[12:13], v[32:33], v[12:13], v[36:37]
	v_pk_fma_f32 v[6:7], v[10:11], s[2:3], v[6:7] op_sel_hi:[1,0,1]
	v_pk_fma_f32 v[8:9], v[12:13], s[2:3], v[8:9] op_sel_hi:[1,0,1]
	v_add_f32_e32 v10, v6, v7
	v_add_f32_e32 v11, v8, v9
	v_add_f32_e32 v10, v10, v11
	v_add_f32_e32 v15, v15, v10
	v_mul_f32_e32 v10, v7, v7
	v_mul_f32_e32 v11, v9, v9
	v_fmac_f32_e32 v10, v6, v6
	v_fmac_f32_e32 v11, v8, v8
	v_add_f32_e32 v10, v10, v11
	v_add_f32_e32 v14, v14, v10
	v_sub_f32_e32 v11, v19, v43
	v_sub_f32_e32 v10, v18, v43
	v_sub_f32_e32 v13, v21, v43
	v_sub_f32_e32 v12, v20, v43
	v_pk_mul_f32 v[12:13], v[42:43], v[12:13] op_sel_hi:[0,1]
	v_pk_mul_f32 v[10:11], v[42:43], v[10:11] op_sel_hi:[0,1]
	v_pk_fma_f32 v[10:11], v[22:23], v[10:11], v[26:27]
	v_pk_fma_f32 v[12:13], v[24:25], v[12:13], v[28:29]
	v_pk_fma_f32 v[2:3], v[10:11], s[2:3], v[2:3] op_sel_hi:[1,0,1]
	v_pk_fma_f32 v[4:5], v[12:13], s[2:3], v[4:5] op_sel_hi:[1,0,1]
	v_add_f32_e32 v10, v2, v3
	v_add_f32_e32 v11, v4, v5
	v_add_f32_e32 v10, v10, v11
	v_mul_f32_e32 v11, v3, v3
	v_mul_f32_e32 v12, v5, v5
	v_add_f32_e32 v10, v15, v10
	v_fmac_f32_e32 v11, v2, v2
	v_fmac_f32_e32 v12, v4, v4
	s_nop 0
	s_nop 1
	v_bfe_u32 v17, v227, 4, 1
	v_sub_u32_e32 v17, 0, v17
	v_lshlrev_b32_e32 v16, 4, v17
	v_lshl_add_u64 v[16:17], v[44:45], 0, v[16:17]
	v_permlane16_swap_b32_e32 v6, v2
	v_permlane16_swap_b32_e32 v7, v3
	v_permlane16_swap_b32_e32 v8, v4
	v_permlane16_swap_b32_e32 v9, v5
	global_store_dwordx4 v[16:17], v[6:9], off offset:512
	global_store_dwordx4 v[16:17], v[2:5], off offset:544
	s_nop 1
	v_permlane16_swap_b32_e32 v6, v2
	v_permlane16_swap_b32_e32 v7, v3
	v_permlane16_swap_b32_e32 v8, v4
	v_permlane16_swap_b32_e32 v9, v5
	v_add_f32_e32 v11, v11, v12
	v_cvt_pk_bf16_f32 v6, v6, v7
	v_cvt_pk_bf16_f32 v7, v8, v9
	v_cvt_pk_bf16_f32 v8, v2, v3
	v_lshl_add_u64 v[2:3], v[74:75], 0, v[0:1]
	v_mov_b32_e32 v0, v10
	v_add_f32_e32 v11, v14, v11
	v_cvt_pk_bf16_f32 v9, v4, v5
	v_permlane16_swap_b32_e32 v10, v0
	global_store_dwordx4 v[2:3], v[6:9], off
	v_add_f32_e32 v2, v10, v0
	v_mov_b32_e32 v0, v11
	s_nop 1
	v_permlane16_swap_b32_e32 v11, v0
	v_add_f32_e32 v3, v11, v0
	v_mov_b32_e32 v4, v2
	v_mov_b32_e32 v5, v3
	s_nop 0
	v_permlane32_swap_b32_e32 v2, v4
	v_permlane32_swap_b32_e32 v3, v5
	s_and_saveexec_b64 s[24:25], s[44:45]
	s_cbranch_execz .LBB0_1551
	v_pk_add_f32 v[2:3], v[2:3], v[4:5]
	v_lshlrev_b64 v[4:5], 7, v[94:95]
	v_lshl_add_u64 v[4:5], s[6:7], 0, v[4:5]
	v_lshl_add_u64 v[4:5], s[52:53], 2, v[4:5]
	global_store_dwordx2 v[4:5], v[2:3], off

; __device__ __forceinline__ float xsum16(float v) { const auto r = __builtin_amdgcn_permlane16_swap(__float_as_uint(v), __float_as_uint(v), false, false); return __uint_as_float(r[0]) + __uint_as_float(r[1]); }
; __device__ __forceinline__ float xsum32(float v) { const auto r = __builtin_amdgcn_permlane32_swap(__float_as_uint(v), __float_as_uint(v), false, false); return __uint_as_float(r[0]) + __uint_as_float(r[1]); }
; __device__ __forceinline__ void row_stats4(const float* st, int rowb, int fq, float (&mu)[4], float (&rs)[4]) {
;     f32x4 a[4], b[4];
; #pragma unroll
;     for (int m = 0; m < 4; ++m) { const f32x4* p = (const f32x4*)(st + (size_t)(rowb + m * 16) * 32 + fq * 8); a[m] = p[0]; b[m] = p[1]; }
; #pragma unroll
;     for (int m = 0; m < 4; ++m) { float s1 = (a[m][0] + a[m][2]) + (b[m][0] + b[m][2]), s2 = (a[m][1] + a[m][3]) + (b[m][1] + b[m][3]);
;         s1 = xsum32(xsum16(s1)); s2 = xsum32(xsum16(s2));
;         const float mm = s1 * (1.0f / 1024.0f); mu[m] = mm; rs[m] = rsqrtf(fmaxf(s2 * (1.0f / 1024.0f) - mm * mm, 0.f) + LN_EPS_); }
;     asm volatile("" ::: "memory");
; }
;     __device__ __forceinline__ void operator()(const f32x4 (&acc)[2][2][4][2], const pg8::Unit& u, int wr, int wc, int fr, int fq) const {
;         const int row0 = u.pm * 256 + wr * 64 + fr, col0 = u.pn * 256 + wc * 32 + fq * 8;
; #pragma unroll
;         for (int ai = 0; ai < 2; ++ai) { float mu4[4], rs4[4]; row_stats4(stp, row0 + ai * 128, fq, mu4, rs4);
; #pragma unroll
;             for (int m = 0; m < 4; ++m) { const int row = row0 + ai * 128 + m * 16; const float mu = mu4[m], rs = rs4[m];
;                 f32x4 yv[2][2], gq[2][2], bq_[2][2];
; #pragma unroll
;                 for (int bj = 0; bj < 2; ++bj)
; #pragma unroll
;                     for (int n = 0; n < 2; ++n) { yv[bj][n] = *(const f32x4*)(Yin + (size_t)row * D_ + col0 + bj * 128 + 4 * n); gq[bj][n] = *(const f32x4*)(g + col0 + bj * 128 + 4 * n); bq_[bj][n] = *(const f32x4*)(b + col0 + bj * 128 + 4 * n); }
.LBB0_1703:
	s_lshl_b32 s3, s3, 8
	s_add_i32 s3, s3, s0
	v_or_b32_e32 v158, s3, v184
	v_ashrrev_i32_e32 v159, 31, v158
	v_lshlrev_b64 v[130:131], 7, v[158:159]
	v_lshl_add_u64 v[136:137], v[146:147], 0, v[130:131]
	v_or_b32_e32 v182, 16, v158
	global_load_dwordx4 v[132:135], v[136:137], off
	global_load_dwordx4 v[166:169], v[136:137], off offset:16
	v_ashrrev_i32_e32 v183, 31, v182
	v_lshlrev_b64 v[172:173], 7, v[182:183]
	v_lshl_add_u64 v[136:137], v[146:147], 0, v[172:173]
	global_load_dwordx4 v[174:177], v[136:137], off
	global_load_dwordx4 v[178:181], v[136:137], off offset:16
	v_or_b32_e32 v170, 32, v158
	v_ashrrev_i32_e32 v171, 31, v170
	v_lshlrev_b64 v[164:165], 7, v[170:171]
	v_lshl_add_u64 v[136:137], v[146:147], 0, v[164:165]
	global_load_dwordx4 v[186:189], v[136:137], off
	global_load_dwordx4 v[190:193], v[136:137], off offset:16
	s_load_dwordx16 s[60:75], s[34:35], 0x38
	s_lshl_b32 s1, s2, 8
	s_lshl_b32 s16, s2, 3
	s_or_b32 s2, s1, s53
	v_or_b32_e32 v162, 48, v158
	v_or_b32_e32 v152, s2, v185
	v_ashrrev_i32_e32 v163, 31, v162
	v_ashrrev_i32_e32 v153, 31, v152
	v_lshlrev_b64 v[136:137], 12, v[158:159]
	v_lshlrev_b64 v[160:161], 7, v[162:163]
	v_lshlrev_b64 v[198:199], 2, v[152:153]
	s_waitcnt lgkmcnt(0)
	v_lshl_add_u64 v[136:137], s[74:75], 0, v[136:137]
	v_lshl_add_u64 v[202:203], v[146:147], 0, v[160:161]
	v_lshl_add_u64 v[156:157], s[10:11], 0, v[198:199]
	v_lshl_add_u64 v[154:155], s[12:13], 0, v[198:199]
	v_lshl_add_u64 v[136:137], v[136:137], 0, v[198:199]
	global_load_dwordx4 v[198:201], v[202:203], off
	s_nop 0
	global_load_dwordx4 v[202:205], v[202:203], off offset:16
	s_or_b32 s38, s16, s15
	s_mov_b32 s16, 0x3a800000
	s_mov_b32 s1, 0x800000
	global_load_dwordx4 v[206:209], v[136:137], off offset:16
	global_load_dwordx4 v[210:213], v[136:137], off
	global_load_dwordx4 v[214:217], v[156:157], off offset:16
	global_load_dwordx4 v[218:221], v[156:157], off
	global_load_dwordx4 v[222:225], v[154:155], off offset:16
	global_load_dwordx4 v[234:237], v[154:155], off
	s_mov_b32 s18, 0x3fd744fd
	s_ashr_i32 s44, s2, 6
	v_bitop3_b32 v196, s2, 56, v185 bitop3:0xc8
	s_ashr_i32 s39, s38, 31
	s_ashr_i32 s45, s44, 31
	s_waitcnt vmcnt(0)
	v_mov_b32_e32 v228, v132
	v_mov_b32_e32 v229, v166
	v_mov_b32_e32 v238, v134
	v_mov_b32_e32 v239, v168
	v_mov_b32_e32 v166, v133
	v_mov_b32_e32 v168, v135
	v_pk_add_f32 v[132:133], v[228:229], v[238:239]
	v_pk_add_f32 v[134:135], v[166:167], v[168:169]
	v_pk_add_f32 v[132:133], v[132:133], v[132:133] op_sel:[0,1] op_sel_hi:[1,0]
	v_pk_add_f32 v[134:135], v[134:135], v[134:135] op_sel:[0,1] op_sel_hi:[1,0]
	v_mov_b32_e32 v166, v174
	v_mov_b32_e32 v167, v178
	v_mov_b32_e32 v168, v176
	v_mov_b32_e32 v169, v180
	v_mov_b32_e32 v0, v132
	v_mov_b32_e32 v133, v134
	v_pk_add_f32 v[166:167], v[166:167], v[168:169]
	v_permlane16_swap_b32_e32 v132, v0
	v_permlane16_swap_b32_e32 v134, v133
	v_mov_b32_e32 v178, v175
	v_mov_b32_e32 v180, v177
	v_pk_add_f32 v[166:167], v[166:167], v[166:167] op_sel:[0,1] op_sel_hi:[1,0]
	v_add_f32_e32 v177, v132, v0
	v_add_f32_e32 v176, v134, v133
	v_pk_add_f32 v[168:169], v[178:179], v[180:181]
	v_mov_b32_e32 v135, v166
	v_mov_b32_e32 v179, v177
	v_mov_b32_e32 v178, v176
	v_permlane16_swap_b32_e32 v166, v135
	v_permlane32_swap_b32_e32 v177, v179
	v_permlane32_swap_b32_e32 v176, v178
	v_add_f32_e32 v133, v166, v135
	v_pk_add_f32 v[166:167], v[176:177], v[178:179]
	v_pk_add_f32 v[168:169], v[168:169], v[168:169] op_sel:[0,1] op_sel_hi:[1,0]
	v_pk_mul_f32 v[228:229], v[166:167], s[16:17] op_sel_hi:[1,0]
	v_mov_b32_e32 v159, v168
	v_fma_f32 v0, -v229, v229, v228
	v_max_f32_e32 v0, 0, v0
	v_permlane16_swap_b32_e32 v168, v159
	v_add_f32_e32 v0, 0x3727c5ac, v0
	v_add_f32_e32 v132, v168, v159
	v_mul_f32_e32 v159, 0x4b800000, v0
	v_cmp_gt_f32_e32 vcc, s1, v0
	v_mov_b32_e32 v174, v186
	v_mov_b32_e32 v175, v190
	v_cndmask_b32_e32 v0, v0, v159, vcc
	v_rsq_f32_e32 v0, v0
	v_mov_b32_e32 v166, v188
	v_mov_b32_e32 v167, v192
	v_pk_add_f32 v[166:167], v[174:175], v[166:167]
	v_mul_f32_e32 v159, 0x45800000, v0
	v_pk_add_f32 v[166:167], v[166:167], v[166:167] op_sel:[0,1] op_sel_hi:[1,0]
	v_mov_b32_e32 v190, v187
	v_mov_b32_e32 v192, v189
	v_cndmask_b32_e32 v0, v0, v159, vcc
	v_pk_add_f32 v[168:169], v[190:191], v[192:193]
	v_mov_b32_e32 v159, v166
	v_pk_add_f32 v[168:169], v[168:169], v[168:169] op_sel:[0,1] op_sel_hi:[1,0]
	s_nop 0
	v_permlane16_swap_b32_e32 v166, v159
	v_add_f32_e32 v175, v166, v159
	v_mov_b32_e32 v159, v168
	s_nop 1
	v_permlane16_swap_b32_e32 v168, v159
	global_load_dwordx4 v[178:181], v[136:137], off offset:528
	global_load_dwordx4 v[186:189], v[136:137], off offset:512
	v_add_f32_e32 v174, v168, v159
	v_mov_b32_e32 v166, v198
	v_mov_b32_e32 v167, v202
	v_mov_b32_e32 v168, v200
	v_mov_b32_e32 v169, v204
	v_mov_b32_e32 v202, v199
	v_mov_b32_e32 v204, v201
	v_pk_add_f32 v[166:167], v[166:167], v[168:169]
	v_pk_add_f32 v[168:169], v[202:203], v[204:205]
	global_load_dwordx4 v[190:193], v[156:157], off offset:528
	global_load_dwordx4 v[198:201], v[156:157], off offset:512
	global_load_dwordx4 v[202:205], v[154:155], off offset:528
	global_load_dwordx4 v[238:241], v[154:155], off offset:512
	v_sub_f32_e32 v213, v213, v229
	v_sub_f32_e32 v212, v212, v229
	v_sub_f32_e32 v211, v211, v229
	v_sub_f32_e32 v210, v210, v229
	v_pk_mul_f32 v[210:211], v[0:1], v[210:211] op_sel_hi:[0,1]
	v_pk_mul_f32 v[212:213], v[0:1], v[212:213] op_sel_hi:[0,1]
	v_sub_f32_e32 v209, v209, v229
	v_sub_f32_e32 v208, v208, v229
	v_sub_f32_e32 v207, v207, v229
	v_sub_f32_e32 v206, v206, v229
	v_pk_fma_f32 v[212:213], v[220:221], v[212:213], v[236:237]
	v_pk_fma_f32 v[210:211], v[218:219], v[210:211], v[234:235]
; __device__ __forceinline__ float xsum16(float v) { const auto r = __builtin_amdgcn_permlane16_swap(__float_as_uint(v), __float_as_uint(v), false, false); return __uint_as_float(r[0]) + __uint_as_float(r[1]); }
; __device__ __forceinline__ float xsum32(float v) { const auto r = __builtin_amdgcn_permlane32_swap(__float_as_uint(v), __float_as_uint(v), false, false); return __uint_as_float(r[0]) + __uint_as_float(r[1]); }
; __device__ __forceinline__ size_t blk_off(int r, int c, int K) { return (size_t)(r >> 8) * 256 * K + (size_t)(c >> 6) * (256 * 64) + (size_t)((r & 255) * 64 + (c & 63)); }
; __device__ __forceinline__ u32x4 pack8(const f32x4 a, const f32x4 b) { u32x4 w; w.x = cvt_pk_bf16(a[0], a[1]); w.y = cvt_pk_bf16(a[2], a[3]); w.z = cvt_pk_bf16(b[0], b[1]); w.w = cvt_pk_bf16(b[2], b[3]); return w; }
;     __device__ __forceinline__ void operator()(const f32x4 (&acc)[2][2][4][2], const pg8::Unit& u, int wr, int wc, int fr, int fq) const {
;     ...
;             for (int m = 0; m < 4; ++m) { const int row = row0 + ai * 128 + m * 16; const float mu = mu4[m], rs = rs4[m];
;                 f32x4 yv[2][2], gq[2][2], bq_[2][2];
; #pragma unroll
;                 for (int bj = 0; bj < 2; ++bj)
; #pragma unroll
;                     for (int n = 0; n < 2; ++n) { yv[bj][n] = *(const f32x4*)(Yin + (size_t)row * D_ + col0 + bj * 128 + 4 * n); gq[bj][n] = *(const f32x4*)(g + col0 + bj * 128 + 4 * n); bq_[bj][n] = *(const f32x4*)(b + col0 + bj * 128 + 4 * n); }
;                 asm volatile("" ::: "memory");
;                 float s1 = 0.f, s2 = 0.f;
; #pragma unroll
;                 for (int bj = 0; bj < 2; ++bj) { float* yp = Y + (size_t)row * D_ + col0 + bj * 128; f32x4 v[2];
; #pragma unroll
;                     for (int n = 0; n < 2; ++n) { v[n] = (((yv[bj][n] - mu) * rs) * gq[bj][n] + bq_[bj][n]) * ALPHA_ + acc[ai][bj][m][n] * sc;
;                         *(f32x4*)(yp + 4 * n) = v[n]; s1 += (v[n][0] + v[n][1]) + (v[n][2] + v[n][3]); s2 += (v[n][0] * v[n][0] + v[n][1] * v[n][1]) + (v[n][2] * v[n][2] + v[n][3] * v[n][3]); }
;                     *(u32x4*)(Yb + blk_off(row, col0 + bj * 128, D_)) = pack8(v[0], v[1]); }
;                 s1 = xsum32(xsum16(s1)); s2 = xsum32(xsum16(s2));
;                 if (fq == 0) *(f32x2*)(stn + (size_t)row * 32 + (u.pn * 4 + wc) * 2) = (f32x2){s1, s2}; asm volatile("" ::: "memory"); } }
	v_pk_mul_f32 v[206:207], v[0:1], v[206:207] op_sel_hi:[0,1]
	v_pk_mul_f32 v[208:209], v[0:1], v[208:209] op_sel_hi:[0,1]
	v_pk_mul_f32 v[210:211], v[210:211], s[18:19] op_sel_hi:[1,0]
	v_pk_mul_f32 v[212:213], v[212:213], s[18:19] op_sel_hi:[1,0]
	v_pk_fma_f32 v[208:209], v[216:217], v[208:209], v[224:225]
	v_pk_fma_f32 v[206:207], v[214:215], v[206:207], v[222:223]
	v_pk_fma_f32 v[128:129], v[128:129], 0.5, v[212:213] op_sel_hi:[1,0,1]
	v_pk_fma_f32 v[126:127], v[126:127], 0.5, v[210:211] op_sel_hi:[1,0,1]
	v_pk_mul_f32 v[206:207], v[206:207], s[18:19] op_sel_hi:[1,0]
	v_pk_mul_f32 v[208:209], v[208:209], s[18:19] op_sel_hi:[1,0]
	v_add_f32_e32 v197, v126, v127
	v_add_f32_e32 v210, v128, v129
	v_pk_fma_f32 v[124:125], v[124:125], 0.5, v[208:209] op_sel_hi:[1,0,1]
	v_pk_fma_f32 v[122:123], v[122:123], 0.5, v[206:207] op_sel_hi:[1,0,1]
	v_pk_add_f32 v[166:167], v[166:167], v[166:167] op_sel:[0,1] op_sel_hi:[1,0]
	v_add_f32_e32 v197, v197, v210
	v_add_f32_e32 v206, v122, v123
	v_add_f32_e32 v207, v124, v125
	v_mov_b32_e32 v159, v166
	v_add_f32_e32 v197, 0, v197
	v_add_f32_e32 v206, v206, v207
	v_pk_add_f32 v[168:169], v[168:169], v[168:169] op_sel:[0,1] op_sel_hi:[1,0]
	v_permlane16_swap_b32_e32 v166, v159
	v_mul_f32_e32 v210, v127, v127
	v_mul_f32_e32 v211, v129, v129
	v_add_f32_e32 v197, v197, v206
	v_mul_f32_e32 v206, v123, v123
	v_mul_f32_e32 v207, v125, v125
	v_add_f32_e32 v167, v166, v159
	v_mov_b32_e32 v159, v168
	s_ashr_i32 s16, s3, 8
	s_nop 0
	v_fmac_f32_e32 v210, v126, v126
	v_fmac_f32_e32 v211, v128, v128
	s_nop 1
	v_bfe_u32 v135, v227, 4, 1
	v_sub_u32_e32 v135, 0, v135
	v_lshlrev_b32_e32 v134, 4, v135
	v_lshl_add_u64 v[134:135], v[136:137], 0, v[134:135]
	v_permlane16_swap_b32_e32 v126, v122
	v_permlane16_swap_b32_e32 v127, v123
	v_permlane16_swap_b32_e32 v128, v124
	v_permlane16_swap_b32_e32 v129, v125
	global_store_dwordx4 v[134:135], v[126:129], off
	global_store_dwordx4 v[134:135], v[122:125], off offset:32
	s_nop 1
	v_permlane16_swap_b32_e32 v126, v122
	v_permlane16_swap_b32_e32 v127, v123
	v_permlane16_swap_b32_e32 v128, v124
	v_permlane16_swap_b32_e32 v129, v125
	v_fmac_f32_e32 v206, v122, v122
	v_fmac_f32_e32 v207, v124, v124
	v_cvt_pk_bf16_f32 v126, v126, v127
	v_cvt_pk_bf16_f32 v127, v128, v129
	v_cvt_pk_bf16_f32 v128, v122, v123
	v_cvt_pk_bf16_f32 v129, v124, v125
	v_permlane16_swap_b32_e32 v168, v159
	s_ashr_i32 s17, s16, 31
	v_add_f32_e32 v166, v168, v159
	s_lshl_b64 s[16:17], s[16:17], 19
	v_lshlrev_b32_e32 v159, 6, v158
	s_movk_i32 s1, 0x33c0
	v_readlane_b32 s2, v253, 59
	v_and_or_b32 v159, v159, s1, v196
	v_readlane_b32 s3, v253, 60
	s_add_u32 s1, s2, s16
	s_addc_u32 s16, s3, s17
	s_lshl_b64 s[24:25], s[44:45], 15
	s_add_u32 s48, s1, s24
	s_waitcnt vmcnt(6)
	v_sub_f32_e32 v123, v189, v229
	v_sub_f32_e32 v122, v188, v229
	v_sub_f32_e32 v125, v187, v229
	v_sub_f32_e32 v124, v186, v229
	v_pk_mul_f32 v[124:125], v[0:1], v[124:125] op_sel_hi:[0,1]
	v_pk_mul_f32 v[122:123], v[0:1], v[122:123] op_sel_hi:[0,1]
	s_addc_u32 s49, s16, s25
	v_lshlrev_b32_e32 v159, 1, v159
	global_store_dwordx4 v159, v[126:129], s[48:49]
	v_add_f32_e32 v210, v210, v211
	s_waitcnt vmcnt(3)
	v_pk_fma_f32 v[122:123], v[200:201], v[122:123], v[240:241]
	v_pk_fma_f32 v[124:125], v[198:199], v[124:125], v[238:239]
	v_pk_mul_f32 v[122:123], v[122:123], s[18:19] op_sel_hi:[1,0]
	v_pk_mul_f32 v[124:125], v[124:125], s[18:19] op_sel_hi:[1,0]
	v_pk_fma_f32 v[120:121], v[120:121], 0.5, v[122:123] op_sel_hi:[1,0,1]
	v_pk_fma_f32 v[118:119], v[118:119], 0.5, v[124:125] op_sel_hi:[1,0,1]
	v_add_f32_e32 v123, v120, v121
	v_add_f32_e32 v122, v118, v119
	v_add_f32_e32 v122, v122, v123
	v_add_f32_e32 v126, v197, v122
	v_mul_f32_e32 v122, v119, v119
	v_mul_f32_e32 v123, v121, v121
	v_add_f32_e32 v206, v206, v207
	v_fmac_f32_e32 v122, v118, v118
	v_fmac_f32_e32 v123, v120, v120
	v_add_f32_e32 v206, v210, v206
	v_add_f32_e32 v122, v122, v123
	v_add_f32_e32 v127, v206, v122
	v_sub_f32_e32 v123, v181, v229
	v_sub_f32_e32 v122, v180, v229
	v_sub_f32_e32 v125, v179, v229
	v_sub_f32_e32 v124, v178, v229
	v_pk_mul_f32 v[124:125], v[0:1], v[124:125] op_sel_hi:[0,1]
	v_pk_mul_f32 v[122:123], v[0:1], v[122:123] op_sel_hi:[0,1]
	v_pk_fma_f32 v[122:123], v[192:193], v[122:123], v[204:205]
	v_pk_fma_f32 v[124:125], v[190:191], v[124:125], v[202:203]
	v_pk_mul_f32 v[122:123], v[122:123], s[18:19] op_sel_hi:[1,0]
	v_pk_mul_f32 v[124:125], v[124:125], s[18:19] op_sel_hi:[1,0]
	v_pk_fma_f32 v[116:117], v[116:117], 0.5, v[122:123] op_sel_hi:[1,0,1]
	v_pk_fma_f32 v[114:115], v[114:115], 0.5, v[124:125] op_sel_hi:[1,0,1]
	v_add_f32_e32 v122, v116, v117
	v_add_f32_e32 v0, v114, v115
	v_add_f32_e32 v0, v0, v122
	v_mul_f32_e32 v122, v115, v115
	v_mul_f32_e32 v123, v117, v117
	v_add_f32_e32 v0, v126, v0
	v_fmac_f32_e32 v122, v114, v114
	v_fmac_f32_e32 v123, v116, v116
	s_nop 0
	s_nop 1
	v_bfe_u32 v125, v227, 4, 1
	v_sub_u32_e32 v125, 0, v125
	v_lshlrev_b32_e32 v124, 4, v125
	v_lshl_add_u64 v[124:125], v[136:137], 0, v[124:125]
	v_permlane16_swap_b32_e32 v118, v114
	v_permlane16_swap_b32_e32 v119, v115
	v_permlane16_swap_b32_e32 v120, v116
	v_permlane16_swap_b32_e32 v121, v117
	global_store_dwordx4 v[124:125], v[118:121], off offset:512
	global_store_dwordx4 v[124:125], v[114:117], off offset:544
	s_nop 1
	v_permlane16_swap_b32_e32 v118, v114
	v_permlane16_swap_b32_e32 v119, v115
	v_permlane16_swap_b32_e32 v120, v116
	v_permlane16_swap_b32_e32 v121, v117
	v_add_f32_e32 v122, v122, v123
	v_cvt_pk_bf16_f32 v118, v118, v119
	v_cvt_pk_bf16_f32 v119, v120, v121
	v_cvt_pk_bf16_f32 v120, v114, v115
	v_mov_b32_e32 v114, v0
	v_add_f32_e32 v122, v127, v122
	s_nop 0
	v_permlane16_swap_b32_e32 v0, v114
	s_or_b32 s2, s44, 2
	v_add_f32_e32 v114, v0, v114
	v_mov_b32_e32 v0, v122
	s_ashr_i32 s3, s2, 31
	s_nop 0
	v_permlane16_swap_b32_e32 v122, v0
	s_lshl_b64 s[44:45], s[2:3], 15
	v_add_f32_e32 v115, v122, v0
	v_mov_b32_e32 v135, v133
	v_mov_b32_e32 v134, v132
	v_mov_b32_e32 v177, v175
	v_mov_b32_e32 v176, v174
	v_mov_b32_e32 v169, v167
	v_mov_b32_e32 v168, v166
	v_cvt_pk_bf16_f32 v121, v116, v117
	s_add_u32 s46, s1, s44
	v_mov_b32_e32 v116, v114
	v_mov_b32_e32 v117, v115
	v_permlane32_swap_b32_e32 v133, v135
	v_permlane32_swap_b32_e32 v132, v134
	v_permlane32_swap_b32_e32 v175, v177
	v_permlane32_swap_b32_e32 v174, v176
	v_permlane32_swap_b32_e32 v167, v169
	v_permlane32_swap_b32_e32 v166, v168
	s_addc_u32 s47, s16, s45
	v_permlane32_swap_b32_e32 v114, v116
	v_permlane32_swap_b32_e32 v115, v117
	global_store_dwordx4 v159, v[118:121], s[46:47]
	s_and_saveexec_b64 s[26:27], s[40:41]
	s_cbranch_execz .LBB0_1705
	v_pk_add_f32 v[114:115], v[114:115], v[116:117]
	v_lshl_add_u64 v[116:117], s[8:9], 0, v[130:131]
	v_lshl_add_u64 v[116:117], s[38:39], 2, v[116:117]
	global_store_dwordx2 v[116:117], v[114:115], off
; __device__ __forceinline__ size_t blk_off(int r, int c, int K) { return (size_t)(r >> 8) * 256 * K + (size_t)(c >> 6) * (256 * 64) + (size_t)((r & 255) * 64 + (c & 63)); }
; __device__ __forceinline__ u32x4 pack8(const f32x4 a, const f32x4 b) { u32x4 w; w.x = cvt_pk_bf16(a[0], a[1]); w.y = cvt_pk_bf16(a[2], a[3]); w.z = cvt_pk_bf16(b[0], b[1]); w.w = cvt_pk_bf16(b[2], b[3]); return w; }
;     __device__ __forceinline__ void operator()(const f32x4 (&acc)[2][2][4][2], const pg8::Unit& u, int wr, int wc, int fr, int fq) const {
;     ...
;             for (int m = 0; m < 4; ++m) { const int row = row0 + ai * 128 + m * 16; const float mu = mu4[m], rs = rs4[m];
;                 f32x4 yv[2][2], gq[2][2], bq_[2][2];
; #pragma unroll
;                 for (int bj = 0; bj < 2; ++bj)
; #pragma unroll
;                     for (int n = 0; n < 2; ++n) { yv[bj][n] = *(const f32x4*)(Yin + (size_t)row * D_ + col0 + bj * 128 + 4 * n); gq[bj][n] = *(const f32x4*)(g + col0 + bj * 128 + 4 * n); bq_[bj][n] = *(const f32x4*)(b + col0 + bj * 128 + 4 * n); }
;                 asm volatile("" ::: "memory");
;                 float s1 = 0.f, s2 = 0.f;
; #pragma unroll
;                 for (int bj = 0; bj < 2; ++bj) { float* yp = Y + (size_t)row * D_ + col0 + bj * 128; f32x4 v[2];
; #pragma unroll
;                     for (int n = 0; n < 2; ++n) { v[n] = (((yv[bj][n] - mu) * rs) * gq[bj][n] + bq_[bj][n]) * ALPHA_ + acc[ai][bj][m][n] * sc;
;                         *(f32x4*)(yp + 4 * n) = v[n]; s1 += (v[n][0] + v[n][1]) + (v[n][2] + v[n][3]); s2 += (v[n][0] * v[n][0] + v[n][1] * v[n][1]) + (v[n][2] * v[n][2] + v[n][3] * v[n][3]); }
;                     *(u32x4*)(Yb + blk_off(row, col0 + bj * 128, D_)) = pack8(v[0], v[1]); }
.LBB0_1705:
	s_or_b64 exec, exec, s[26:27]
	v_pk_add_f32 v[114:115], v[132:133], v[134:135]
	s_mov_b32 s2, 0x3a800000
	v_pk_mul_f32 v[178:179], v[114:115], s[2:3] op_sel_hi:[1,0]
	s_mov_b32 s1, 0x800000
	v_fma_f32 v0, -v179, v179, v178
	v_max_f32_e32 v0, 0, v0
	v_add_f32_e32 v0, 0x3727c5ac, v0
	v_cmp_gt_f32_e32 vcc, s1, v0
	v_mul_f32_e32 v114, 0x4b800000, v0
	s_load_dwordx16 s[60:75], s[34:35], 0x38
	v_cndmask_b32_e32 v0, v0, v114, vcc
	v_rsq_f32_e32 v0, v0
	v_lshlrev_b32_e32 v159, 6, v182
	s_mov_b32 s2, 0x3fd744fd
	v_mul_f32_e32 v114, 0x45800000, v0
	v_cndmask_b32_e32 v0, v0, v114, vcc
	v_lshlrev_b64 v[114:115], 12, v[182:183]
	s_waitcnt lgkmcnt(0)
	v_lshl_add_u64 v[114:115], s[74:75], 0, v[114:115]
	v_lshl_add_u64 v[180:181], v[152:153], 2, v[114:115]
	global_load_dwordx4 v[186:189], v[180:181], off offset:16
	global_load_dwordx4 v[190:193], v[180:181], off
	global_load_dwordx4 v[198:201], v[156:157], off offset:16
	global_load_dwordx4 v[202:205], v[156:157], off
	global_load_dwordx4 v[206:209], v[154:155], off offset:16
	global_load_dwordx4 v[210:213], v[154:155], off
	global_load_dwordx4 v[114:117], v[180:181], off offset:528
	global_load_dwordx4 v[134:137], v[180:181], off offset:512
	global_load_dwordx4 v[118:121], v[156:157], off offset:528
	global_load_dwordx4 v[126:129], v[156:157], off offset:512
	global_load_dwordx4 v[122:125], v[154:155], off offset:528
	global_load_dwordx4 v[130:133], v[154:155], off offset:512
	s_movk_i32 s1, 0x37c0
	v_and_or_b32 v159, v159, s1, v196
	v_lshlrev_b32_e32 v159, 1, v159
	s_waitcnt vmcnt(11)
	v_sub_f32_e32 v187, v187, v179
	s_waitcnt vmcnt(10)
	v_sub_f32_e32 v183, v193, v179
	v_sub_f32_e32 v182, v192, v179
	v_sub_f32_e32 v191, v191, v179
	v_sub_f32_e32 v190, v190, v179
	v_pk_mul_f32 v[190:191], v[0:1], v[190:191] op_sel_hi:[0,1]
	v_pk_mul_f32 v[182:183], v[0:1], v[182:183] op_sel_hi:[0,1]
	s_waitcnt vmcnt(6)
	v_pk_fma_f32 v[182:183], v[204:205], v[182:183], v[212:213]
	v_pk_fma_f32 v[190:191], v[202:203], v[190:191], v[210:211]
	v_pk_mul_f32 v[182:183], v[182:183], s[2:3] op_sel_hi:[1,0]
	v_pk_mul_f32 v[190:191], v[190:191], s[2:3] op_sel_hi:[1,0]
	v_pk_fma_f32 v[112:113], v[112:113], 0.5, v[182:183] op_sel_hi:[1,0,1]
	v_pk_fma_f32 v[110:111], v[110:111], 0.5, v[190:191] op_sel_hi:[1,0,1]
	v_add_f32_e32 v182, v112, v113
	v_add_f32_e32 v178, v110, v111
	v_add_f32_e32 v178, v178, v182
	v_mul_f32_e32 v182, v111, v111
	v_mul_f32_e32 v183, v113, v113
	v_fmac_f32_e32 v182, v110, v110
	v_fmac_f32_e32 v183, v112, v112
	v_add_f32_e32 v190, v182, v183
	v_sub_f32_e32 v183, v189, v179
	v_sub_f32_e32 v182, v188, v179
	v_sub_f32_e32 v186, v186, v179
	v_pk_mul_f32 v[186:187], v[0:1], v[186:187] op_sel_hi:[0,1]
	v_pk_mul_f32 v[182:183], v[0:1], v[182:183] op_sel_hi:[0,1]
	v_pk_fma_f32 v[182:183], v[200:201], v[182:183], v[208:209]
	v_pk_fma_f32 v[186:187], v[198:199], v[186:187], v[206:207]
	v_pk_mul_f32 v[182:183], v[182:183], s[2:3] op_sel_hi:[1,0]
	v_pk_mul_f32 v[186:187], v[186:187], s[2:3] op_sel_hi:[1,0]
	v_pk_fma_f32 v[108:109], v[108:109], 0.5, v[182:183] op_sel_hi:[1,0,1]
	v_pk_fma_f32 v[106:107], v[106:107], 0.5, v[186:187] op_sel_hi:[1,0,1]
	v_add_f32_e32 v183, v108, v109
	v_add_f32_e32 v182, v106, v107
	v_add_f32_e32 v178, 0, v178
	v_add_f32_e32 v182, v182, v183
	v_add_f32_e32 v178, v178, v182
	v_mul_f32_e32 v182, v107, v107
	v_mul_f32_e32 v183, v109, v109
	s_nop 0
	s_nop 1
	v_bfe_u32 v187, v227, 4, 1
	v_sub_u32_e32 v187, 0, v187
	v_lshlrev_b32_e32 v186, 4, v187
	v_lshl_add_u64 v[186:187], v[180:181], 0, v[186:187]
	v_permlane16_swap_b32_e32 v110, v106
	v_permlane16_swap_b32_e32 v111, v107
	v_permlane16_swap_b32_e32 v112, v108
	v_permlane16_swap_b32_e32 v113, v109
	global_store_dwordx4 v[186:187], v[110:113], off
	global_store_dwordx4 v[186:187], v[106:109], off offset:32
	s_nop 1
	v_permlane16_swap_b32_e32 v110, v106
	v_permlane16_swap_b32_e32 v111, v107
	v_permlane16_swap_b32_e32 v112, v108
	v_permlane16_swap_b32_e32 v113, v109
	v_fmac_f32_e32 v182, v106, v106
	v_fmac_f32_e32 v183, v108, v108
	v_cvt_pk_bf16_f32 v110, v110, v111
	v_cvt_pk_bf16_f32 v111, v112, v113
	v_cvt_pk_bf16_f32 v112, v106, v107
	v_cvt_pk_bf16_f32 v113, v108, v109
	s_waitcnt vmcnt(6)
	v_sub_f32_e32 v107, v137, v179
	v_sub_f32_e32 v106, v136, v179
	v_sub_f32_e32 v109, v135, v179
	v_sub_f32_e32 v108, v134, v179
	v_pk_mul_f32 v[108:109], v[0:1], v[108:109] op_sel_hi:[0,1]
	v_pk_mul_f32 v[106:107], v[0:1], v[106:107] op_sel_hi:[0,1]
	s_waitcnt vmcnt(2)
; __device__ __forceinline__ float xsum16(float v) { const auto r = __builtin_amdgcn_permlane16_swap(__float_as_uint(v), __float_as_uint(v), false, false); return __uint_as_float(r[0]) + __uint_as_float(r[1]); }
; __device__ __forceinline__ float xsum32(float v) { const auto r = __builtin_amdgcn_permlane32_swap(__float_as_uint(v), __float_as_uint(v), false, false); return __uint_as_float(r[0]) + __uint_as_float(r[1]); }
; __device__ __forceinline__ size_t blk_off(int r, int c, int K) { return (size_t)(r >> 8) * 256 * K + (size_t)(c >> 6) * (256 * 64) + (size_t)((r & 255) * 64 + (c & 63)); }
; __device__ __forceinline__ u32x4 pack8(const f32x4 a, const f32x4 b) { u32x4 w; w.x = cvt_pk_bf16(a[0], a[1]); w.y = cvt_pk_bf16(a[2], a[3]); w.z = cvt_pk_bf16(b[0], b[1]); w.w = cvt_pk_bf16(b[2], b[3]); return w; }
;     __device__ __forceinline__ void operator()(const f32x4 (&acc)[2][2][4][2], const pg8::Unit& u, int wr, int wc, int fr, int fq) const {
;     ...
;             for (int m = 0; m < 4; ++m) { const int row = row0 + ai * 128 + m * 16; const float mu = mu4[m], rs = rs4[m];
;                 f32x4 yv[2][2], gq[2][2], bq_[2][2];
; #pragma unroll
;                 for (int bj = 0; bj < 2; ++bj)
; #pragma unroll
;                     for (int n = 0; n < 2; ++n) { yv[bj][n] = *(const f32x4*)(Yin + (size_t)row * D_ + col0 + bj * 128 + 4 * n); gq[bj][n] = *(const f32x4*)(g + col0 + bj * 128 + 4 * n); bq_[bj][n] = *(const f32x4*)(b + col0 + bj * 128 + 4 * n); }
;                 asm volatile("" ::: "memory");
;                 float s1 = 0.f, s2 = 0.f;
; #pragma unroll
;                 for (int bj = 0; bj < 2; ++bj) { float* yp = Y + (size_t)row * D_ + col0 + bj * 128; f32x4 v[2];
; #pragma unroll
;                     for (int n = 0; n < 2; ++n) { v[n] = (((yv[bj][n] - mu) * rs) * gq[bj][n] + bq_[bj][n]) * ALPHA_ + acc[ai][bj][m][n] * sc;
;                         *(f32x4*)(yp + 4 * n) = v[n]; s1 += (v[n][0] + v[n][1]) + (v[n][2] + v[n][3]); s2 += (v[n][0] * v[n][0] + v[n][1] * v[n][1]) + (v[n][2] * v[n][2] + v[n][3] * v[n][3]); }
;                     *(u32x4*)(Yb + blk_off(row, col0 + bj * 128, D_)) = pack8(v[0], v[1]); }
;                 s1 = xsum32(xsum16(s1)); s2 = xsum32(xsum16(s2));
;                 if (fq == 0) *(f32x2*)(stn + (size_t)row * 32 + (u.pn * 4 + wc) * 2) = (f32x2){s1, s2}; asm volatile("" ::: "memory"); } }
	v_pk_fma_f32 v[106:107], v[128:129], v[106:107], v[132:133]
	v_pk_fma_f32 v[108:109], v[126:127], v[108:109], v[130:131]
	v_pk_mul_f32 v[106:107], v[106:107], s[2:3] op_sel_hi:[1,0]
	v_pk_mul_f32 v[108:109], v[108:109], s[2:3] op_sel_hi:[1,0]
	v_pk_fma_f32 v[104:105], v[104:105], 0.5, v[106:107] op_sel_hi:[1,0,1]
	v_pk_fma_f32 v[102:103], v[102:103], 0.5, v[108:109] op_sel_hi:[1,0,1]
	v_add_f32_e32 v107, v104, v105
	v_add_f32_e32 v106, v102, v103
	v_add_f32_e32 v106, v106, v107
	global_store_dwordx4 v159, v[110:113], s[48:49]
	v_mul_f32_e32 v107, v105, v105
	v_add_f32_e32 v182, v182, v183
	v_add_f32_e32 v110, v178, v106
	v_mul_f32_e32 v106, v103, v103
	v_fmac_f32_e32 v106, v102, v102
	v_fmac_f32_e32 v107, v104, v104
	v_add_f32_e32 v182, v190, v182
	v_add_f32_e32 v106, v106, v107
	v_add_f32_e32 v111, v182, v106
	v_sub_f32_e32 v107, v117, v179
	v_sub_f32_e32 v106, v116, v179
	v_sub_f32_e32 v109, v115, v179
	v_sub_f32_e32 v108, v114, v179
	v_pk_mul_f32 v[108:109], v[0:1], v[108:109] op_sel_hi:[0,1]
	v_pk_mul_f32 v[106:107], v[0:1], v[106:107] op_sel_hi:[0,1]
	v_pk_fma_f32 v[106:107], v[120:121], v[106:107], v[124:125]
	v_pk_fma_f32 v[108:109], v[118:119], v[108:109], v[122:123]
	v_pk_mul_f32 v[106:107], v[106:107], s[2:3] op_sel_hi:[1,0]
	v_pk_mul_f32 v[108:109], v[108:109], s[2:3] op_sel_hi:[1,0]
	v_pk_fma_f32 v[100:101], v[100:101], 0.5, v[106:107] op_sel_hi:[1,0,1]
	v_pk_fma_f32 v[98:99], v[98:99], 0.5, v[108:109] op_sel_hi:[1,0,1]
	v_add_f32_e32 v106, v100, v101
	v_add_f32_e32 v0, v98, v99
	v_add_f32_e32 v0, v0, v106
	v_mul_f32_e32 v106, v99, v99
	v_mul_f32_e32 v107, v101, v101
	v_add_f32_e32 v0, v110, v0
	v_fmac_f32_e32 v106, v98, v98
	v_fmac_f32_e32 v107, v100, v100
	s_nop 0
	s_nop 1
	v_bfe_u32 v109, v227, 4, 1
	v_sub_u32_e32 v109, 0, v109
	v_lshlrev_b32_e32 v108, 4, v109
	v_lshl_add_u64 v[108:109], v[180:181], 0, v[108:109]
	v_permlane16_swap_b32_e32 v102, v98
	v_permlane16_swap_b32_e32 v103, v99
	v_permlane16_swap_b32_e32 v104, v100
	v_permlane16_swap_b32_e32 v105, v101
	global_store_dwordx4 v[108:109], v[102:105], off offset:512
	global_store_dwordx4 v[108:109], v[98:101], off offset:544
	s_nop 1
	v_permlane16_swap_b32_e32 v102, v98
	v_permlane16_swap_b32_e32 v103, v99
	v_permlane16_swap_b32_e32 v104, v100
	v_permlane16_swap_b32_e32 v105, v101
	v_add_f32_e32 v106, v106, v107
	v_cvt_pk_bf16_f32 v102, v102, v103
	v_cvt_pk_bf16_f32 v103, v104, v105
	v_cvt_pk_bf16_f32 v104, v98, v99
	v_mov_b32_e32 v98, v0
	v_add_f32_e32 v106, v111, v106
	s_nop 0
	v_permlane16_swap_b32_e32 v0, v98
	v_add_f32_e32 v98, v0, v98
	v_mov_b32_e32 v0, v106
	s_nop 1
	v_permlane16_swap_b32_e32 v106, v0
	v_add_f32_e32 v99, v106, v0
	v_cvt_pk_bf16_f32 v105, v100, v101
	v_mov_b32_e32 v100, v98
	v_mov_b32_e32 v101, v99
	s_nop 0
	v_permlane32_swap_b32_e32 v98, v100
	v_permlane32_swap_b32_e32 v99, v101
	global_store_dwordx4 v159, v[102:105], s[46:47]
	s_and_saveexec_b64 s[26:27], s[40:41]
	s_cbranch_execz .LBB0_1707
	v_pk_add_f32 v[98:99], v[98:99], v[100:101]
	v_lshl_add_u64 v[100:101], s[8:9], 0, v[172:173]
	v_lshl_add_u64 v[100:101], s[38:39], 2, v[100:101]
	global_store_dwordx2 v[100:101], v[98:99], off
.LBB0_1707:
	s_or_b64 exec, exec, s[26:27]
	v_pk_add_f32 v[98:99], v[174:175], v[176:177]
	s_mov_b32 s2, 0x3a800000
	v_pk_mul_f32 v[122:123], v[98:99], s[2:3] op_sel_hi:[1,0]
	s_mov_b32 s1, 0x800000
	v_fma_f32 v0, -v123, v123, v122
	v_max_f32_e32 v0, 0, v0
	v_add_f32_e32 v0, 0x3727c5ac, v0
	v_cmp_gt_f32_e32 vcc, s1, v0
	v_mul_f32_e32 v98, 0x4b800000, v0
	s_load_dwordx16 s[60:75], s[34:35], 0x38
	v_cndmask_b32_e32 v0, v0, v98, vcc
	v_rsq_f32_e32 v0, v0
	s_mov_b32 s2, 0x3fd744fd
	v_lshlrev_b32_e32 v122, 6, v170
	v_mul_f32_e32 v98, 0x45800000, v0
	v_cndmask_b32_e32 v0, v0, v98, vcc
	v_lshlrev_b64 v[98:99], 12, v[170:171]
	s_waitcnt lgkmcnt(0)
	v_lshl_add_u64 v[98:99], s[74:75], 0, v[98:99]
	v_lshl_add_u64 v[124:125], v[152:153], 2, v[98:99]
	global_load_dwordx4 v[126:129], v[124:125], off offset:16
	global_load_dwordx4 v[130:133], v[124:125], off
	global_load_dwordx4 v[134:137], v[156:157], off offset:16
	global_load_dwordx4 v[172:175], v[156:157], off
	global_load_dwordx4 v[176:179], v[154:155], off offset:16
	global_load_dwordx4 v[180:183], v[154:155], off
	global_load_dwordx4 v[98:101], v[124:125], off offset:528
	global_load_dwordx4 v[118:121], v[124:125], off offset:512
	global_load_dwordx4 v[102:105], v[156:157], off offset:528
	global_load_dwordx4 v[110:113], v[156:157], off offset:512
	global_load_dwordx4 v[106:109], v[154:155], off offset:528
	global_load_dwordx4 v[114:117], v[154:155], off offset:512
	s_movk_i32 s1, 0x3bc0
	v_and_or_b32 v122, v122, s1, v196
	v_lshlrev_b32_e32 v122, 1, v122
	s_waitcnt vmcnt(11)
	v_sub_f32_e32 v129, v129, v123
	s_waitcnt vmcnt(10)
	v_sub_f32_e32 v133, v133, v123
	v_sub_f32_e32 v132, v132, v123
	v_sub_f32_e32 v131, v131, v123
	v_sub_f32_e32 v130, v130, v123
	v_sub_f32_e32 v128, v128, v123
	v_sub_f32_e32 v127, v127, v123
	v_sub_f32_e32 v126, v126, v123
	v_pk_mul_f32 v[130:131], v[0:1], v[130:131] op_sel_hi:[0,1]
	v_pk_mul_f32 v[132:133], v[0:1], v[132:133] op_sel_hi:[0,1]
	v_pk_mul_f32 v[126:127], v[0:1], v[126:127] op_sel_hi:[0,1]
	v_pk_mul_f32 v[128:129], v[0:1], v[128:129] op_sel_hi:[0,1]
	s_waitcnt vmcnt(6)
; __device__ __forceinline__ float xsum16(float v) { const auto r = __builtin_amdgcn_permlane16_swap(__float_as_uint(v), __float_as_uint(v), false, false); return __uint_as_float(r[0]) + __uint_as_float(r[1]); }
; __device__ __forceinline__ float xsum32(float v) { const auto r = __builtin_amdgcn_permlane32_swap(__float_as_uint(v), __float_as_uint(v), false, false); return __uint_as_float(r[0]) + __uint_as_float(r[1]); }
; __device__ __forceinline__ size_t blk_off(int r, int c, int K) { return (size_t)(r >> 8) * 256 * K + (size_t)(c >> 6) * (256 * 64) + (size_t)((r & 255) * 64 + (c & 63)); }
; __device__ __forceinline__ u32x4 pack8(const f32x4 a, const f32x4 b) { u32x4 w; w.x = cvt_pk_bf16(a[0], a[1]); w.y = cvt_pk_bf16(a[2], a[3]); w.z = cvt_pk_bf16(b[0], b[1]); w.w = cvt_pk_bf16(b[2], b[3]); return w; }
;     __device__ __forceinline__ void operator()(const f32x4 (&acc)[2][2][4][2], const pg8::Unit& u, int wr, int wc, int fr, int fq) const {
;     ...
;             for (int m = 0; m < 4; ++m) { const int row = row0 + ai * 128 + m * 16; const float mu = mu4[m], rs = rs4[m];
;                 f32x4 yv[2][2], gq[2][2], bq_[2][2];
; #pragma unroll
;                 for (int bj = 0; bj < 2; ++bj)
; #pragma unroll
;                     for (int n = 0; n < 2; ++n) { yv[bj][n] = *(const f32x4*)(Yin + (size_t)row * D_ + col0 + bj * 128 + 4 * n); gq[bj][n] = *(const f32x4*)(g + col0 + bj * 128 + 4 * n); bq_[bj][n] = *(const f32x4*)(b + col0 + bj * 128 + 4 * n); }
;                 asm volatile("" ::: "memory");
;                 float s1 = 0.f, s2 = 0.f;
; #pragma unroll
;                 for (int bj = 0; bj < 2; ++bj) { float* yp = Y + (size_t)row * D_ + col0 + bj * 128; f32x4 v[2];
; #pragma unroll
;                     for (int n = 0; n < 2; ++n) { v[n] = (((yv[bj][n] - mu) * rs) * gq[bj][n] + bq_[bj][n]) * ALPHA_ + acc[ai][bj][m][n] * sc;
;                         *(f32x4*)(yp + 4 * n) = v[n]; s1 += (v[n][0] + v[n][1]) + (v[n][2] + v[n][3]); s2 += (v[n][0] * v[n][0] + v[n][1] * v[n][1]) + (v[n][2] * v[n][2] + v[n][3] * v[n][3]); }
;                     *(u32x4*)(Yb + blk_off(row, col0 + bj * 128, D_)) = pack8(v[0], v[1]); }
;                 s1 = xsum32(xsum16(s1)); s2 = xsum32(xsum16(s2));
;                 if (fq == 0) *(f32x2*)(stn + (size_t)row * 32 + (u.pn * 4 + wc) * 2) = (f32x2){s1, s2}; asm volatile("" ::: "memory"); } }
	v_pk_fma_f32 v[132:133], v[174:175], v[132:133], v[182:183]
	v_pk_fma_f32 v[130:131], v[172:173], v[130:131], v[180:181]
	v_pk_fma_f32 v[128:129], v[136:137], v[128:129], v[178:179]
	v_pk_fma_f32 v[126:127], v[134:135], v[126:127], v[176:177]
	v_pk_mul_f32 v[130:131], v[130:131], s[2:3] op_sel_hi:[1,0]
	v_pk_mul_f32 v[132:133], v[132:133], s[2:3] op_sel_hi:[1,0]
	v_pk_mul_f32 v[126:127], v[126:127], s[2:3] op_sel_hi:[1,0]
	v_pk_mul_f32 v[128:129], v[128:129], s[2:3] op_sel_hi:[1,0]
	v_pk_fma_f32 v[96:97], v[96:97], 0.5, v[132:133] op_sel_hi:[1,0,1]
	v_pk_fma_f32 v[94:95], v[94:95], 0.5, v[130:131] op_sel_hi:[1,0,1]
	v_pk_fma_f32 v[92:93], v[92:93], 0.5, v[128:129] op_sel_hi:[1,0,1]
	v_pk_fma_f32 v[90:91], v[90:91], 0.5, v[126:127] op_sel_hi:[1,0,1]
	v_add_f32_e32 v130, v94, v95
	v_add_f32_e32 v131, v96, v97
	v_add_f32_e32 v126, v90, v91
	v_add_f32_e32 v127, v92, v93
	v_add_f32_e32 v130, v130, v131
	v_mul_f32_e32 v131, v95, v95
	v_mul_f32_e32 v132, v97, v97
	v_add_f32_e32 v126, v126, v127
	v_mul_f32_e32 v127, v91, v91
	v_mul_f32_e32 v128, v93, v93
	s_nop 0
	v_fmac_f32_e32 v131, v94, v94
	v_fmac_f32_e32 v132, v96, v96
	s_nop 1
	v_bfe_u32 v135, v227, 4, 1
	v_sub_u32_e32 v135, 0, v135
	v_lshlrev_b32_e32 v134, 4, v135
	v_lshl_add_u64 v[134:135], v[124:125], 0, v[134:135]
	v_permlane16_swap_b32_e32 v94, v90
	v_permlane16_swap_b32_e32 v95, v91
	v_permlane16_swap_b32_e32 v96, v92
	v_permlane16_swap_b32_e32 v97, v93
	global_store_dwordx4 v[134:135], v[94:97], off
	global_store_dwordx4 v[134:135], v[90:93], off offset:32
	s_nop 1
	v_permlane16_swap_b32_e32 v94, v90
	v_permlane16_swap_b32_e32 v95, v91
	v_permlane16_swap_b32_e32 v96, v92
	v_permlane16_swap_b32_e32 v97, v93
	v_fmac_f32_e32 v127, v90, v90
	v_fmac_f32_e32 v128, v92, v92
	v_cvt_pk_bf16_f32 v94, v94, v95
	v_cvt_pk_bf16_f32 v95, v96, v97
	v_cvt_pk_bf16_f32 v96, v90, v91
	v_cvt_pk_bf16_f32 v97, v92, v93
	s_waitcnt vmcnt(6)
	v_sub_f32_e32 v91, v121, v123
	v_sub_f32_e32 v90, v120, v123
	v_sub_f32_e32 v93, v119, v123
	v_sub_f32_e32 v92, v118, v123
	v_pk_mul_f32 v[92:93], v[0:1], v[92:93] op_sel_hi:[0,1]
	v_pk_mul_f32 v[90:91], v[0:1], v[90:91] op_sel_hi:[0,1]
	s_waitcnt vmcnt(2)
	v_pk_fma_f32 v[90:91], v[112:113], v[90:91], v[116:117]
	v_pk_fma_f32 v[92:93], v[110:111], v[92:93], v[114:115]
	v_pk_mul_f32 v[90:91], v[90:91], s[2:3] op_sel_hi:[1,0]
	v_pk_mul_f32 v[92:93], v[92:93], s[2:3] op_sel_hi:[1,0]
	v_pk_fma_f32 v[88:89], v[88:89], 0.5, v[90:91] op_sel_hi:[1,0,1]
	v_pk_fma_f32 v[86:87], v[86:87], 0.5, v[92:93] op_sel_hi:[1,0,1]
	v_add_f32_e32 v130, 0, v130
	v_add_f32_e32 v90, v86, v87
	v_add_f32_e32 v91, v88, v89
	v_add_f32_e32 v126, v130, v126
	v_add_f32_e32 v90, v90, v91
	global_store_dwordx4 v122, v[94:97], s[48:49]
	v_mul_f32_e32 v91, v89, v89
	v_add_f32_e32 v131, v131, v132
	v_add_f32_e32 v94, v126, v90
	v_mul_f32_e32 v90, v87, v87
	v_add_f32_e32 v127, v127, v128
	v_fmac_f32_e32 v90, v86, v86
	v_fmac_f32_e32 v91, v88, v88
	v_add_f32_e32 v127, v131, v127
	v_add_f32_e32 v90, v90, v91
	v_add_f32_e32 v95, v127, v90
	v_sub_f32_e32 v91, v101, v123
	v_sub_f32_e32 v90, v100, v123
	v_sub_f32_e32 v93, v99, v123
	v_sub_f32_e32 v92, v98, v123
	v_pk_mul_f32 v[92:93], v[0:1], v[92:93] op_sel_hi:[0,1]
	v_pk_mul_f32 v[90:91], v[0:1], v[90:91] op_sel_hi:[0,1]
	v_pk_fma_f32 v[90:91], v[104:105], v[90:91], v[108:109]
	v_pk_fma_f32 v[92:93], v[102:103], v[92:93], v[106:107]
	v_pk_mul_f32 v[90:91], v[90:91], s[2:3] op_sel_hi:[1,0]
	v_pk_mul_f32 v[92:93], v[92:93], s[2:3] op_sel_hi:[1,0]
	v_pk_fma_f32 v[84:85], v[84:85], 0.5, v[90:91] op_sel_hi:[1,0,1]
	v_pk_fma_f32 v[82:83], v[82:83], 0.5, v[92:93] op_sel_hi:[1,0,1]
	v_add_f32_e32 v90, v84, v85
	v_add_f32_e32 v0, v82, v83
	v_add_f32_e32 v0, v0, v90
	v_mul_f32_e32 v90, v83, v83
	v_mul_f32_e32 v91, v85, v85
	v_add_f32_e32 v0, v94, v0
	v_fmac_f32_e32 v90, v82, v82
	v_fmac_f32_e32 v91, v84, v84
	s_nop 0
	s_nop 1
	v_bfe_u32 v93, v227, 4, 1
	v_sub_u32_e32 v93, 0, v93
	v_lshlrev_b32_e32 v92, 4, v93
	v_lshl_add_u64 v[92:93], v[124:125], 0, v[92:93]
	v_permlane16_swap_b32_e32 v86, v82
	v_permlane16_swap_b32_e32 v87, v83
	v_permlane16_swap_b32_e32 v88, v84
	v_permlane16_swap_b32_e32 v89, v85
	global_store_dwordx4 v[92:93], v[86:89], off offset:512
	global_store_dwordx4 v[92:93], v[82:85], off offset:544
	s_nop 1
	v_permlane16_swap_b32_e32 v86, v82
	v_permlane16_swap_b32_e32 v87, v83
	v_permlane16_swap_b32_e32 v88, v84
	v_permlane16_swap_b32_e32 v89, v85
	v_add_f32_e32 v90, v90, v91
	v_cvt_pk_bf16_f32 v86, v86, v87
	v_cvt_pk_bf16_f32 v87, v88, v89
	v_cvt_pk_bf16_f32 v88, v82, v83
	v_mov_b32_e32 v82, v0
	v_add_f32_e32 v90, v95, v90
	s_nop 0
	v_permlane16_swap_b32_e32 v0, v82
	v_add_f32_e32 v82, v0, v82
	v_mov_b32_e32 v0, v90
	s_nop 1
	v_permlane16_swap_b32_e32 v90, v0
	v_add_f32_e32 v83, v90, v0
	v_cvt_pk_bf16_f32 v89, v84, v85
	v_mov_b32_e32 v84, v82
	v_mov_b32_e32 v85, v83
	s_nop 0
	v_permlane32_swap_b32_e32 v82, v84
	v_permlane32_swap_b32_e32 v83, v85
	global_store_dwordx4 v122, v[86:89], s[46:47]
	s_and_saveexec_b64 s[26:27], s[40:41]
	s_cbranch_execz .LBB0_1709
	v_pk_add_f32 v[82:83], v[82:83], v[84:85]
	v_lshl_add_u64 v[84:85], s[8:9], 0, v[164:165]
	v_lshl_add_u64 v[84:85], s[38:39], 2, v[84:85]
	global_store_dwordx2 v[84:85], v[82:83], off
; __device__ __forceinline__ size_t blk_off(int r, int c, int K) { return (size_t)(r >> 8) * 256 * K + (size_t)(c >> 6) * (256 * 64) + (size_t)((r & 255) * 64 + (c & 63)); }
; __device__ __forceinline__ u32x4 pack8(const f32x4 a, const f32x4 b) { u32x4 w; w.x = cvt_pk_bf16(a[0], a[1]); w.y = cvt_pk_bf16(a[2], a[3]); w.z = cvt_pk_bf16(b[0], b[1]); w.w = cvt_pk_bf16(b[2], b[3]); return w; }
;     __device__ __forceinline__ void operator()(const f32x4 (&acc)[2][2][4][2], const pg8::Unit& u, int wr, int wc, int fr, int fq) const {
;     ...
;             for (int m = 0; m < 4; ++m) { const int row = row0 + ai * 128 + m * 16; const float mu = mu4[m], rs = rs4[m];
;                 f32x4 yv[2][2], gq[2][2], bq_[2][2];
; #pragma unroll
;                 for (int bj = 0; bj < 2; ++bj)
; #pragma unroll
;                     for (int n = 0; n < 2; ++n) { yv[bj][n] = *(const f32x4*)(Yin + (size_t)row * D_ + col0 + bj * 128 + 4 * n); gq[bj][n] = *(const f32x4*)(g + col0 + bj * 128 + 4 * n); bq_[bj][n] = *(const f32x4*)(b + col0 + bj * 128 + 4 * n); }
;                 asm volatile("" ::: "memory");
;                 float s1 = 0.f, s2 = 0.f;
; #pragma unroll
;                 for (int bj = 0; bj < 2; ++bj) { float* yp = Y + (size_t)row * D_ + col0 + bj * 128; f32x4 v[2];
; #pragma unroll
;                     for (int n = 0; n < 2; ++n) { v[n] = (((yv[bj][n] - mu) * rs) * gq[bj][n] + bq_[bj][n]) * ALPHA_ + acc[ai][bj][m][n] * sc;
;                         *(f32x4*)(yp + 4 * n) = v[n]; s1 += (v[n][0] + v[n][1]) + (v[n][2] + v[n][3]); s2 += (v[n][0] * v[n][0] + v[n][1] * v[n][1]) + (v[n][2] * v[n][2] + v[n][3] * v[n][3]); }
;                     *(u32x4*)(Yb + blk_off(row, col0 + bj * 128, D_)) = pack8(v[0], v[1]); }
.LBB0_1709:
	s_or_b64 exec, exec, s[26:27]
	v_pk_add_f32 v[82:83], v[166:167], v[168:169]
	s_mov_b32 s2, 0x3a800000
	v_pk_mul_f32 v[106:107], v[82:83], s[2:3] op_sel_hi:[1,0]
	s_mov_b32 s1, 0x800000
	v_fma_f32 v0, -v107, v107, v106
	v_max_f32_e32 v0, 0, v0
	v_add_f32_e32 v0, 0x3727c5ac, v0
	v_cmp_gt_f32_e32 vcc, s1, v0
	v_mul_f32_e32 v82, 0x4b800000, v0
	s_load_dwordx16 s[60:75], s[34:35], 0x38
	v_cndmask_b32_e32 v0, v0, v82, vcc
	v_rsq_f32_e32 v0, v0
	s_mov_b32 s2, 0x3fd744fd
	v_lshlrev_b32_e32 v106, 6, v162
	v_mul_f32_e32 v82, 0x45800000, v0
	v_cndmask_b32_e32 v0, v0, v82, vcc
	v_lshlrev_b64 v[82:83], 12, v[162:163]
	s_waitcnt lgkmcnt(0)
	v_lshl_add_u64 v[82:83], s[74:75], 0, v[82:83]
	v_lshl_add_u64 v[108:109], v[152:153], 2, v[82:83]
	global_load_dwordx4 v[110:113], v[108:109], off offset:16
	global_load_dwordx4 v[114:117], v[108:109], off
	global_load_dwordx4 v[118:121], v[156:157], off offset:16
	global_load_dwordx4 v[122:125], v[156:157], off
	global_load_dwordx4 v[126:129], v[154:155], off offset:16
	global_load_dwordx4 v[130:133], v[154:155], off
	global_load_dwordx4 v[82:85], v[108:109], off offset:528
	global_load_dwordx4 v[102:105], v[108:109], off offset:512
	global_load_dwordx4 v[86:89], v[156:157], off offset:528
	global_load_dwordx4 v[94:97], v[156:157], off offset:512
	global_load_dwordx4 v[90:93], v[154:155], off offset:528
	global_load_dwordx4 v[98:101], v[154:155], off offset:512
	s_movk_i32 s1, 0x3fc0
	v_and_or_b32 v106, v106, s1, v196
	v_lshlrev_b32_e32 v106, 1, v106
	s_waitcnt vmcnt(11)
	v_sub_f32_e32 v113, v113, v107
	s_waitcnt vmcnt(10)
	v_sub_f32_e32 v117, v117, v107
	v_sub_f32_e32 v116, v116, v107
	v_sub_f32_e32 v115, v115, v107
	v_sub_f32_e32 v114, v114, v107
	v_sub_f32_e32 v112, v112, v107
	v_sub_f32_e32 v111, v111, v107
	v_sub_f32_e32 v110, v110, v107
	v_pk_mul_f32 v[114:115], v[0:1], v[114:115] op_sel_hi:[0,1]
	v_pk_mul_f32 v[116:117], v[0:1], v[116:117] op_sel_hi:[0,1]
	v_pk_mul_f32 v[110:111], v[0:1], v[110:111] op_sel_hi:[0,1]
	v_pk_mul_f32 v[112:113], v[0:1], v[112:113] op_sel_hi:[0,1]
	s_waitcnt vmcnt(6)
	v_pk_fma_f32 v[116:117], v[124:125], v[116:117], v[132:133]
	v_pk_fma_f32 v[114:115], v[122:123], v[114:115], v[130:131]
	v_pk_fma_f32 v[112:113], v[120:121], v[112:113], v[128:129]
	v_pk_fma_f32 v[110:111], v[118:119], v[110:111], v[126:127]
	v_pk_mul_f32 v[114:115], v[114:115], s[2:3] op_sel_hi:[1,0]
	v_pk_mul_f32 v[116:117], v[116:117], s[2:3] op_sel_hi:[1,0]
	v_pk_mul_f32 v[110:111], v[110:111], s[2:3] op_sel_hi:[1,0]
	v_pk_mul_f32 v[112:113], v[112:113], s[2:3] op_sel_hi:[1,0]
	v_pk_fma_f32 v[80:81], v[80:81], 0.5, v[116:117] op_sel_hi:[1,0,1]
	v_pk_fma_f32 v[78:79], v[78:79], 0.5, v[114:115] op_sel_hi:[1,0,1]
	v_pk_fma_f32 v[76:77], v[76:77], 0.5, v[112:113] op_sel_hi:[1,0,1]
	v_pk_fma_f32 v[74:75], v[74:75], 0.5, v[110:111] op_sel_hi:[1,0,1]
	v_add_f32_e32 v114, v78, v79
	v_add_f32_e32 v115, v80, v81
	v_add_f32_e32 v110, v74, v75
	v_add_f32_e32 v111, v76, v77
	v_add_f32_e32 v114, v114, v115
	v_mul_f32_e32 v115, v79, v79
	v_mul_f32_e32 v116, v81, v81
	v_add_f32_e32 v110, v110, v111
	v_mul_f32_e32 v111, v75, v75
	v_mul_f32_e32 v112, v77, v77
	s_nop 0
	v_fmac_f32_e32 v115, v78, v78
	v_fmac_f32_e32 v116, v80, v80
	s_nop 1
	v_bfe_u32 v119, v227, 4, 1
	v_sub_u32_e32 v119, 0, v119
	v_lshlrev_b32_e32 v118, 4, v119
	v_lshl_add_u64 v[118:119], v[108:109], 0, v[118:119]
	v_permlane16_swap_b32_e32 v78, v74
	v_permlane16_swap_b32_e32 v79, v75
	v_permlane16_swap_b32_e32 v80, v76
	v_permlane16_swap_b32_e32 v81, v77
	global_store_dwordx4 v[118:119], v[78:81], off
	global_store_dwordx4 v[118:119], v[74:77], off offset:32
	s_nop 1
	v_permlane16_swap_b32_e32 v78, v74
	v_permlane16_swap_b32_e32 v79, v75
	v_permlane16_swap_b32_e32 v80, v76
	v_permlane16_swap_b32_e32 v81, v77
	v_fmac_f32_e32 v111, v74, v74
	v_fmac_f32_e32 v112, v76, v76
	v_cvt_pk_bf16_f32 v78, v78, v79
	v_cvt_pk_bf16_f32 v79, v80, v81
	v_cvt_pk_bf16_f32 v80, v74, v75
	v_cvt_pk_bf16_f32 v81, v76, v77
	s_waitcnt vmcnt(6)
	v_sub_f32_e32 v75, v105, v107
	v_sub_f32_e32 v74, v104, v107
	v_sub_f32_e32 v77, v103, v107
	v_sub_f32_e32 v76, v102, v107
	v_pk_mul_f32 v[76:77], v[0:1], v[76:77] op_sel_hi:[0,1]
	v_pk_mul_f32 v[74:75], v[0:1], v[74:75] op_sel_hi:[0,1]
	s_waitcnt vmcnt(2)
; __device__ __forceinline__ void row_stats4(const float* st, int rowb, int fq, float (&mu)[4], float (&rs)[4]) {
;     f32x4 a[4], b[4];
; #pragma unroll
;     for (int m = 0; m < 4; ++m) { const f32x4* p = (const f32x4*)(st + (size_t)(rowb + m * 16) * 32 + fq * 8); a[m] = p[0]; b[m] = p[1]; }
; #pragma unroll
;     for (int m = 0; m < 4; ++m) { float s1 = (a[m][0] + a[m][2]) + (b[m][0] + b[m][2]), s2 = (a[m][1] + a[m][3]) + (b[m][1] + b[m][3]);
;         s1 = xsum32(xsum16(s1)); s2 = xsum32(xsum16(s2));
;         const float mm = s1 * (1.0f / 1024.0f); mu[m] = mm; rs[m] = rsqrtf(fmaxf(s2 * (1.0f / 1024.0f) - mm * mm, 0.f) + LN_EPS_); }
;     asm volatile("" ::: "memory");
; }
;     __device__ __forceinline__ void operator()(const f32x4 (&acc)[2][2][4][2], const pg8::Unit& u, int wr, int wc, int fr, int fq) const {
;     ...
;             for (int m = 0; m < 4; ++m) { const int row = row0 + ai * 128 + m * 16; const float mu = mu4[m], rs = rs4[m];
;                 f32x4 yv[2][2], gq[2][2], bq_[2][2];
; #pragma unroll
;                 for (int bj = 0; bj < 2; ++bj)
; #pragma unroll
;                     for (int n = 0; n < 2; ++n) { yv[bj][n] = *(const f32x4*)(Yin + (size_t)row * D_ + col0 + bj * 128 + 4 * n); gq[bj][n] = *(const f32x4*)(g + col0 + bj * 128 + 4 * n); bq_[bj][n] = *(const f32x4*)(b + col0 + bj * 128 + 4 * n); }
;                 asm volatile("" ::: "memory");
;                 float s1 = 0.f, s2 = 0.f;
; #pragma unroll
;                 for (int bj = 0; bj < 2; ++bj) { float* yp = Y + (size_t)row * D_ + col0 + bj * 128; f32x4 v[2];
; #pragma unroll
;                     for (int n = 0; n < 2; ++n) { v[n] = (((yv[bj][n] - mu) * rs) * gq[bj][n] + bq_[bj][n]) * ALPHA_ + acc[ai][bj][m][n] * sc;
;                         *(f32x4*)(yp + 4 * n) = v[n]; s1 += (v[n][0] + v[n][1]) + (v[n][2] + v[n][3]); s2 += (v[n][0] * v[n][0] + v[n][1] * v[n][1]) + (v[n][2] * v[n][2] + v[n][3] * v[n][3]); }
;                     *(u32x4*)(Yb + blk_off(row, col0 + bj * 128, D_)) = pack8(v[0], v[1]); }
;                 s1 = xsum32(xsum16(s1)); s2 = xsum32(xsum16(s2));
;                 if (fq == 0) *(f32x2*)(stn + (size_t)row * 32 + (u.pn * 4 + wc) * 2) = (f32x2){s1, s2}; asm volatile("" ::: "memory"); } }
	v_pk_fma_f32 v[74:75], v[96:97], v[74:75], v[100:101]
	v_pk_fma_f32 v[76:77], v[94:95], v[76:77], v[98:99]
	v_pk_mul_f32 v[74:75], v[74:75], s[2:3] op_sel_hi:[1,0]
	v_pk_mul_f32 v[76:77], v[76:77], s[2:3] op_sel_hi:[1,0]
	v_pk_fma_f32 v[72:73], v[72:73], 0.5, v[74:75] op_sel_hi:[1,0,1]
	v_pk_fma_f32 v[70:71], v[70:71], 0.5, v[76:77] op_sel_hi:[1,0,1]
	v_add_f32_e32 v114, 0, v114
	v_add_f32_e32 v74, v70, v71
	v_add_f32_e32 v75, v72, v73
	v_add_f32_e32 v110, v114, v110
	v_add_f32_e32 v74, v74, v75
	global_store_dwordx4 v106, v[78:81], s[48:49]
	v_mul_f32_e32 v75, v73, v73
	v_add_f32_e32 v115, v115, v116
	v_add_f32_e32 v78, v110, v74
	v_mul_f32_e32 v74, v71, v71
	v_add_f32_e32 v111, v111, v112
	v_fmac_f32_e32 v74, v70, v70
	v_fmac_f32_e32 v75, v72, v72
	v_add_f32_e32 v111, v115, v111
	v_add_f32_e32 v74, v74, v75
	v_add_f32_e32 v79, v111, v74
	v_sub_f32_e32 v75, v85, v107
	v_sub_f32_e32 v74, v84, v107
	v_sub_f32_e32 v77, v83, v107
	v_sub_f32_e32 v76, v82, v107
	v_pk_mul_f32 v[76:77], v[0:1], v[76:77] op_sel_hi:[0,1]
	v_pk_mul_f32 v[74:75], v[0:1], v[74:75] op_sel_hi:[0,1]
	v_pk_fma_f32 v[74:75], v[88:89], v[74:75], v[92:93]
	v_pk_fma_f32 v[76:77], v[86:87], v[76:77], v[90:91]
	v_pk_mul_f32 v[74:75], v[74:75], s[2:3] op_sel_hi:[1,0]
	v_pk_mul_f32 v[76:77], v[76:77], s[2:3] op_sel_hi:[1,0]
	v_pk_fma_f32 v[68:69], v[68:69], 0.5, v[74:75] op_sel_hi:[1,0,1]
	v_pk_fma_f32 v[66:67], v[66:67], 0.5, v[76:77] op_sel_hi:[1,0,1]
	v_add_f32_e32 v74, v68, v69
	v_add_f32_e32 v0, v66, v67
	v_add_f32_e32 v0, v0, v74
	v_mul_f32_e32 v74, v67, v67
	v_mul_f32_e32 v75, v69, v69
	v_add_f32_e32 v0, v78, v0
	v_fmac_f32_e32 v74, v66, v66
	v_fmac_f32_e32 v75, v68, v68
	s_nop 0
	s_nop 1
	v_bfe_u32 v77, v227, 4, 1
	v_sub_u32_e32 v77, 0, v77
	v_lshlrev_b32_e32 v76, 4, v77
	v_lshl_add_u64 v[76:77], v[108:109], 0, v[76:77]
	v_permlane16_swap_b32_e32 v70, v66
	v_permlane16_swap_b32_e32 v71, v67
	v_permlane16_swap_b32_e32 v72, v68
	v_permlane16_swap_b32_e32 v73, v69
	global_store_dwordx4 v[76:77], v[70:73], off offset:512
	global_store_dwordx4 v[76:77], v[66:69], off offset:544
	s_nop 1
	v_permlane16_swap_b32_e32 v70, v66
	v_permlane16_swap_b32_e32 v71, v67
	v_permlane16_swap_b32_e32 v72, v68
	v_permlane16_swap_b32_e32 v73, v69
	v_add_f32_e32 v74, v74, v75
	v_cvt_pk_bf16_f32 v70, v70, v71
	v_cvt_pk_bf16_f32 v71, v72, v73
	v_cvt_pk_bf16_f32 v72, v66, v67
	v_mov_b32_e32 v66, v0
	v_add_f32_e32 v74, v79, v74
	s_nop 0
	v_permlane16_swap_b32_e32 v0, v66
	v_add_f32_e32 v66, v0, v66
	v_mov_b32_e32 v0, v74
	s_nop 1
	v_permlane16_swap_b32_e32 v74, v0
	v_add_f32_e32 v67, v74, v0
	v_cvt_pk_bf16_f32 v73, v68, v69
	v_mov_b32_e32 v68, v66
	v_mov_b32_e32 v69, v67
	s_nop 0
	v_permlane32_swap_b32_e32 v66, v68
	v_permlane32_swap_b32_e32 v67, v69
	global_store_dwordx4 v106, v[70:73], s[46:47]
	s_and_saveexec_b64 s[26:27], s[40:41]
	s_cbranch_execz .LBB0_1711
	v_pk_add_f32 v[66:67], v[66:67], v[68:69]
	v_lshl_add_u64 v[68:69], s[8:9], 0, v[160:161]
	v_lshl_add_u64 v[68:69], s[38:39], 2, v[68:69]
	global_store_dwordx2 v[68:69], v[66:67], off
.LBB0_1711:
	s_or_b64 exec, exec, s[26:27]
	v_add_u32_e32 v68, 0x80, v158
	v_ashrrev_i32_e32 v69, 31, v68
	v_lshlrev_b64 v[66:67], 7, v[68:69]
	v_lshl_add_u64 v[74:75], v[146:147], 0, v[66:67]
	v_add_u32_e32 v96, 0x90, v158
	global_load_dwordx4 v[70:73], v[74:75], off
	global_load_dwordx4 v[82:85], v[74:75], off offset:16
	v_ashrrev_i32_e32 v97, 31, v96
	v_lshlrev_b64 v[86:87], 7, v[96:97]
	v_add_u32_e32 v80, 0xa0, v158
	v_lshl_add_u64 v[74:75], v[146:147], 0, v[86:87]
	v_ashrrev_i32_e32 v81, 31, v80
	global_load_dwordx4 v[88:91], v[74:75], off
	global_load_dwordx4 v[92:95], v[74:75], off offset:16
	v_lshlrev_b64 v[74:75], 7, v[80:81]
	v_lshl_add_u64 v[74:75], v[146:147], 0, v[74:75]
	global_load_dwordx4 v[98:101], v[74:75], off
	global_load_dwordx4 v[102:105], v[74:75], off offset:16
	v_add_u32_e32 v74, 0xb0, v158
	v_ashrrev_i32_e32 v75, 31, v74
	v_lshlrev_b64 v[76:77], 7, v[74:75]
	v_lshl_add_u64 v[76:77], v[146:147], 0, v[76:77]
	global_load_dwordx4 v[106:109], v[76:77], off
	global_load_dwordx4 v[110:113], v[76:77], off offset:16
	s_load_dwordx16 s[60:75], s[34:35], 0x38
	v_lshlrev_b64 v[78:79], 12, v[68:69]
	s_mov_b32 s2, 0x3a800000
	s_mov_b32 s1, 0x800000
	s_waitcnt lgkmcnt(0)
	v_lshl_add_u64 v[78:79], s[74:75], 0, v[78:79]
	v_lshl_add_u64 v[76:77], v[152:153], 2, v[78:79]
	global_load_dwordx4 v[114:117], v[76:77], off offset:16
	global_load_dwordx4 v[118:121], v[76:77], off
	global_load_dwordx4 v[122:125], v[156:157], off offset:16
	global_load_dwordx4 v[126:129], v[156:157], off
	global_load_dwordx4 v[130:133], v[154:155], off offset:16
	global_load_dwordx4 v[134:137], v[154:155], off
	s_mov_b32 s16, 0x3fd744fd
	s_waitcnt vmcnt(13)
	v_mov_b32_e32 v78, v70
	s_waitcnt vmcnt(12)
	v_mov_b32_e32 v79, v82
	v_mov_b32_e32 v158, v72
	v_mov_b32_e32 v159, v84
	v_mov_b32_e32 v82, v71
	v_mov_b32_e32 v84, v73
	v_pk_add_f32 v[78:79], v[78:79], v[158:159]
	v_pk_add_f32 v[82:83], v[82:83], v[84:85]
	v_pk_add_f32 v[78:79], v[78:79], v[78:79] op_sel:[0,1] op_sel_hi:[1,0]
	v_pk_add_f32 v[82:83], v[82:83], v[82:83] op_sel:[0,1] op_sel_hi:[1,0]
	v_mov_b32_e32 v0, v78
	v_mov_b32_e32 v69, v82
	s_nop 0
	v_permlane16_swap_b32_e32 v78, v0
	v_permlane16_swap_b32_e32 v82, v69
	v_add_f32_e32 v79, v78, v0
	v_add_f32_e32 v78, v82, v69
	v_mov_b32_e32 v83, v79
	v_mov_b32_e32 v82, v78
	s_waitcnt vmcnt(11)
	v_mov_b32_e32 v70, v88
	s_waitcnt vmcnt(10)
	v_mov_b32_e32 v71, v92
	v_mov_b32_e32 v72, v90
	v_mov_b32_e32 v73, v94
	v_mov_b32_e32 v92, v89
	v_mov_b32_e32 v94, v91
	v_permlane32_swap_b32_e32 v79, v83
	v_permlane32_swap_b32_e32 v78, v82
	s_waitcnt vmcnt(9)
	v_mov_b32_e32 v88, v98
	s_waitcnt vmcnt(8)
; __device__ __forceinline__ size_t blk_off(int r, int c, int K) { return (size_t)(r >> 8) * 256 * K + (size_t)(c >> 6) * (256 * 64) + (size_t)((r & 255) * 64 + (c & 63)); }
; __device__ __forceinline__ u32x4 pack8(const f32x4 a, const f32x4 b) { u32x4 w; w.x = cvt_pk_bf16(a[0], a[1]); w.y = cvt_pk_bf16(a[2], a[3]); w.z = cvt_pk_bf16(b[0], b[1]); w.w = cvt_pk_bf16(b[2], b[3]); return w; }
;     __device__ __forceinline__ void operator()(const f32x4 (&acc)[2][2][4][2], const pg8::Unit& u, int wr, int wc, int fr, int fq) const {
;     ...
;             for (int m = 0; m < 4; ++m) { const int row = row0 + ai * 128 + m * 16; const float mu = mu4[m], rs = rs4[m];
;                 f32x4 yv[2][2], gq[2][2], bq_[2][2];
; #pragma unroll
;                 for (int bj = 0; bj < 2; ++bj)
; #pragma unroll
;                     for (int n = 0; n < 2; ++n) { yv[bj][n] = *(const f32x4*)(Yin + (size_t)row * D_ + col0 + bj * 128 + 4 * n); gq[bj][n] = *(const f32x4*)(g + col0 + bj * 128 + 4 * n); bq_[bj][n] = *(const f32x4*)(b + col0 + bj * 128 + 4 * n); }
;                 asm volatile("" ::: "memory");
;                 float s1 = 0.f, s2 = 0.f;
; #pragma unroll
;                 for (int bj = 0; bj < 2; ++bj) { float* yp = Y + (size_t)row * D_ + col0 + bj * 128; f32x4 v[2];
; #pragma unroll
;                     for (int n = 0; n < 2; ++n) { v[n] = (((yv[bj][n] - mu) * rs) * gq[bj][n] + bq_[bj][n]) * ALPHA_ + acc[ai][bj][m][n] * sc;
;                         *(f32x4*)(yp + 4 * n) = v[n]; s1 += (v[n][0] + v[n][1]) + (v[n][2] + v[n][3]); s2 += (v[n][0] * v[n][0] + v[n][1] * v[n][1]) + (v[n][2] * v[n][2] + v[n][3] * v[n][3]); }
;                     *(u32x4*)(Yb + blk_off(row, col0 + bj * 128, D_)) = pack8(v[0], v[1]); }
	v_mov_b32_e32 v89, v102
	v_mov_b32_e32 v90, v100
	v_mov_b32_e32 v91, v104
	v_mov_b32_e32 v102, v99
	v_mov_b32_e32 v104, v101
	v_pk_add_f32 v[70:71], v[70:71], v[72:73]
	v_pk_add_f32 v[72:73], v[92:93], v[94:95]
	v_pk_add_f32 v[78:79], v[78:79], v[82:83]
	global_load_dwordx4 v[92:95], v[76:77], off offset:528
	global_load_dwordx4 v[98:101], v[76:77], off offset:512
	v_pk_mul_f32 v[162:163], v[78:79], s[2:3] op_sel_hi:[1,0]
	s_waitcnt vmcnt(9)
	v_mov_b32_e32 v78, v106
	s_waitcnt vmcnt(8)
	v_mov_b32_e32 v79, v110
	v_mov_b32_e32 v82, v108
	v_mov_b32_e32 v83, v112
	v_mov_b32_e32 v110, v107
	v_mov_b32_e32 v112, v109
	v_pk_add_f32 v[84:85], v[88:89], v[90:91]
	v_pk_add_f32 v[88:89], v[102:103], v[104:105]
	v_pk_add_f32 v[78:79], v[78:79], v[82:83]
	v_pk_add_f32 v[82:83], v[110:111], v[112:113]
	global_load_dwordx4 v[102:105], v[156:157], off offset:528
	global_load_dwordx4 v[106:109], v[156:157], off offset:512
	global_load_dwordx4 v[110:113], v[154:155], off offset:528
	global_load_dwordx4 v[158:161], v[154:155], off offset:512
	v_fma_f32 v0, -v163, v163, v162
	v_max_f32_e32 v0, 0, v0
	v_add_f32_e32 v0, 0x3727c5ac, v0
	v_mul_f32_e32 v69, 0x4b800000, v0
	v_cmp_gt_f32_e32 vcc, s1, v0
	v_pk_add_f32 v[88:89], v[88:89], v[88:89] op_sel:[0,1] op_sel_hi:[1,0]
	v_pk_add_f32 v[78:79], v[78:79], v[78:79] op_sel:[0,1] op_sel_hi:[1,0]
	v_cndmask_b32_e32 v0, v0, v69, vcc
	v_rsq_f32_e32 v0, v0
	v_pk_add_f32 v[82:83], v[82:83], v[82:83] op_sel:[0,1] op_sel_hi:[1,0]
	s_waitcnt vmcnt(10)
	v_sub_f32_e32 v119, v119, v163
	v_sub_f32_e32 v118, v118, v163
	v_mul_f32_e32 v69, 0x45800000, v0
	v_cndmask_b32_e32 v162, v0, v69, vcc
	v_mov_b32_e32 v0, v88
	s_nop 1
	v_permlane16_swap_b32_e32 v88, v0
	v_add_f32_e32 v88, v88, v0
	v_mov_b32_e32 v0, v78
	s_nop 1
	v_permlane16_swap_b32_e32 v78, v0
	v_add_f32_e32 v83, v78, v0
	v_mov_b32_e32 v0, v82
	s_nop 1
	v_permlane16_swap_b32_e32 v82, v0
	v_add_f32_e32 v82, v82, v0
	v_ashrrev_i32_e32 v78, 8, v68
	v_lshlrev_b32_e32 v0, 6, v68
	v_sub_f32_e32 v69, v121, v163
	v_sub_f32_e32 v68, v120, v163
	v_pk_mul_f32 v[118:119], v[162:163], v[118:119] op_sel_hi:[0,1]
	v_pk_mul_f32 v[68:69], v[162:163], v[68:69] op_sel_hi:[0,1]
	s_waitcnt vmcnt(6)
	v_pk_fma_f32 v[68:69], v[128:129], v[68:69], v[136:137]
	v_pk_fma_f32 v[118:119], v[126:127], v[118:119], v[134:135]
	v_pk_mul_f32 v[68:69], v[68:69], s[16:17] op_sel_hi:[1,0]
	v_pk_mul_f32 v[118:119], v[118:119], s[16:17] op_sel_hi:[1,0]
	v_pk_fma_f32 v[64:65], v[64:65], 0.5, v[68:69] op_sel_hi:[1,0,1]
	v_pk_fma_f32 v[62:63], v[62:63], 0.5, v[118:119] op_sel_hi:[1,0,1]
	v_add_f32_e32 v69, v64, v65
	v_add_f32_e32 v68, v62, v63
	v_add_f32_e32 v68, v68, v69
	v_add_f32_e32 v118, 0, v68
	v_mul_f32_e32 v68, v63, v63
	v_mul_f32_e32 v69, v65, v65
	v_fmac_f32_e32 v68, v62, v62
	v_fmac_f32_e32 v69, v64, v64
	v_add_f32_e32 v119, v68, v69
	v_sub_f32_e32 v69, v117, v163
	v_sub_f32_e32 v68, v116, v163
	v_sub_f32_e32 v115, v115, v163
	v_sub_f32_e32 v114, v114, v163
	v_pk_mul_f32 v[114:115], v[162:163], v[114:115] op_sel_hi:[0,1]
	v_pk_mul_f32 v[68:69], v[162:163], v[68:69] op_sel_hi:[0,1]
	v_pk_fma_f32 v[68:69], v[124:125], v[68:69], v[132:133]
	v_pk_fma_f32 v[114:115], v[122:123], v[114:115], v[130:131]
	v_pk_mul_f32 v[68:69], v[68:69], s[16:17] op_sel_hi:[1,0]
	v_pk_mul_f32 v[114:115], v[114:115], s[16:17] op_sel_hi:[1,0]
	v_pk_fma_f32 v[60:61], v[60:61], 0.5, v[68:69] op_sel_hi:[1,0,1]
	v_pk_fma_f32 v[58:59], v[58:59], 0.5, v[114:115] op_sel_hi:[1,0,1]
	v_ashrrev_i32_e32 v79, 31, v78
	v_add_f32_e32 v68, v58, v59
	v_add_f32_e32 v69, v60, v61
	v_readlane_b32 s2, v253, 59
	v_lshlrev_b64 v[78:79], 19, v[78:79]
	s_movk_i32 s1, 0x33c0
	v_add_f32_e32 v68, v68, v69
	v_mul_f32_e32 v69, v59, v59
	v_readlane_b32 s3, v253, 60
	v_and_or_b32 v0, v0, s1, v196
	s_nop 0
	s_nop 1
	v_bfe_u32 v91, v227, 4, 1
	v_sub_u32_e32 v91, 0, v91
	v_lshlrev_b32_e32 v90, 4, v91
	v_lshl_add_u64 v[90:91], v[76:77], 0, v[90:91]
	v_permlane16_swap_b32_e32 v62, v58
	v_permlane16_swap_b32_e32 v63, v59
	v_permlane16_swap_b32_e32 v64, v60
	v_permlane16_swap_b32_e32 v65, v61
	global_store_dwordx4 v[90:91], v[62:65], off
	global_store_dwordx4 v[90:91], v[58:61], off offset:32
	s_nop 1
	v_permlane16_swap_b32_e32 v62, v58
	v_permlane16_swap_b32_e32 v63, v59
	v_permlane16_swap_b32_e32 v64, v60
	v_permlane16_swap_b32_e32 v65, v61
	v_fmac_f32_e32 v69, v58, v58
	v_cvt_pk_bf16_f32 v62, v62, v63
	v_cvt_pk_bf16_f32 v63, v64, v65
	v_cvt_pk_bf16_f32 v64, v58, v59
	v_lshl_add_u64 v[58:59], s[2:3], 0, v[78:79]
	v_mul_f32_e32 v114, v61, v61
	v_lshl_add_u64 v[78:79], v[58:59], 0, s[24:25]
	v_lshlrev_b32_e32 v0, 1, v0
	v_fmac_f32_e32 v114, v60, v60
	v_cvt_pk_bf16_f32 v65, v60, v61
	v_lshl_add_u64 v[60:61], v[78:79], 0, v[0:1]
	global_store_dwordx4 v[60:61], v[62:65], off
	s_waitcnt vmcnt(7)
	v_sub_f32_e32 v61, v101, v163
	v_sub_f32_e32 v60, v100, v163
	v_sub_f32_e32 v63, v99, v163
	v_sub_f32_e32 v62, v98, v163
	v_pk_mul_f32 v[62:63], v[162:163], v[62:63] op_sel_hi:[0,1]
	v_pk_mul_f32 v[60:61], v[162:163], v[60:61] op_sel_hi:[0,1]
	s_waitcnt vmcnt(3)
; __device__ __forceinline__ float xsum16(float v) { const auto r = __builtin_amdgcn_permlane16_swap(__float_as_uint(v), __float_as_uint(v), false, false); return __uint_as_float(r[0]) + __uint_as_float(r[1]); }
; __device__ __forceinline__ float xsum32(float v) { const auto r = __builtin_amdgcn_permlane32_swap(__float_as_uint(v), __float_as_uint(v), false, false); return __uint_as_float(r[0]) + __uint_as_float(r[1]); }
; __device__ __forceinline__ size_t blk_off(int r, int c, int K) { return (size_t)(r >> 8) * 256 * K + (size_t)(c >> 6) * (256 * 64) + (size_t)((r & 255) * 64 + (c & 63)); }
; __device__ __forceinline__ u32x4 pack8(const f32x4 a, const f32x4 b) { u32x4 w; w.x = cvt_pk_bf16(a[0], a[1]); w.y = cvt_pk_bf16(a[2], a[3]); w.z = cvt_pk_bf16(b[0], b[1]); w.w = cvt_pk_bf16(b[2], b[3]); return w; }
;     __device__ __forceinline__ void operator()(const f32x4 (&acc)[2][2][4][2], const pg8::Unit& u, int wr, int wc, int fr, int fq) const {
;     ...
;             for (int m = 0; m < 4; ++m) { const int row = row0 + ai * 128 + m * 16; const float mu = mu4[m], rs = rs4[m];
;                 f32x4 yv[2][2], gq[2][2], bq_[2][2];
; #pragma unroll
;                 for (int bj = 0; bj < 2; ++bj)
; #pragma unroll
;                     for (int n = 0; n < 2; ++n) { yv[bj][n] = *(const f32x4*)(Yin + (size_t)row * D_ + col0 + bj * 128 + 4 * n); gq[bj][n] = *(const f32x4*)(g + col0 + bj * 128 + 4 * n); bq_[bj][n] = *(const f32x4*)(b + col0 + bj * 128 + 4 * n); }
;                 asm volatile("" ::: "memory");
;                 float s1 = 0.f, s2 = 0.f;
; #pragma unroll
;                 for (int bj = 0; bj < 2; ++bj) { float* yp = Y + (size_t)row * D_ + col0 + bj * 128; f32x4 v[2];
; #pragma unroll
;                     for (int n = 0; n < 2; ++n) { v[n] = (((yv[bj][n] - mu) * rs) * gq[bj][n] + bq_[bj][n]) * ALPHA_ + acc[ai][bj][m][n] * sc;
;                         *(f32x4*)(yp + 4 * n) = v[n]; s1 += (v[n][0] + v[n][1]) + (v[n][2] + v[n][3]); s2 += (v[n][0] * v[n][0] + v[n][1] * v[n][1]) + (v[n][2] * v[n][2] + v[n][3] * v[n][3]); }
;                     *(u32x4*)(Yb + blk_off(row, col0 + bj * 128, D_)) = pack8(v[0], v[1]); }
;                 s1 = xsum32(xsum16(s1)); s2 = xsum32(xsum16(s2));
;                 if (fq == 0) *(f32x2*)(stn + (size_t)row * 32 + (u.pn * 4 + wc) * 2) = (f32x2){s1, s2}; asm volatile("" ::: "memory"); } }
	v_pk_fma_f32 v[60:61], v[108:109], v[60:61], v[160:161]
	v_pk_fma_f32 v[62:63], v[106:107], v[62:63], v[158:159]
	v_pk_mul_f32 v[60:61], v[60:61], s[16:17] op_sel_hi:[1,0]
	v_pk_mul_f32 v[62:63], v[62:63], s[16:17] op_sel_hi:[1,0]
	v_pk_fma_f32 v[56:57], v[56:57], 0.5, v[60:61] op_sel_hi:[1,0,1]
	v_pk_fma_f32 v[54:55], v[54:55], 0.5, v[62:63] op_sel_hi:[1,0,1]
	v_add_f32_e32 v61, v56, v57
	v_add_f32_e32 v60, v54, v55
	v_add_f32_e32 v68, v118, v68
	v_add_f32_e32 v60, v60, v61
	v_add_f32_e32 v64, v68, v60
	v_mul_f32_e32 v60, v55, v55
	v_mul_f32_e32 v61, v57, v57
	v_add_f32_e32 v69, v69, v114
	v_fmac_f32_e32 v60, v54, v54
	v_fmac_f32_e32 v61, v56, v56
	v_add_f32_e32 v69, v119, v69
	v_add_f32_e32 v60, v60, v61
	v_add_f32_e32 v65, v69, v60
	v_sub_f32_e32 v61, v95, v163
	v_sub_f32_e32 v60, v94, v163
	v_sub_f32_e32 v63, v93, v163
	v_sub_f32_e32 v62, v92, v163
	v_pk_mul_f32 v[62:63], v[162:163], v[62:63] op_sel_hi:[0,1]
	v_pk_mul_f32 v[60:61], v[162:163], v[60:61] op_sel_hi:[0,1]
	v_pk_fma_f32 v[60:61], v[104:105], v[60:61], v[112:113]
	v_pk_fma_f32 v[62:63], v[102:103], v[62:63], v[110:111]
	v_pk_mul_f32 v[60:61], v[60:61], s[16:17] op_sel_hi:[1,0]
	v_pk_mul_f32 v[62:63], v[62:63], s[16:17] op_sel_hi:[1,0]
	v_pk_fma_f32 v[52:53], v[52:53], 0.5, v[60:61] op_sel_hi:[1,0,1]
	v_pk_fma_f32 v[50:51], v[50:51], 0.5, v[62:63] op_sel_hi:[1,0,1]
	v_add_f32_e32 v61, v52, v53
	v_add_f32_e32 v60, v50, v51
	v_add_f32_e32 v60, v60, v61
	v_mul_f32_e32 v61, v51, v51
	v_mul_f32_e32 v62, v53, v53
	s_nop 0
	s_nop 1
	v_bfe_u32 v69, v227, 4, 1
	v_sub_u32_e32 v69, 0, v69
	v_lshlrev_b32_e32 v68, 4, v69
	v_lshl_add_u64 v[68:69], v[76:77], 0, v[68:69]
	v_permlane16_swap_b32_e32 v54, v50
	v_permlane16_swap_b32_e32 v55, v51
	v_permlane16_swap_b32_e32 v56, v52
	v_permlane16_swap_b32_e32 v57, v53
	global_store_dwordx4 v[68:69], v[54:57], off offset:512
	global_store_dwordx4 v[68:69], v[50:53], off offset:544
	s_nop 1
	v_permlane16_swap_b32_e32 v54, v50
	v_permlane16_swap_b32_e32 v55, v51
	v_permlane16_swap_b32_e32 v56, v52
	v_permlane16_swap_b32_e32 v57, v53
	v_add_f32_e32 v60, v64, v60
	v_fmac_f32_e32 v61, v50, v50
	v_fmac_f32_e32 v62, v52, v52
	v_lshl_add_u64 v[76:77], v[58:59], 0, s[44:45]
	v_add_f32_e32 v61, v61, v62
	v_cvt_pk_bf16_f32 v54, v54, v55
	v_cvt_pk_bf16_f32 v55, v56, v57
	v_cvt_pk_bf16_f32 v56, v50, v51
	v_lshl_add_u64 v[50:51], v[76:77], 0, v[0:1]
	v_mov_b32_e32 v0, v60
	v_pk_add_f32 v[70:71], v[70:71], v[70:71] op_sel:[0,1] op_sel_hi:[1,0]
	v_pk_add_f32 v[72:73], v[72:73], v[72:73] op_sel:[0,1] op_sel_hi:[1,0]
	v_pk_add_f32 v[84:85], v[84:85], v[84:85] op_sel:[0,1] op_sel_hi:[1,0]
	v_add_f32_e32 v61, v65, v61
	v_cvt_pk_bf16_f32 v57, v52, v53
	v_permlane16_swap_b32_e32 v60, v0
	v_mov_b32_e32 v71, v70
	v_mov_b32_e32 v73, v72
	v_mov_b32_e32 v85, v84
	global_store_dwordx4 v[50:51], v[54:57], off
	v_add_f32_e32 v50, v60, v0
	v_mov_b32_e32 v0, v61
	v_permlane16_swap_b32_e32 v70, v71
	v_permlane16_swap_b32_e32 v72, v73
	v_permlane16_swap_b32_e32 v84, v85
	v_permlane16_swap_b32_e32 v61, v0
	v_add_f32_e32 v71, v70, v71
	v_add_f32_e32 v70, v72, v73
	v_add_f32_e32 v89, v84, v85
	v_add_f32_e32 v51, v61, v0
	v_mov_b32_e32 v73, v71
	v_mov_b32_e32 v72, v70
	v_mov_b32_e32 v91, v89
	v_mov_b32_e32 v90, v88
	v_mov_b32_e32 v85, v83
	v_mov_b32_e32 v84, v82
	v_mov_b32_e32 v52, v50
	v_mov_b32_e32 v53, v51
	v_permlane32_swap_b32_e32 v71, v73
	v_permlane32_swap_b32_e32 v70, v72
	v_permlane32_swap_b32_e32 v89, v91
	v_permlane32_swap_b32_e32 v88, v90
	v_permlane32_swap_b32_e32 v83, v85
	v_permlane32_swap_b32_e32 v82, v84
	v_permlane32_swap_b32_e32 v50, v52
	v_permlane32_swap_b32_e32 v51, v53
	s_and_saveexec_b64 s[24:25], s[40:41]
	s_cbranch_execz .LBB0_1713
	v_pk_add_f32 v[50:51], v[50:51], v[52:53]
	v_lshl_add_u64 v[52:53], s[8:9], 0, v[66:67]
	v_lshl_add_u64 v[52:53], s[38:39], 2, v[52:53]
	global_store_dwordx2 v[52:53], v[50:51], off
.LBB0_1713:
	s_or_b64 exec, exec, s[24:25]
	v_pk_add_f32 v[50:51], v[70:71], v[72:73]
	s_mov_b32 s2, 0x3a800000
	v_pk_mul_f32 v[92:93], v[50:51], s[2:3] op_sel_hi:[1,0]
	s_mov_b32 s1, 0x800000
	v_fma_f32 v0, -v93, v93, v92
	v_max_f32_e32 v0, 0, v0
	v_add_f32_e32 v0, 0x3727c5ac, v0
	v_cmp_gt_f32_e32 vcc, s1, v0
	v_mul_f32_e32 v50, 0x4b800000, v0
	s_load_dwordx16 s[60:75], s[34:35], 0x38
	v_cndmask_b32_e32 v0, v0, v50, vcc
	v_rsq_f32_e32 v0, v0
	s_mov_b32 s2, 0x3fd744fd
	s_movk_i32 s1, 0x37c0
	v_mul_f32_e32 v50, 0x45800000, v0
	v_cndmask_b32_e32 v92, v0, v50, vcc
	v_lshlrev_b64 v[50:51], 12, v[96:97]
	s_waitcnt lgkmcnt(0)
	v_lshl_add_u64 v[50:51], s[74:75], 0, v[50:51]
	v_lshl_add_u64 v[94:95], v[152:153], 2, v[50:51]
	global_load_dwordx4 v[98:101], v[94:95], off offset:16
	global_load_dwordx4 v[102:105], v[94:95], off
	global_load_dwordx4 v[106:109], v[156:157], off offset:16
	global_load_dwordx4 v[110:113], v[156:157], off
	global_load_dwordx4 v[114:117], v[154:155], off offset:16
	global_load_dwordx4 v[118:121], v[154:155], off
	global_load_dwordx4 v[50:53], v[94:95], off offset:528
	global_load_dwordx4 v[70:73], v[94:95], off offset:512
	global_load_dwordx4 v[54:57], v[156:157], off offset:528
	global_load_dwordx4 v[62:65], v[156:157], off offset:512
	global_load_dwordx4 v[58:61], v[154:155], off offset:528
	global_load_dwordx4 v[66:69], v[154:155], off offset:512
	v_lshlrev_b32_e32 v0, 6, v96
	v_and_or_b32 v0, v0, s1, v196
	v_lshlrev_b32_e32 v0, 1, v0
	s_waitcnt vmcnt(10)
	v_sub_f32_e32 v97, v105, v93
	v_sub_f32_e32 v96, v104, v93
	v_sub_f32_e32 v103, v103, v93
	v_sub_f32_e32 v102, v102, v93
	v_pk_mul_f32 v[102:103], v[92:93], v[102:103] op_sel_hi:[0,1]
	v_pk_mul_f32 v[96:97], v[92:93], v[96:97] op_sel_hi:[0,1]
	s_waitcnt vmcnt(6)
; __device__ __forceinline__ float xsum16(float v) { const auto r = __builtin_amdgcn_permlane16_swap(__float_as_uint(v), __float_as_uint(v), false, false); return __uint_as_float(r[0]) + __uint_as_float(r[1]); }
; __device__ __forceinline__ float xsum32(float v) { const auto r = __builtin_amdgcn_permlane32_swap(__float_as_uint(v), __float_as_uint(v), false, false); return __uint_as_float(r[0]) + __uint_as_float(r[1]); }
; __device__ __forceinline__ size_t blk_off(int r, int c, int K) { return (size_t)(r >> 8) * 256 * K + (size_t)(c >> 6) * (256 * 64) + (size_t)((r & 255) * 64 + (c & 63)); }
; __device__ __forceinline__ u32x4 pack8(const f32x4 a, const f32x4 b) { u32x4 w; w.x = cvt_pk_bf16(a[0], a[1]); w.y = cvt_pk_bf16(a[2], a[3]); w.z = cvt_pk_bf16(b[0], b[1]); w.w = cvt_pk_bf16(b[2], b[3]); return w; }
;     __device__ __forceinline__ void operator()(const f32x4 (&acc)[2][2][4][2], const pg8::Unit& u, int wr, int wc, int fr, int fq) const {
;     ...
;             for (int m = 0; m < 4; ++m) { const int row = row0 + ai * 128 + m * 16; const float mu = mu4[m], rs = rs4[m];
;                 f32x4 yv[2][2], gq[2][2], bq_[2][2];
; #pragma unroll
;                 for (int bj = 0; bj < 2; ++bj)
; #pragma unroll
;                     for (int n = 0; n < 2; ++n) { yv[bj][n] = *(const f32x4*)(Yin + (size_t)row * D_ + col0 + bj * 128 + 4 * n); gq[bj][n] = *(const f32x4*)(g + col0 + bj * 128 + 4 * n); bq_[bj][n] = *(const f32x4*)(b + col0 + bj * 128 + 4 * n); }
;                 asm volatile("" ::: "memory");
;                 float s1 = 0.f, s2 = 0.f;
; #pragma unroll
;                 for (int bj = 0; bj < 2; ++bj) { float* yp = Y + (size_t)row * D_ + col0 + bj * 128; f32x4 v[2];
; #pragma unroll
;                     for (int n = 0; n < 2; ++n) { v[n] = (((yv[bj][n] - mu) * rs) * gq[bj][n] + bq_[bj][n]) * ALPHA_ + acc[ai][bj][m][n] * sc;
;                         *(f32x4*)(yp + 4 * n) = v[n]; s1 += (v[n][0] + v[n][1]) + (v[n][2] + v[n][3]); s2 += (v[n][0] * v[n][0] + v[n][1] * v[n][1]) + (v[n][2] * v[n][2] + v[n][3] * v[n][3]); }
;                     *(u32x4*)(Yb + blk_off(row, col0 + bj * 128, D_)) = pack8(v[0], v[1]); }
;                 s1 = xsum32(xsum16(s1)); s2 = xsum32(xsum16(s2));
;                 if (fq == 0) *(f32x2*)(stn + (size_t)row * 32 + (u.pn * 4 + wc) * 2) = (f32x2){s1, s2}; asm volatile("" ::: "memory"); } }
	v_pk_fma_f32 v[96:97], v[112:113], v[96:97], v[120:121]
	v_pk_fma_f32 v[102:103], v[110:111], v[102:103], v[118:119]
	v_pk_mul_f32 v[96:97], v[96:97], s[2:3] op_sel_hi:[1,0]
	v_pk_mul_f32 v[102:103], v[102:103], s[2:3] op_sel_hi:[1,0]
	v_pk_fma_f32 v[104:105], v[48:49], 0.5, v[96:97] op_sel_hi:[1,0,1]
	v_pk_fma_f32 v[102:103], v[46:47], 0.5, v[102:103] op_sel_hi:[1,0,1]
	v_add_f32_e32 v47, v104, v105
	v_add_f32_e32 v46, v102, v103
	v_add_f32_e32 v46, v46, v47
	v_add_f32_e32 v110, 0, v46
	v_mul_f32_e32 v46, v103, v103
	v_mul_f32_e32 v47, v105, v105
	v_fmac_f32_e32 v46, v102, v102
	v_fmac_f32_e32 v47, v104, v104
	v_add_f32_e32 v111, v46, v47
	v_sub_f32_e32 v47, v101, v93
	v_sub_f32_e32 v46, v100, v93
	v_sub_f32_e32 v49, v99, v93
	v_sub_f32_e32 v48, v98, v93
	v_pk_mul_f32 v[48:49], v[92:93], v[48:49] op_sel_hi:[0,1]
	v_pk_mul_f32 v[46:47], v[92:93], v[46:47] op_sel_hi:[0,1]
	v_pk_fma_f32 v[46:47], v[108:109], v[46:47], v[116:117]
	v_pk_fma_f32 v[48:49], v[106:107], v[48:49], v[114:115]
	v_pk_mul_f32 v[46:47], v[46:47], s[2:3] op_sel_hi:[1,0]
	v_pk_mul_f32 v[48:49], v[48:49], s[2:3] op_sel_hi:[1,0]
	v_pk_fma_f32 v[98:99], v[44:45], 0.5, v[46:47] op_sel_hi:[1,0,1]
	v_pk_fma_f32 v[96:97], v[42:43], 0.5, v[48:49] op_sel_hi:[1,0,1]
	v_add_f32_e32 v43, v98, v99
	v_add_f32_e32 v42, v96, v97
	v_add_f32_e32 v42, v42, v43
	v_add_f32_e32 v47, v110, v42
	v_mul_f32_e32 v42, v97, v97
	v_mul_f32_e32 v43, v99, v99
	v_fmac_f32_e32 v42, v96, v96
	v_fmac_f32_e32 v43, v98, v98
	v_add_f32_e32 v42, v42, v43
	v_add_f32_e32 v46, v111, v42
	v_cvt_pk_bf16_f32 v42, v102, v103
	v_cvt_pk_bf16_f32 v43, v104, v105
	v_cvt_pk_bf16_f32 v44, v96, v97
	v_cvt_pk_bf16_f32 v45, v98, v99
	v_lshl_add_u64 v[48:49], v[78:79], 0, v[0:1]
	s_nop 0
	s_nop 1
	v_bfe_u32 v101, v227, 4, 1
	v_sub_u32_e32 v101, 0, v101
	v_lshlrev_b32_e32 v100, 4, v101
	v_lshl_add_u64 v[100:101], v[94:95], 0, v[100:101]
	v_permlane16_swap_b32_e32 v102, v96
	v_permlane16_swap_b32_e32 v103, v97
	v_permlane16_swap_b32_e32 v104, v98
	v_permlane16_swap_b32_e32 v105, v99
	global_store_dwordx4 v[100:101], v[102:105], off
	global_store_dwordx4 v[100:101], v[96:99], off offset:32
	s_nop 1
	v_permlane16_swap_b32_e32 v102, v96
	v_permlane16_swap_b32_e32 v103, v97
	v_permlane16_swap_b32_e32 v104, v98
	v_permlane16_swap_b32_e32 v105, v99
	global_store_dwordx4 v[48:49], v[42:45], off
	s_waitcnt vmcnt(7)
	s_nop 0
	v_sub_f32_e32 v43, v73, v93
	v_sub_f32_e32 v42, v72, v93
	v_sub_f32_e32 v45, v71, v93
	v_sub_f32_e32 v44, v70, v93
	v_pk_mul_f32 v[44:45], v[92:93], v[44:45] op_sel_hi:[0,1]
	v_pk_mul_f32 v[42:43], v[92:93], v[42:43] op_sel_hi:[0,1]
	s_waitcnt vmcnt(3)
	v_pk_fma_f32 v[42:43], v[64:65], v[42:43], v[68:69]
	v_pk_fma_f32 v[44:45], v[62:63], v[44:45], v[66:67]
	v_pk_mul_f32 v[42:43], v[42:43], s[2:3] op_sel_hi:[1,0]
	v_pk_mul_f32 v[44:45], v[44:45], s[2:3] op_sel_hi:[1,0]
	v_pk_fma_f32 v[40:41], v[40:41], 0.5, v[42:43] op_sel_hi:[1,0,1]
	v_pk_fma_f32 v[38:39], v[38:39], 0.5, v[44:45] op_sel_hi:[1,0,1]
	v_add_f32_e32 v43, v40, v41
	v_add_f32_e32 v42, v38, v39
	v_add_f32_e32 v42, v42, v43
	v_add_f32_e32 v47, v47, v42
	v_mul_f32_e32 v42, v39, v39
	v_mul_f32_e32 v43, v41, v41
	v_fmac_f32_e32 v42, v38, v38
	v_fmac_f32_e32 v43, v40, v40
	v_add_f32_e32 v42, v42, v43
	v_add_f32_e32 v46, v46, v42
	v_sub_f32_e32 v43, v53, v93
	v_sub_f32_e32 v42, v52, v93
	v_sub_f32_e32 v45, v51, v93
	v_sub_f32_e32 v44, v50, v93
	v_pk_mul_f32 v[44:45], v[92:93], v[44:45] op_sel_hi:[0,1]
	v_pk_mul_f32 v[42:43], v[92:93], v[42:43] op_sel_hi:[0,1]
	v_pk_fma_f32 v[42:43], v[56:57], v[42:43], v[60:61]
	v_pk_fma_f32 v[44:45], v[54:55], v[44:45], v[58:59]
	v_pk_mul_f32 v[42:43], v[42:43], s[2:3] op_sel_hi:[1,0]
	v_pk_mul_f32 v[44:45], v[44:45], s[2:3] op_sel_hi:[1,0]
	v_pk_fma_f32 v[36:37], v[36:37], 0.5, v[42:43] op_sel_hi:[1,0,1]
	v_pk_fma_f32 v[34:35], v[34:35], 0.5, v[44:45] op_sel_hi:[1,0,1]
	v_add_f32_e32 v43, v36, v37
	v_add_f32_e32 v42, v34, v35
	v_add_f32_e32 v42, v42, v43
	v_mul_f32_e32 v43, v35, v35
	v_mul_f32_e32 v44, v37, v37
	v_add_f32_e32 v42, v47, v42
	v_fmac_f32_e32 v43, v34, v34
	v_fmac_f32_e32 v44, v36, v36
	s_nop 0
	s_nop 1
	v_bfe_u32 v49, v227, 4, 1
	v_sub_u32_e32 v49, 0, v49
	v_lshlrev_b32_e32 v48, 4, v49
	v_lshl_add_u64 v[48:49], v[94:95], 0, v[48:49]
	v_permlane16_swap_b32_e32 v38, v34
	v_permlane16_swap_b32_e32 v39, v35
	v_permlane16_swap_b32_e32 v40, v36
	v_permlane16_swap_b32_e32 v41, v37
	global_store_dwordx4 v[48:49], v[38:41], off offset:512
	global_store_dwordx4 v[48:49], v[34:37], off offset:544
	s_nop 1
	v_permlane16_swap_b32_e32 v38, v34
	v_permlane16_swap_b32_e32 v39, v35
	v_permlane16_swap_b32_e32 v40, v36
	v_permlane16_swap_b32_e32 v41, v37
	v_add_f32_e32 v43, v43, v44
	v_cvt_pk_bf16_f32 v38, v38, v39
	v_cvt_pk_bf16_f32 v39, v40, v41
	v_cvt_pk_bf16_f32 v40, v34, v35
	v_lshl_add_u64 v[34:35], v[76:77], 0, v[0:1]
	v_mov_b32_e32 v0, v42
	v_add_f32_e32 v43, v46, v43
	v_cvt_pk_bf16_f32 v41, v36, v37
	v_permlane16_swap_b32_e32 v42, v0
	global_store_dwordx4 v[34:35], v[38:41], off
	v_add_f32_e32 v34, v42, v0
	v_mov_b32_e32 v0, v43
	s_nop 1
	v_permlane16_swap_b32_e32 v43, v0
	v_add_f32_e32 v35, v43, v0
	v_mov_b32_e32 v36, v34
	v_mov_b32_e32 v37, v35
	s_nop 0
	v_permlane32_swap_b32_e32 v34, v36
	v_permlane32_swap_b32_e32 v35, v37
	s_and_saveexec_b64 s[24:25], s[40:41]
	s_cbranch_execz .LBB0_1715
	v_pk_add_f32 v[34:35], v[34:35], v[36:37]
	v_lshl_add_u64 v[36:37], s[8:9], 0, v[86:87]
	v_lshl_add_u64 v[36:37], s[38:39], 2, v[36:37]
	global_store_dwordx2 v[36:37], v[34:35], off
; __device__ __forceinline__ float xsum16(float v) { const auto r = __builtin_amdgcn_permlane16_swap(__float_as_uint(v), __float_as_uint(v), false, false); return __uint_as_float(r[0]) + __uint_as_float(r[1]); }
; __device__ __forceinline__ float xsum32(float v) { const auto r = __builtin_amdgcn_permlane32_swap(__float_as_uint(v), __float_as_uint(v), false, false); return __uint_as_float(r[0]) + __uint_as_float(r[1]); }
; __device__ __forceinline__ size_t blk_off(int r, int c, int K) { return (size_t)(r >> 8) * 256 * K + (size_t)(c >> 6) * (256 * 64) + (size_t)((r & 255) * 64 + (c & 63)); }
; __device__ __forceinline__ u32x4 pack8(const f32x4 a, const f32x4 b) { u32x4 w; w.x = cvt_pk_bf16(a[0], a[1]); w.y = cvt_pk_bf16(a[2], a[3]); w.z = cvt_pk_bf16(b[0], b[1]); w.w = cvt_pk_bf16(b[2], b[3]); return w; }
;     __device__ __forceinline__ void operator()(const f32x4 (&acc)[2][2][4][2], const pg8::Unit& u, int wr, int wc, int fr, int fq) const {
;     ...
;             for (int m = 0; m < 4; ++m) { const int row = row0 + ai * 128 + m * 16; const float mu = mu4[m], rs = rs4[m];
;                 f32x4 yv[2][2], gq[2][2], bq_[2][2];
; #pragma unroll
;                 for (int bj = 0; bj < 2; ++bj)
; #pragma unroll
;                     for (int n = 0; n < 2; ++n) { yv[bj][n] = *(const f32x4*)(Yin + (size_t)row * D_ + col0 + bj * 128 + 4 * n); gq[bj][n] = *(const f32x4*)(g + col0 + bj * 128 + 4 * n); bq_[bj][n] = *(const f32x4*)(b + col0 + bj * 128 + 4 * n); }
;                 asm volatile("" ::: "memory");
;                 float s1 = 0.f, s2 = 0.f;
; #pragma unroll
;                 for (int bj = 0; bj < 2; ++bj) { float* yp = Y + (size_t)row * D_ + col0 + bj * 128; f32x4 v[2];
; #pragma unroll
;                     for (int n = 0; n < 2; ++n) { v[n] = (((yv[bj][n] - mu) * rs) * gq[bj][n] + bq_[bj][n]) * ALPHA_ + acc[ai][bj][m][n] * sc;
;                         *(f32x4*)(yp + 4 * n) = v[n]; s1 += (v[n][0] + v[n][1]) + (v[n][2] + v[n][3]); s2 += (v[n][0] * v[n][0] + v[n][1] * v[n][1]) + (v[n][2] * v[n][2] + v[n][3] * v[n][3]); }
;                     *(u32x4*)(Yb + blk_off(row, col0 + bj * 128, D_)) = pack8(v[0], v[1]); }
;                 s1 = xsum32(xsum16(s1)); s2 = xsum32(xsum16(s2));
;                 if (fq == 0) *(f32x2*)(stn + (size_t)row * 32 + (u.pn * 4 + wc) * 2) = (f32x2){s1, s2}; asm volatile("" ::: "memory"); } }
.LBB0_1715:
	s_or_b64 exec, exec, s[24:25]
	v_pk_add_f32 v[34:35], v[88:89], v[90:91]
	s_mov_b32 s2, 0x3a800000
	v_pk_mul_f32 v[58:59], v[34:35], s[2:3] op_sel_hi:[1,0]
	s_mov_b32 s1, 0x800000
	v_fma_f32 v0, -v59, v59, v58
	v_max_f32_e32 v0, 0, v0
	v_add_f32_e32 v0, 0x3727c5ac, v0
	v_cmp_gt_f32_e32 vcc, s1, v0
	v_mul_f32_e32 v34, 0x4b800000, v0
	s_load_dwordx16 s[60:75], s[34:35], 0x38
	v_cndmask_b32_e32 v0, v0, v34, vcc
	v_rsq_f32_e32 v0, v0
	s_mov_b32 s2, 0x3fd744fd
	s_movk_i32 s1, 0x3bc0
	v_mul_f32_e32 v34, 0x45800000, v0
	v_cndmask_b32_e32 v58, v0, v34, vcc
	v_lshlrev_b64 v[34:35], 12, v[80:81]
	s_waitcnt lgkmcnt(0)
	v_lshl_add_u64 v[34:35], s[74:75], 0, v[34:35]
	v_lshl_add_u64 v[60:61], v[152:153], 2, v[34:35]
	global_load_dwordx4 v[62:65], v[60:61], off offset:16
	global_load_dwordx4 v[66:69], v[60:61], off
	global_load_dwordx4 v[70:73], v[156:157], off offset:16
	global_load_dwordx4 v[86:89], v[156:157], off
	global_load_dwordx4 v[90:93], v[154:155], off offset:16
	global_load_dwordx4 v[94:97], v[154:155], off
	global_load_dwordx4 v[34:37], v[60:61], off offset:528
	global_load_dwordx4 v[54:57], v[60:61], off offset:512
	global_load_dwordx4 v[38:41], v[156:157], off offset:528
	global_load_dwordx4 v[46:49], v[156:157], off offset:512
	global_load_dwordx4 v[42:45], v[154:155], off offset:528
	global_load_dwordx4 v[50:53], v[154:155], off offset:512
	v_lshlrev_b32_e32 v0, 6, v80
	v_and_or_b32 v0, v0, s1, v196
	v_lshlrev_b32_e32 v0, 1, v0
	s_waitcnt vmcnt(10)
	v_sub_f32_e32 v69, v69, v59
	v_sub_f32_e32 v68, v68, v59
	v_sub_f32_e32 v67, v67, v59
	v_sub_f32_e32 v66, v66, v59
	v_pk_mul_f32 v[66:67], v[58:59], v[66:67] op_sel_hi:[0,1]
	v_pk_mul_f32 v[68:69], v[58:59], v[68:69] op_sel_hi:[0,1]
	s_waitcnt vmcnt(6)
	v_pk_fma_f32 v[68:69], v[88:89], v[68:69], v[96:97]
	v_pk_fma_f32 v[66:67], v[86:87], v[66:67], v[94:95]
	v_pk_mul_f32 v[68:69], v[68:69], s[2:3] op_sel_hi:[1,0]
	v_pk_mul_f32 v[66:67], v[66:67], s[2:3] op_sel_hi:[1,0]
	v_pk_fma_f32 v[68:69], v[32:33], 0.5, v[68:69] op_sel_hi:[1,0,1]
	v_pk_fma_f32 v[66:67], v[30:31], 0.5, v[66:67] op_sel_hi:[1,0,1]
	v_add_f32_e32 v31, v68, v69
	v_add_f32_e32 v30, v66, v67
	v_add_f32_e32 v30, v30, v31
	v_add_f32_e32 v86, 0, v30
	v_mul_f32_e32 v30, v67, v67
	v_mul_f32_e32 v31, v69, v69
	v_fmac_f32_e32 v30, v66, v66
	v_fmac_f32_e32 v31, v68, v68
	v_add_f32_e32 v87, v30, v31
	v_sub_f32_e32 v31, v65, v59
	v_sub_f32_e32 v30, v64, v59
	v_sub_f32_e32 v33, v63, v59
	v_sub_f32_e32 v32, v62, v59
	v_pk_mul_f32 v[32:33], v[58:59], v[32:33] op_sel_hi:[0,1]
	v_pk_mul_f32 v[30:31], v[58:59], v[30:31] op_sel_hi:[0,1]
	v_pk_fma_f32 v[30:31], v[72:73], v[30:31], v[92:93]
	v_pk_fma_f32 v[32:33], v[70:71], v[32:33], v[90:91]
	v_pk_mul_f32 v[30:31], v[30:31], s[2:3] op_sel_hi:[1,0]
	v_pk_mul_f32 v[32:33], v[32:33], s[2:3] op_sel_hi:[1,0]
	v_pk_fma_f32 v[64:65], v[28:29], 0.5, v[30:31] op_sel_hi:[1,0,1]
	v_pk_fma_f32 v[62:63], v[26:27], 0.5, v[32:33] op_sel_hi:[1,0,1]
	v_add_f32_e32 v27, v64, v65
	v_add_f32_e32 v26, v62, v63
	v_add_f32_e32 v26, v26, v27
	v_add_f32_e32 v31, v86, v26
	v_mul_f32_e32 v26, v63, v63
	v_mul_f32_e32 v27, v65, v65
	v_fmac_f32_e32 v26, v62, v62
	v_fmac_f32_e32 v27, v64, v64
	v_add_f32_e32 v26, v26, v27
	v_add_f32_e32 v30, v87, v26
	v_cvt_pk_bf16_f32 v26, v66, v67
	v_cvt_pk_bf16_f32 v27, v68, v69
	v_cvt_pk_bf16_f32 v28, v62, v63
	v_cvt_pk_bf16_f32 v29, v64, v65
	v_lshl_add_u64 v[32:33], v[78:79], 0, v[0:1]
	s_nop 0
	s_nop 1
	v_bfe_u32 v71, v227, 4, 1
	v_sub_u32_e32 v71, 0, v71
	v_lshlrev_b32_e32 v70, 4, v71
	v_lshl_add_u64 v[70:71], v[60:61], 0, v[70:71]
	v_permlane16_swap_b32_e32 v66, v62
	v_permlane16_swap_b32_e32 v67, v63
	v_permlane16_swap_b32_e32 v68, v64
	v_permlane16_swap_b32_e32 v69, v65
	global_store_dwordx4 v[70:71], v[66:69], off
	global_store_dwordx4 v[70:71], v[62:65], off offset:32
	s_nop 1
	v_permlane16_swap_b32_e32 v66, v62
	v_permlane16_swap_b32_e32 v67, v63
	v_permlane16_swap_b32_e32 v68, v64
	v_permlane16_swap_b32_e32 v69, v65
	global_store_dwordx4 v[32:33], v[26:29], off
	s_waitcnt vmcnt(7)
	s_nop 0
	v_sub_f32_e32 v27, v57, v59
	v_sub_f32_e32 v26, v56, v59
	v_sub_f32_e32 v29, v55, v59
	v_sub_f32_e32 v28, v54, v59
	v_pk_mul_f32 v[28:29], v[58:59], v[28:29] op_sel_hi:[0,1]
	v_pk_mul_f32 v[26:27], v[58:59], v[26:27] op_sel_hi:[0,1]
	s_waitcnt vmcnt(3)
	v_pk_fma_f32 v[26:27], v[48:49], v[26:27], v[52:53]
	v_pk_fma_f32 v[28:29], v[46:47], v[28:29], v[50:51]
	v_pk_mul_f32 v[26:27], v[26:27], s[2:3] op_sel_hi:[1,0]
	v_pk_mul_f32 v[28:29], v[28:29], s[2:3] op_sel_hi:[1,0]
	v_pk_fma_f32 v[24:25], v[24:25], 0.5, v[26:27] op_sel_hi:[1,0,1]
	v_pk_fma_f32 v[22:23], v[22:23], 0.5, v[28:29] op_sel_hi:[1,0,1]
	v_add_f32_e32 v27, v24, v25
	v_add_f32_e32 v26, v22, v23
	v_add_f32_e32 v26, v26, v27
	v_add_f32_e32 v31, v31, v26
	v_mul_f32_e32 v26, v23, v23
	v_mul_f32_e32 v27, v25, v25
	v_fmac_f32_e32 v26, v22, v22
	v_fmac_f32_e32 v27, v24, v24
	v_add_f32_e32 v26, v26, v27
	v_add_f32_e32 v30, v30, v26
	v_sub_f32_e32 v27, v37, v59
	v_sub_f32_e32 v26, v36, v59
	v_sub_f32_e32 v29, v35, v59
	v_sub_f32_e32 v28, v34, v59
	v_pk_mul_f32 v[28:29], v[58:59], v[28:29] op_sel_hi:[0,1]
	v_pk_mul_f32 v[26:27], v[58:59], v[26:27] op_sel_hi:[0,1]
	v_pk_fma_f32 v[26:27], v[40:41], v[26:27], v[44:45]
	v_pk_fma_f32 v[28:29], v[38:39], v[28:29], v[42:43]
	v_pk_mul_f32 v[26:27], v[26:27], s[2:3] op_sel_hi:[1,0]
	v_pk_mul_f32 v[28:29], v[28:29], s[2:3] op_sel_hi:[1,0]
	v_pk_fma_f32 v[20:21], v[20:21], 0.5, v[26:27] op_sel_hi:[1,0,1]
	v_pk_fma_f32 v[18:19], v[18:19], 0.5, v[28:29] op_sel_hi:[1,0,1]
	v_add_f32_e32 v27, v20, v21
	v_add_f32_e32 v26, v18, v19
	v_add_f32_e32 v26, v26, v27
	v_mul_f32_e32 v27, v19, v19
	v_mul_f32_e32 v28, v21, v21
	v_add_f32_e32 v26, v31, v26
	v_fmac_f32_e32 v27, v18, v18
	v_fmac_f32_e32 v28, v20, v20
	s_nop 0
	s_nop 1
	v_bfe_u32 v33, v227, 4, 1
	v_sub_u32_e32 v33, 0, v33
	v_lshlrev_b32_e32 v32, 4, v33
	v_lshl_add_u64 v[32:33], v[60:61], 0, v[32:33]
	v_permlane16_swap_b32_e32 v22, v18
	v_permlane16_swap_b32_e32 v23, v19
	v_permlane16_swap_b32_e32 v24, v20
	v_permlane16_swap_b32_e32 v25, v21
	global_store_dwordx4 v[32:33], v[22:25], off offset:512
	global_store_dwordx4 v[32:33], v[18:21], off offset:544
	s_nop 1
	v_permlane16_swap_b32_e32 v22, v18
	v_permlane16_swap_b32_e32 v23, v19
	v_permlane16_swap_b32_e32 v24, v20
	v_permlane16_swap_b32_e32 v25, v21
	v_add_f32_e32 v27, v27, v28
	v_cvt_pk_bf16_f32 v22, v22, v23
	v_cvt_pk_bf16_f32 v23, v24, v25
	v_cvt_pk_bf16_f32 v24, v18, v19
	v_lshl_add_u64 v[18:19], v[76:77], 0, v[0:1]
	v_mov_b32_e32 v0, v26
	v_add_f32_e32 v27, v30, v27
	v_cvt_pk_bf16_f32 v25, v20, v21
	v_permlane16_swap_b32_e32 v26, v0
	global_store_dwordx4 v[18:19], v[22:25], off
	v_add_f32_e32 v18, v26, v0
	v_mov_b32_e32 v0, v27
	s_nop 1
	v_permlane16_swap_b32_e32 v27, v0
	v_add_f32_e32 v19, v27, v0
	v_mov_b32_e32 v20, v18
	v_mov_b32_e32 v21, v19
	s_nop 0
	v_permlane32_swap_b32_e32 v18, v20
	v_permlane32_swap_b32_e32 v19, v21
	s_and_saveexec_b64 s[24:25], s[40:41]
	s_cbranch_execz .LBB0_1717
; __device__ __forceinline__ size_t blk_off(int r, int c, int K) { return (size_t)(r >> 8) * 256 * K + (size_t)(c >> 6) * (256 * 64) + (size_t)((r & 255) * 64 + (c & 63)); }
; __device__ __forceinline__ u32x4 pack8(const f32x4 a, const f32x4 b) { u32x4 w; w.x = cvt_pk_bf16(a[0], a[1]); w.y = cvt_pk_bf16(a[2], a[3]); w.z = cvt_pk_bf16(b[0], b[1]); w.w = cvt_pk_bf16(b[2], b[3]); return w; }
;     __device__ __forceinline__ void operator()(const f32x4 (&acc)[2][2][4][2], const pg8::Unit& u, int wr, int wc, int fr, int fq) const {
;     ...
;             for (int m = 0; m < 4; ++m) { const int row = row0 + ai * 128 + m * 16; const float mu = mu4[m], rs = rs4[m];
;                 f32x4 yv[2][2], gq[2][2], bq_[2][2];
; #pragma unroll
;                 for (int bj = 0; bj < 2; ++bj)
; #pragma unroll
;                     for (int n = 0; n < 2; ++n) { yv[bj][n] = *(const f32x4*)(Yin + (size_t)row * D_ + col0 + bj * 128 + 4 * n); gq[bj][n] = *(const f32x4*)(g + col0 + bj * 128 + 4 * n); bq_[bj][n] = *(const f32x4*)(b + col0 + bj * 128 + 4 * n); }
;                 asm volatile("" ::: "memory");
;                 float s1 = 0.f, s2 = 0.f;
; #pragma unroll
;                 for (int bj = 0; bj < 2; ++bj) { float* yp = Y + (size_t)row * D_ + col0 + bj * 128; f32x4 v[2];
; #pragma unroll
;                     for (int n = 0; n < 2; ++n) { v[n] = (((yv[bj][n] - mu) * rs) * gq[bj][n] + bq_[bj][n]) * ALPHA_ + acc[ai][bj][m][n] * sc;
;                         *(f32x4*)(yp + 4 * n) = v[n]; s1 += (v[n][0] + v[n][1]) + (v[n][2] + v[n][3]); s2 += (v[n][0] * v[n][0] + v[n][1] * v[n][1]) + (v[n][2] * v[n][2] + v[n][3] * v[n][3]); }
;                     *(u32x4*)(Yb + blk_off(row, col0 + bj * 128, D_)) = pack8(v[0], v[1]); }
	v_pk_add_f32 v[18:19], v[18:19], v[20:21]
	v_lshlrev_b64 v[20:21], 7, v[80:81]
	v_lshl_add_u64 v[20:21], s[8:9], 0, v[20:21]
	v_lshl_add_u64 v[20:21], s[38:39], 2, v[20:21]
	global_store_dwordx2 v[20:21], v[18:19], off
.LBB0_1717:
	s_or_b64 exec, exec, s[24:25]
	v_pk_add_f32 v[18:19], v[82:83], v[84:85]
	s_mov_b32 s2, 0x3a800000
	v_pk_mul_f32 v[42:43], v[18:19], s[2:3] op_sel_hi:[1,0]
	s_mov_b32 s1, 0x800000
	v_fma_f32 v0, -v43, v43, v42
	v_max_f32_e32 v0, 0, v0
	v_add_f32_e32 v0, 0x3727c5ac, v0
	v_cmp_gt_f32_e32 vcc, s1, v0
	v_mul_f32_e32 v18, 0x4b800000, v0
	s_load_dwordx16 s[60:75], s[34:35], 0x38
	v_cndmask_b32_e32 v0, v0, v18, vcc
	v_rsq_f32_e32 v0, v0
	s_mov_b32 s2, 0x3fd744fd
	s_movk_i32 s1, 0x3fc0
	v_mul_f32_e32 v18, 0x45800000, v0
	v_cndmask_b32_e32 v42, v0, v18, vcc
	v_lshlrev_b64 v[18:19], 12, v[74:75]
	s_waitcnt lgkmcnt(0)
	v_lshl_add_u64 v[18:19], s[74:75], 0, v[18:19]
	v_lshl_add_u64 v[44:45], v[152:153], 2, v[18:19]
	global_load_dwordx4 v[46:49], v[44:45], off offset:16
	global_load_dwordx4 v[50:53], v[44:45], off
	global_load_dwordx4 v[54:57], v[156:157], off offset:16
	global_load_dwordx4 v[58:61], v[156:157], off
	global_load_dwordx4 v[62:65], v[154:155], off offset:16
	global_load_dwordx4 v[66:69], v[154:155], off
	global_load_dwordx4 v[18:21], v[44:45], off offset:528
	global_load_dwordx4 v[38:41], v[44:45], off offset:512
	global_load_dwordx4 v[22:25], v[156:157], off offset:528
	global_load_dwordx4 v[30:33], v[156:157], off offset:512
	global_load_dwordx4 v[26:29], v[154:155], off offset:528
	global_load_dwordx4 v[34:37], v[154:155], off offset:512
	v_lshlrev_b32_e32 v0, 6, v74
	v_and_or_b32 v0, v0, s1, v196
	v_lshlrev_b32_e32 v0, 1, v0
	s_waitcnt vmcnt(10)
	v_sub_f32_e32 v53, v53, v43
	v_sub_f32_e32 v52, v52, v43
	v_sub_f32_e32 v51, v51, v43
	v_sub_f32_e32 v50, v50, v43
	v_pk_mul_f32 v[50:51], v[42:43], v[50:51] op_sel_hi:[0,1]
	v_pk_mul_f32 v[52:53], v[42:43], v[52:53] op_sel_hi:[0,1]
	s_waitcnt vmcnt(6)
	v_pk_fma_f32 v[52:53], v[60:61], v[52:53], v[68:69]
	v_pk_fma_f32 v[50:51], v[58:59], v[50:51], v[66:67]
	v_pk_mul_f32 v[52:53], v[52:53], s[2:3] op_sel_hi:[1,0]
	v_pk_mul_f32 v[50:51], v[50:51], s[2:3] op_sel_hi:[1,0]
	v_pk_fma_f32 v[52:53], v[16:17], 0.5, v[52:53] op_sel_hi:[1,0,1]
	v_pk_fma_f32 v[50:51], v[14:15], 0.5, v[50:51] op_sel_hi:[1,0,1]
	v_add_f32_e32 v15, v52, v53
	v_add_f32_e32 v14, v50, v51
	v_add_f32_e32 v14, v14, v15
	v_add_f32_e32 v58, 0, v14
	v_mul_f32_e32 v14, v51, v51
	v_mul_f32_e32 v15, v53, v53
	v_fmac_f32_e32 v14, v50, v50
	v_fmac_f32_e32 v15, v52, v52
	v_add_f32_e32 v59, v14, v15
	v_sub_f32_e32 v15, v49, v43
	v_sub_f32_e32 v14, v48, v43
	v_sub_f32_e32 v17, v47, v43
	v_sub_f32_e32 v16, v46, v43
	v_pk_mul_f32 v[16:17], v[42:43], v[16:17] op_sel_hi:[0,1]
	v_pk_mul_f32 v[14:15], v[42:43], v[14:15] op_sel_hi:[0,1]
	v_pk_fma_f32 v[14:15], v[56:57], v[14:15], v[64:65]
	v_pk_fma_f32 v[16:17], v[54:55], v[16:17], v[62:63]
	v_pk_mul_f32 v[14:15], v[14:15], s[2:3] op_sel_hi:[1,0]
	v_pk_mul_f32 v[16:17], v[16:17], s[2:3] op_sel_hi:[1,0]
	v_pk_fma_f32 v[48:49], v[12:13], 0.5, v[14:15] op_sel_hi:[1,0,1]
	v_pk_fma_f32 v[46:47], v[10:11], 0.5, v[16:17] op_sel_hi:[1,0,1]
	v_add_f32_e32 v11, v48, v49
	v_add_f32_e32 v10, v46, v47
	v_add_f32_e32 v10, v10, v11
	v_add_f32_e32 v15, v58, v10
	v_mul_f32_e32 v10, v47, v47
	v_mul_f32_e32 v11, v49, v49
	v_fmac_f32_e32 v10, v46, v46
	v_fmac_f32_e32 v11, v48, v48
	v_add_f32_e32 v10, v10, v11
	v_add_f32_e32 v14, v59, v10
	v_cvt_pk_bf16_f32 v10, v50, v51
	v_cvt_pk_bf16_f32 v11, v52, v53
	v_cvt_pk_bf16_f32 v12, v46, v47
	v_cvt_pk_bf16_f32 v13, v48, v49
	v_lshl_add_u64 v[16:17], v[78:79], 0, v[0:1]
	s_nop 0
	s_nop 1
	v_bfe_u32 v55, v227, 4, 1
	v_sub_u32_e32 v55, 0, v55
	v_lshlrev_b32_e32 v54, 4, v55
	v_lshl_add_u64 v[54:55], v[44:45], 0, v[54:55]
	v_permlane16_swap_b32_e32 v50, v46
	v_permlane16_swap_b32_e32 v51, v47
	v_permlane16_swap_b32_e32 v52, v48
	v_permlane16_swap_b32_e32 v53, v49
	global_store_dwordx4 v[54:55], v[50:53], off
	global_store_dwordx4 v[54:55], v[46:49], off offset:32
	s_nop 1
	v_permlane16_swap_b32_e32 v50, v46
	v_permlane16_swap_b32_e32 v51, v47
	v_permlane16_swap_b32_e32 v52, v48
	v_permlane16_swap_b32_e32 v53, v49
	global_store_dwordx4 v[16:17], v[10:13], off
	s_waitcnt vmcnt(7)
; __device__ __forceinline__ float xsum16(float v) { const auto r = __builtin_amdgcn_permlane16_swap(__float_as_uint(v), __float_as_uint(v), false, false); return __uint_as_float(r[0]) + __uint_as_float(r[1]); }
; __device__ __forceinline__ float xsum32(float v) { const auto r = __builtin_amdgcn_permlane32_swap(__float_as_uint(v), __float_as_uint(v), false, false); return __uint_as_float(r[0]) + __uint_as_float(r[1]); }
; __device__ __forceinline__ size_t blk_off(int r, int c, int K) { return (size_t)(r >> 8) * 256 * K + (size_t)(c >> 6) * (256 * 64) + (size_t)((r & 255) * 64 + (c & 63)); }
; __device__ __forceinline__ u32x4 pack8(const f32x4 a, const f32x4 b) { u32x4 w; w.x = cvt_pk_bf16(a[0], a[1]); w.y = cvt_pk_bf16(a[2], a[3]); w.z = cvt_pk_bf16(b[0], b[1]); w.w = cvt_pk_bf16(b[2], b[3]); return w; }
;     __device__ __forceinline__ void operator()(const f32x4 (&acc)[2][2][4][2], const pg8::Unit& u, int wr, int wc, int fr, int fq) const {
;     ...
;             for (int m = 0; m < 4; ++m) { const int row = row0 + ai * 128 + m * 16; const float mu = mu4[m], rs = rs4[m];
;                 f32x4 yv[2][2], gq[2][2], bq_[2][2];
; #pragma unroll
;                 for (int bj = 0; bj < 2; ++bj)
; #pragma unroll
;                     for (int n = 0; n < 2; ++n) { yv[bj][n] = *(const f32x4*)(Yin + (size_t)row * D_ + col0 + bj * 128 + 4 * n); gq[bj][n] = *(const f32x4*)(g + col0 + bj * 128 + 4 * n); bq_[bj][n] = *(const f32x4*)(b + col0 + bj * 128 + 4 * n); }
;                 asm volatile("" ::: "memory");
;                 float s1 = 0.f, s2 = 0.f;
; #pragma unroll
;                 for (int bj = 0; bj < 2; ++bj) { float* yp = Y + (size_t)row * D_ + col0 + bj * 128; f32x4 v[2];
; #pragma unroll
;                     for (int n = 0; n < 2; ++n) { v[n] = (((yv[bj][n] - mu) * rs) * gq[bj][n] + bq_[bj][n]) * ALPHA_ + acc[ai][bj][m][n] * sc;
;                         *(f32x4*)(yp + 4 * n) = v[n]; s1 += (v[n][0] + v[n][1]) + (v[n][2] + v[n][3]); s2 += (v[n][0] * v[n][0] + v[n][1] * v[n][1]) + (v[n][2] * v[n][2] + v[n][3] * v[n][3]); }
;                     *(u32x4*)(Yb + blk_off(row, col0 + bj * 128, D_)) = pack8(v[0], v[1]); }
;                 s1 = xsum32(xsum16(s1)); s2 = xsum32(xsum16(s2));
;                 if (fq == 0) *(f32x2*)(stn + (size_t)row * 32 + (u.pn * 4 + wc) * 2) = (f32x2){s1, s2}; asm volatile("" ::: "memory"); } }
	s_nop 0
	v_sub_f32_e32 v11, v41, v43
	v_sub_f32_e32 v10, v40, v43
	v_sub_f32_e32 v13, v39, v43
	v_sub_f32_e32 v12, v38, v43
	v_pk_mul_f32 v[12:13], v[42:43], v[12:13] op_sel_hi:[0,1]
	v_pk_mul_f32 v[10:11], v[42:43], v[10:11] op_sel_hi:[0,1]
	s_waitcnt vmcnt(3)
	v_pk_fma_f32 v[10:11], v[32:33], v[10:11], v[36:37]
	v_pk_fma_f32 v[12:13], v[30:31], v[12:13], v[34:35]
	v_pk_mul_f32 v[10:11], v[10:11], s[2:3] op_sel_hi:[1,0]
	v_pk_mul_f32 v[12:13], v[12:13], s[2:3] op_sel_hi:[1,0]
	v_pk_fma_f32 v[8:9], v[8:9], 0.5, v[10:11] op_sel_hi:[1,0,1]
	v_pk_fma_f32 v[6:7], v[6:7], 0.5, v[12:13] op_sel_hi:[1,0,1]
	v_add_f32_e32 v11, v8, v9
	v_add_f32_e32 v10, v6, v7
	v_add_f32_e32 v10, v10, v11
	v_add_f32_e32 v15, v15, v10
	v_mul_f32_e32 v10, v7, v7
	v_mul_f32_e32 v11, v9, v9
	v_fmac_f32_e32 v10, v6, v6
	v_fmac_f32_e32 v11, v8, v8
	v_add_f32_e32 v10, v10, v11
	v_add_f32_e32 v14, v14, v10
	v_sub_f32_e32 v11, v21, v43
	v_sub_f32_e32 v10, v20, v43
	v_sub_f32_e32 v13, v19, v43
	v_sub_f32_e32 v12, v18, v43
	v_pk_mul_f32 v[12:13], v[42:43], v[12:13] op_sel_hi:[0,1]
	v_pk_mul_f32 v[10:11], v[42:43], v[10:11] op_sel_hi:[0,1]
	v_pk_fma_f32 v[10:11], v[24:25], v[10:11], v[28:29]
	v_pk_fma_f32 v[12:13], v[22:23], v[12:13], v[26:27]
	v_pk_mul_f32 v[10:11], v[10:11], s[2:3] op_sel_hi:[1,0]
	v_pk_mul_f32 v[12:13], v[12:13], s[2:3] op_sel_hi:[1,0]
	v_pk_fma_f32 v[4:5], v[4:5], 0.5, v[10:11] op_sel_hi:[1,0,1]
	v_pk_fma_f32 v[2:3], v[2:3], 0.5, v[12:13] op_sel_hi:[1,0,1]
	v_add_f32_e32 v11, v4, v5
	v_add_f32_e32 v10, v2, v3
	v_add_f32_e32 v10, v10, v11
	v_mul_f32_e32 v11, v3, v3
	v_mul_f32_e32 v12, v5, v5
	v_add_f32_e32 v10, v15, v10
	v_fmac_f32_e32 v11, v2, v2
	v_fmac_f32_e32 v12, v4, v4
	s_nop 0
	s_nop 1
	v_bfe_u32 v17, v227, 4, 1
	v_sub_u32_e32 v17, 0, v17
	v_lshlrev_b32_e32 v16, 4, v17
	v_lshl_add_u64 v[16:17], v[44:45], 0, v[16:17]
	v_permlane16_swap_b32_e32 v6, v2
	v_permlane16_swap_b32_e32 v7, v3
	v_permlane16_swap_b32_e32 v8, v4
	v_permlane16_swap_b32_e32 v9, v5
	global_store_dwordx4 v[16:17], v[6:9], off offset:512
	global_store_dwordx4 v[16:17], v[2:5], off offset:544
	s_nop 1
	v_permlane16_swap_b32_e32 v6, v2
	v_permlane16_swap_b32_e32 v7, v3
	v_permlane16_swap_b32_e32 v8, v4
	v_permlane16_swap_b32_e32 v9, v5
	v_add_f32_e32 v11, v11, v12
	v_cvt_pk_bf16_f32 v6, v6, v7
	v_cvt_pk_bf16_f32 v7, v8, v9
	v_cvt_pk_bf16_f32 v8, v2, v3
	v_lshl_add_u64 v[2:3], v[76:77], 0, v[0:1]
	v_mov_b32_e32 v0, v10
	v_add_f32_e32 v11, v14, v11
	v_cvt_pk_bf16_f32 v9, v4, v5
	v_permlane16_swap_b32_e32 v10, v0
	global_store_dwordx4 v[2:3], v[6:9], off
	v_add_f32_e32 v2, v10, v0
	v_mov_b32_e32 v0, v11
	s_nop 1
	v_permlane16_swap_b32_e32 v11, v0
	v_add_f32_e32 v3, v11, v0
	v_mov_b32_e32 v4, v2
	v_mov_b32_e32 v5, v3
	s_nop 0
	v_permlane32_swap_b32_e32 v2, v4
	v_permlane32_swap_b32_e32 v3, v5
	s_and_saveexec_b64 s[24:25], s[40:41]
	s_cbranch_execz .LBB0_1719
	v_pk_add_f32 v[2:3], v[2:3], v[4:5]
	v_lshlrev_b64 v[4:5], 7, v[74:75]
	v_lshl_add_u64 v[4:5], s[8:9], 0, v[4:5]
	v_lshl_add_u64 v[4:5], s[38:39], 2, v[4:5]
	global_store_dwordx2 v[4:5], v[2:3], off
